# hand-written sample window attention part 1: K rows double-buffered one round ahead, address math hoisted, DPP chains interleaved
# baseline (speedup 1.0000x reference)
; DI f32x4 unpack4(v2u w) { return (f32x4){bflo(w.x), bfhi(w.x), bflo(w.y), bfhi(w.y)}; }
; DI float fexp2(float x) { return __builtin_amdgcn_exp2f(x); }
; DI void unit_sample_attn2(int u, const bf16* __restrict__ Q, const float* __restrict__ ckw, const float* __restrict__ cvw, const float* __restrict__ nkw, const float* __restrict__ nvw, const bf16* __restrict__ G, bf16* __restrict__ MIX, ...
;     ...
;     const int b = u >> 2, hq = u & 3, half = lane >> 5, hl = (lane >> 4) & 1, coff = hq * 128 + (lane & 31) * 4;
;     const float slope2 = fexp2(-(float)(hq * 2 + hl + 1)) * LOG2E;
;     const float* ck = ckw + (size_t)b * 2048 * 512 + coff; const float* cv = cvw + (size_t)b * 2048 * 512 + coff;
;     const float* nk = nkw + (size_t)b * 4 * 512 + coff;    const float* nv = nvw + (size_t)b * 4 * 512 + coff;
;     f32x4 q[4];
; #pragma unroll
;     for (int jj = 0; jj < 4; ++jj) q[jj] = unpack4(*(const v2u*)(Q + (size_t)(MP + b * 4 + jj) * 512 + coff));
;     const int j1 = wave & 3, sub = wave >> 2;
;     const f32x4 qs = (j1 == 0) ? q[0] : (j1 == 1) ? q[1] : (j1 == 2) ? q[2] : q[3];
;     float mB = NEG, lB = 0.f; f32x4 oB = (f32x4){0.f, 0.f, 0.f, 0.f};
; #pragma unroll 1
;     for (int n0 = 0; n0 < 96; n0 += 32) {
.LBB0_732:
	v_bfe_u32 v137, v169, 4, 1
	v_lshl_or_b32 v5, s1, 1, v137
	v_add_u32_e32 v5, 1, v5
	v_cvt_f32_ubyte0_e32 v5, v5
	v_exp_f32_e64 v5, -v5
	v_lshlrev_b32_e32 v162, 2, v4
	v_xor_b32_e32 v4, 1, v1
	s_ashr_i32 s6, s0, 2
	v_mul_f32_e32 v136, 0x3fb8aa3b, v5
	v_and_b32_e32 v5, 64, v1
	v_add_u32_e32 v5, 64, v5
	v_cmp_lt_i32_e32 vcc, v4, v5
	s_ashr_i32 s7, s6, 31
	v_readlane_b32 s8, v247, 2
	v_cndmask_b32_e32 v4, v1, v4, vcc
	v_lshlrev_b32_e32 v168, 2, v4
	v_xor_b32_e32 v4, 2, v1
	v_cmp_lt_i32_e32 vcc, v4, v5
	s_lshl_b64 s[0:1], s[6:7], 22
	v_readlane_b32 s16, v247, 10
	v_cndmask_b32_e32 v4, v1, v4, vcc
	v_lshlrev_b32_e32 v167, 2, v4
	v_xor_b32_e32 v4, 4, v1
	v_cmp_lt_i32_e32 vcc, v4, v5
	v_readlane_b32 s17, v247, 11
	s_add_u32 s2, s16, s0
	v_cndmask_b32_e32 v4, v1, v4, vcc
	v_lshlrev_b32_e32 v166, 2, v4
	v_xor_b32_e32 v4, 8, v1
	v_readlane_b32 s14, v247, 8
	s_addc_u32 s3, s17, s1
	v_cmp_lt_i32_e32 vcc, v4, v5
	v_readlane_b32 s15, v247, 9
	v_ashrrev_i32_e32 v170, 5, v169
	s_add_u32 s0, s14, s0
	v_cndmask_b32_e32 v4, v1, v4, vcc
	s_addc_u32 s1, s15, s1
	v_mov_b32_e32 v163, v2
	v_lshlrev_b32_e32 v165, 2, v4
	v_lshlrev_b32_e32 v4, 2, v170
	v_lshl_add_u64 v[156:157], s[0:1], 0, v[162:163]
	v_lshl_add_u64 v[154:155], s[2:3], 0, v[162:163]
	v_sub_u32_e32 v163, 0x188, v4
	v_add_u32_e32 v171, 0xfffffe00, v4
	v_lshlrev_b32_e32 v4, 4, v170
	v_mov_b32_e32 v87, 0
	v_add_u32_e32 v172, 0x3f0, v4
	v_sub_u32_e32 v173, 0xfffffc10, v4
	v_mov_b32_e32 v85, 0xf149f2ca
	v_mov_b32_e32 v4, 0
	v_mov_b32_e32 v5, v87
	v_mov_b32_e32 v6, v87
	v_mov_b32_e32 v7, v87
	v_readlane_b32 s9, v247, 3
	v_readlane_b32 s10, v247, 4
	v_readlane_b32 s11, v247, 5
	v_readlane_b32 s12, v247, 6
	v_readlane_b32 s13, v247, 7
	v_readlane_b32 s18, v247, 12
	v_readlane_b32 s19, v247, 13
	v_readlane_b32 s20, v247, 14
	v_readlane_b32 s21, v247, 15
	v_readlane_b32 s22, v247, 16
	v_readlane_b32 s23, v247, 17

; DI float dot16(f32x4 a, f32x4 b) { float d = (a[0] * b[0] + a[1] * b[1]) + (a[2] * b[2] + a[3] * b[3]); d += __shfl_xor(d, 1); d += __shfl_xor(d, 2); d += __shfl_xor(d, 4); d += __shfl_xor(d, 8); return d; }
; DI void unit_sample_attn2(int u, const bf16* __restrict__ Q, const float* __restrict__ ckw, const float* __restrict__ cvw, const float* __restrict__ nkw, const float* __restrict__ nvw, const bf16* __restrict__ G, bf16* __restrict__ MIX, ...
;     ...
;     for (int n0 = 0; n0 < 96; n0 += 32) {
;         f32x4 kv[16], vv[16]; float s[16];
; #pragma unroll
;         for (int i = 0; i < 16; ++i) { const int n = n0 + 2 * i + half, dlt = sub ? 16 * (33 + n) : 512 - 4 * n; const size_t ro = (size_t)(2048 + j1 - dlt) * 512;
;             kv[i] = __builtin_nontemporal_load((const f32x4*)(ck + ro)); }
; #pragma unroll
;         for (int i = 0; i < 16; ++i) { const int n = n0 + 2 * i + half, dlt = sub ? 16 * (33 + n) : 512 - 4 * n; const size_t ro = (size_t)(2048 + j1 - dlt) * 512;
;             vv[i] = __builtin_nontemporal_load((const f32x4*)(cv + ro)); }
; #pragma unroll
;         for (int i = 0; i < 16; ++i) { const int n = n0 + 2 * i + half, dlt = sub ? 16 * (33 + n) : 512 - 4 * n;
;             s[i] = dot16(qs, kv[i]) - slope2 * (float)dlt + ((!sub && (dlt & 15) == 0) ? 1.f : 0.f); }
.Ls1_n:
	v_add_u32_e32 v224, s94, v171
	v_lshl_add_u32 v224, v224, 11, v162
	v_cmp_eq_u32_e32 vcc, 0, v170
	s_nop 1
	v_cndmask_b32_e64 v172, 0, 1.0, vcc
	v_mov_b32_e32 v175, v85
	v_mov_b32_e32 v174, v87
	v_mov_b32_e32 v225, v224
	global_load_dwordx4 v[132:135], v225, s[0:1] nt
	v_add_u32_e32 v225, 0x4000, v225
	global_load_dwordx4 v[128:131], v225, s[0:1] nt
	v_add_u32_e32 v225, 0x4000, v225
	global_load_dwordx4 v[124:127], v225, s[0:1] nt
	v_add_u32_e32 v225, 0x4000, v225
	global_load_dwordx4 v[120:123], v225, s[0:1] nt
	v_add_u32_e32 v225, 0x4000, v225
	global_load_dwordx4 v[116:119], v225, s[0:1] nt
	v_add_u32_e32 v225, 0x4000, v225
	global_load_dwordx4 v[112:115], v225, s[0:1] nt
	v_add_u32_e32 v225, 0x4000, v225
	global_load_dwordx4 v[108:111], v225, s[0:1] nt
	v_add_u32_e32 v225, 0x4000, v225
	global_load_dwordx4 v[104:107], v225, s[0:1] nt
	v_add_u32_e32 v225, 0x4000, v225
	global_load_dwordx4 v[100:103], v225, s[0:1] nt
	v_add_u32_e32 v225, 0x4000, v225
	global_load_dwordx4 v[96:99], v225, s[0:1] nt
	v_add_u32_e32 v225, 0x4000, v225
	global_load_dwordx4 v[92:95], v225, s[0:1] nt
	v_add_u32_e32 v225, 0x4000, v225
	global_load_dwordx4 v[88:91], v225, s[0:1] nt
	v_add_u32_e32 v225, 0x4000, v225
	global_load_dwordx4 v[84:87], v225, s[0:1] nt
	v_add_u32_e32 v225, 0x4000, v225
	global_load_dwordx4 v[80:83], v225, s[0:1] nt
	v_add_u32_e32 v225, 0x4000, v225
	global_load_dwordx4 v[76:79], v225, s[0:1] nt
	v_add_u32_e32 v225, 0x4000, v225
	global_load_dwordx4 v[72:75], v225, s[0:1] nt
	v_mov_b32_e32 v225, v224
	global_load_dwordx4 v[68:71], v225, s[2:3] nt
	v_add_u32_e32 v225, 0x4000, v225
	global_load_dwordx4 v[64:67], v225, s[2:3] nt
	v_add_u32_e32 v225, 0x4000, v225
	global_load_dwordx4 v[60:63], v225, s[2:3] nt
	v_add_u32_e32 v225, 0x4000, v225
	global_load_dwordx4 v[56:59], v225, s[2:3] nt
	v_add_u32_e32 v225, 0x4000, v225
	global_load_dwordx4 v[52:55], v225, s[2:3] nt
	v_add_u32_e32 v225, 0x4000, v225
	global_load_dwordx4 v[48:51], v225, s[2:3] nt
	v_add_u32_e32 v225, 0x4000, v225
	global_load_dwordx4 v[44:47], v225, s[2:3] nt
	v_add_u32_e32 v225, 0x4000, v225
	global_load_dwordx4 v[40:43], v225, s[2:3] nt
	v_add_u32_e32 v225, 0x4000, v225
	global_load_dwordx4 v[36:39], v225, s[2:3] nt
	v_add_u32_e32 v225, 0x4000, v225
	global_load_dwordx4 v[32:35], v225, s[2:3] nt
	v_add_u32_e32 v225, 0x4000, v225
	global_load_dwordx4 v[28:31], v225, s[2:3] nt
	v_add_u32_e32 v225, 0x4000, v225
	global_load_dwordx4 v[24:27], v225, s[2:3] nt
	v_add_u32_e32 v225, 0x4000, v225
	global_load_dwordx4 v[20:23], v225, s[2:3] nt
	v_add_u32_e32 v225, 0x4000, v225
	global_load_dwordx4 v[16:19], v225, s[2:3] nt
	v_add_u32_e32 v225, 0x4000, v225
	global_load_dwordx4 v[12:15], v225, s[2:3] nt
	v_add_u32_e32 v225, 0x4000, v225
	global_load_dwordx4 v[8:11], v225, s[2:3] nt
	v_add_u32_e32 v225, 0x40000, v224
	global_load_dwordx4 v[188:191], v225, s[0:1] nt
	v_add_u32_e32 v225, 0x4000, v225
	global_load_dwordx4 v[192:195], v225, s[0:1] nt
	v_add_u32_e32 v225, 0x4000, v225
	global_load_dwordx4 v[196:199], v225, s[0:1] nt
	v_add_u32_e32 v225, 0x4000, v225
	global_load_dwordx4 v[200:203], v225, s[0:1] nt
	v_add_u32_e32 v225, 0x4000, v225
	global_load_dwordx4 v[204:207], v225, s[0:1] nt
	v_add_u32_e32 v225, 0x4000, v225
	global_load_dwordx4 v[208:211], v225, s[0:1] nt
	v_add_u32_e32 v225, 0x4000, v225
	global_load_dwordx4 v[212:215], v225, s[0:1] nt
	v_add_u32_e32 v225, 0x4000, v225
	global_load_dwordx4 v[216:219], v225, s[0:1] nt
	v_add_u32_e32 v225, 0x4000, v225
	global_load_dwordx4 v[220:223], v225, s[0:1] nt
	v_add_u32_e32 v225, 0x4000, v225
	global_load_dwordx4 v[228:231], v225, s[0:1] nt
	v_add_u32_e32 v225, 0x4000, v225
	global_load_dwordx4 v[232:235], v225, s[0:1] nt
	v_add_u32_e32 v225, 0x4000, v225
	global_load_dwordx4 v[236:239], v225, s[0:1] nt
	v_add_u32_e32 v225, 0x4000, v225
	global_load_dwordx4 v[240:243], v225, s[0:1] nt
	v_add_u32_e32 v225, 0x4000, v225
	global_load_dwordx4 v[176:179], v225, s[0:1] nt
	v_add_u32_e32 v225, 0x4000, v225
	global_load_dwordx4 v[184:187], v225, s[0:1] nt
	v_add_u32_e32 v225, 0x4000, v225
	global_load_dwordx2 v[180:181], v225, s[0:1] nt
	global_load_dwordx2 v[244:245], v225, s[0:1] offset:8 nt
	v_add_u32_e32 v227, 0x78, v163
	s_waitcnt vmcnt(45)
	v_pk_mul_f32 v[132:133], v[132:133], v[158:159]
	v_pk_mul_f32 v[134:135], v[134:135], v[160:161]
	v_pk_mul_f32 v[128:129], v[128:129], v[158:159]
	v_pk_mul_f32 v[130:131], v[130:131], v[160:161]
	v_pk_mul_f32 v[124:125], v[124:125], v[158:159]
	v_pk_mul_f32 v[126:127], v[126:127], v[160:161]
	v_pk_mul_f32 v[120:121], v[120:121], v[158:159]
	v_pk_mul_f32 v[122:123], v[122:123], v[160:161]
	v_add_f32_e32 v132, v133, v132
	v_add_f32_e32 v134, v134, v135
	v_add_f32_e32 v128, v129, v128
	v_add_f32_e32 v130, v130, v131
	v_add_f32_e32 v124, v125, v124
	v_add_f32_e32 v126, v126, v127
	v_add_f32_e32 v120, v121, v120
	v_add_f32_e32 v122, v122, v123
	v_add_f32_e32 v132, v132, v134
	v_add_f32_e32 v128, v128, v130
	v_add_f32_e32 v124, v124, v126
	v_add_f32_e32 v120, v120, v122
	v_add_f32_dpp v132, v132, v132 quad_perm:[1,0,3,2] row_mask:0xf bank_mask:0xf
	v_add_f32_dpp v128, v128, v128 quad_perm:[1,0,3,2] row_mask:0xf bank_mask:0xf
	v_add_f32_dpp v124, v124, v124 quad_perm:[1,0,3,2] row_mask:0xf bank_mask:0xf
	v_add_f32_dpp v120, v120, v120 quad_perm:[1,0,3,2] row_mask:0xf bank_mask:0xf
	v_add_f32_dpp v132, v132, v132 quad_perm:[2,3,0,1] row_mask:0xf bank_mask:0xf
	v_add_f32_dpp v128, v128, v128 quad_perm:[2,3,0,1] row_mask:0xf bank_mask:0xf
	v_add_f32_dpp v124, v124, v124 quad_perm:[2,3,0,1] row_mask:0xf bank_mask:0xf
	v_add_f32_dpp v120, v120, v120 quad_perm:[2,3,0,1] row_mask:0xf bank_mask:0xf
	v_add_f32_dpp v132, v132, v132 row_half_mirror row_mask:0xf bank_mask:0xf
	v_add_f32_dpp v128, v128, v128 row_half_mirror row_mask:0xf bank_mask:0xf
	v_add_f32_dpp v124, v124, v124 row_half_mirror row_mask:0xf bank_mask:0xf
	v_add_f32_dpp v120, v120, v120 row_half_mirror row_mask:0xf bank_mask:0xf
	v_add_f32_dpp v132, v132, v132 row_mirror row_mask:0xf bank_mask:0xf
	v_add_f32_dpp v128, v128, v128 row_mirror row_mask:0xf bank_mask:0xf
	v_add_f32_dpp v124, v124, v124 row_mirror row_mask:0xf bank_mask:0xf
	v_add_f32_dpp v120, v120, v120 row_mirror row_mask:0xf bank_mask:0xf
	v_cvt_f32_i32_e32 v173, v227
	v_add_u32_e32 v227, 0xfffffff8, v227
	v_fma_f32 v132, -v136, v173, v132
	v_add_f32_e32 v132, v172, v132
	v_cvt_f32_i32_e32 v171, v227
	v_add_u32_e32 v227, 0xfffffff8, v227
	v_fma_f32 v128, -v136, v171, v128
	v_cvt_f32_i32_e32 v173, v227
	v_add_u32_e32 v227, 0xfffffff8, v227
	v_fma_f32 v124, -v136, v173, v124
	v_add_f32_e32 v124, v172, v124
	v_cvt_f32_i32_e32 v171, v227
	v_add_u32_e32 v227, 0xfffffff8, v227
	v_fma_f32 v120, -v136, v171, v120
	s_waitcnt vmcnt(41)
; DI float dot16(f32x4 a, f32x4 b) { float d = (a[0] * b[0] + a[1] * b[1]) + (a[2] * b[2] + a[3] * b[3]); d += __shfl_xor(d, 1); d += __shfl_xor(d, 2); d += __shfl_xor(d, 4); d += __shfl_xor(d, 8); return d; }
; DI void unit_sample_attn2(int u, const bf16* __restrict__ Q, const float* __restrict__ ckw, const float* __restrict__ cvw, const float* __restrict__ nkw, const float* __restrict__ nvw, const bf16* __restrict__ G, bf16* __restrict__ MIX, ...
;     ...
;         for (int i = 0; i < 16; ++i) { const int n = n0 + 2 * i + half, dlt = sub ? 16 * (33 + n) : 512 - 4 * n;
;             s[i] = dot16(qs, kv[i]) - slope2 * (float)dlt + ((!sub && (dlt & 15) == 0) ? 1.f : 0.f); }
	v_pk_mul_f32 v[116:117], v[116:117], v[158:159]
	v_pk_mul_f32 v[118:119], v[118:119], v[160:161]
	v_pk_mul_f32 v[112:113], v[112:113], v[158:159]
	v_pk_mul_f32 v[114:115], v[114:115], v[160:161]
	v_pk_mul_f32 v[108:109], v[108:109], v[158:159]
	v_pk_mul_f32 v[110:111], v[110:111], v[160:161]
	v_pk_mul_f32 v[104:105], v[104:105], v[158:159]
	v_pk_mul_f32 v[106:107], v[106:107], v[160:161]
	v_add_f32_e32 v116, v117, v116
	v_add_f32_e32 v118, v118, v119
	v_add_f32_e32 v112, v113, v112
	v_add_f32_e32 v114, v114, v115
	v_add_f32_e32 v108, v109, v108
	v_add_f32_e32 v110, v110, v111
	v_add_f32_e32 v104, v105, v104
	v_add_f32_e32 v106, v106, v107
	v_add_f32_e32 v116, v116, v118
	v_add_f32_e32 v112, v112, v114
	v_add_f32_e32 v108, v108, v110
	v_add_f32_e32 v104, v104, v106
	v_add_f32_dpp v116, v116, v116 quad_perm:[1,0,3,2] row_mask:0xf bank_mask:0xf
	v_add_f32_dpp v112, v112, v112 quad_perm:[1,0,3,2] row_mask:0xf bank_mask:0xf
	v_add_f32_dpp v108, v108, v108 quad_perm:[1,0,3,2] row_mask:0xf bank_mask:0xf
	v_add_f32_dpp v104, v104, v104 quad_perm:[1,0,3,2] row_mask:0xf bank_mask:0xf
	v_add_f32_dpp v116, v116, v116 quad_perm:[2,3,0,1] row_mask:0xf bank_mask:0xf
	v_add_f32_dpp v112, v112, v112 quad_perm:[2,3,0,1] row_mask:0xf bank_mask:0xf
	v_add_f32_dpp v108, v108, v108 quad_perm:[2,3,0,1] row_mask:0xf bank_mask:0xf
	v_add_f32_dpp v104, v104, v104 quad_perm:[2,3,0,1] row_mask:0xf bank_mask:0xf
	v_add_f32_dpp v116, v116, v116 row_half_mirror row_mask:0xf bank_mask:0xf
	v_add_f32_dpp v112, v112, v112 row_half_mirror row_mask:0xf bank_mask:0xf
	v_add_f32_dpp v108, v108, v108 row_half_mirror row_mask:0xf bank_mask:0xf
	v_add_f32_dpp v104, v104, v104 row_half_mirror row_mask:0xf bank_mask:0xf
	v_add_f32_dpp v116, v116, v116 row_mirror row_mask:0xf bank_mask:0xf
	v_add_f32_dpp v112, v112, v112 row_mirror row_mask:0xf bank_mask:0xf
	v_add_f32_dpp v108, v108, v108 row_mirror row_mask:0xf bank_mask:0xf
	v_add_f32_dpp v104, v104, v104 row_mirror row_mask:0xf bank_mask:0xf
	v_cvt_f32_i32_e32 v173, v227
	v_add_u32_e32 v227, 0xfffffff8, v227
	v_fma_f32 v116, -v136, v173, v116
	v_add_f32_e32 v116, v172, v116
	v_cvt_f32_i32_e32 v171, v227
	v_add_u32_e32 v227, 0xfffffff8, v227
	v_fma_f32 v112, -v136, v171, v112
	v_cvt_f32_i32_e32 v173, v227
	v_add_u32_e32 v227, 0xfffffff8, v227
	v_fma_f32 v108, -v136, v173, v108
	v_add_f32_e32 v108, v172, v108
	v_cvt_f32_i32_e32 v171, v227
	v_add_u32_e32 v227, 0xfffffff8, v227
	v_fma_f32 v104, -v136, v171, v104
	s_waitcnt vmcnt(37)
	v_pk_mul_f32 v[100:101], v[100:101], v[158:159]
	v_pk_mul_f32 v[102:103], v[102:103], v[160:161]
	v_pk_mul_f32 v[96:97], v[96:97], v[158:159]
	v_pk_mul_f32 v[98:99], v[98:99], v[160:161]
	v_pk_mul_f32 v[92:93], v[92:93], v[158:159]
	v_pk_mul_f32 v[94:95], v[94:95], v[160:161]
	v_pk_mul_f32 v[88:89], v[88:89], v[158:159]
	v_pk_mul_f32 v[90:91], v[90:91], v[160:161]
	v_add_f32_e32 v100, v101, v100
	v_add_f32_e32 v102, v102, v103
	v_add_f32_e32 v96, v97, v96
	v_add_f32_e32 v98, v98, v99
	v_add_f32_e32 v92, v93, v92
	v_add_f32_e32 v94, v94, v95
	v_add_f32_e32 v88, v89, v88
	v_add_f32_e32 v90, v90, v91
	v_add_f32_e32 v100, v100, v102
	v_add_f32_e32 v96, v96, v98
	v_add_f32_e32 v92, v92, v94
	v_add_f32_e32 v88, v88, v90
	v_add_f32_dpp v100, v100, v100 quad_perm:[1,0,3,2] row_mask:0xf bank_mask:0xf
	v_add_f32_dpp v96, v96, v96 quad_perm:[1,0,3,2] row_mask:0xf bank_mask:0xf
	v_add_f32_dpp v92, v92, v92 quad_perm:[1,0,3,2] row_mask:0xf bank_mask:0xf
	v_add_f32_dpp v88, v88, v88 quad_perm:[1,0,3,2] row_mask:0xf bank_mask:0xf
	v_add_f32_dpp v100, v100, v100 quad_perm:[2,3,0,1] row_mask:0xf bank_mask:0xf
	v_add_f32_dpp v96, v96, v96 quad_perm:[2,3,0,1] row_mask:0xf bank_mask:0xf
	v_add_f32_dpp v92, v92, v92 quad_perm:[2,3,0,1] row_mask:0xf bank_mask:0xf
	v_add_f32_dpp v88, v88, v88 quad_perm:[2,3,0,1] row_mask:0xf bank_mask:0xf
	v_add_f32_dpp v100, v100, v100 row_half_mirror row_mask:0xf bank_mask:0xf
	v_add_f32_dpp v96, v96, v96 row_half_mirror row_mask:0xf bank_mask:0xf
	v_add_f32_dpp v92, v92, v92 row_half_mirror row_mask:0xf bank_mask:0xf
	v_add_f32_dpp v88, v88, v88 row_half_mirror row_mask:0xf bank_mask:0xf
	v_add_f32_dpp v100, v100, v100 row_mirror row_mask:0xf bank_mask:0xf
	v_add_f32_dpp v96, v96, v96 row_mirror row_mask:0xf bank_mask:0xf
	v_add_f32_dpp v92, v92, v92 row_mirror row_mask:0xf bank_mask:0xf
	v_add_f32_dpp v88, v88, v88 row_mirror row_mask:0xf bank_mask:0xf
	v_cvt_f32_i32_e32 v173, v227
	v_add_u32_e32 v227, 0xfffffff8, v227
	v_fma_f32 v100, -v136, v173, v100
	v_add_f32_e32 v100, v172, v100
	v_cvt_f32_i32_e32 v171, v227
	v_add_u32_e32 v227, 0xfffffff8, v227
	v_fma_f32 v96, -v136, v171, v96
	v_cvt_f32_i32_e32 v173, v227
	v_add_u32_e32 v227, 0xfffffff8, v227
	v_fma_f32 v92, -v136, v173, v92
	v_add_f32_e32 v92, v172, v92
	v_cvt_f32_i32_e32 v171, v227
	v_add_u32_e32 v227, 0xfffffff8, v227
	v_fma_f32 v88, -v136, v171, v88
	s_waitcnt vmcnt(33)
; DI float fexp2(float x) { return __builtin_amdgcn_exp2f(x); }
; DI float dot16(f32x4 a, f32x4 b) { float d = (a[0] * b[0] + a[1] * b[1]) + (a[2] * b[2] + a[3] * b[3]); d += __shfl_xor(d, 1); d += __shfl_xor(d, 2); d += __shfl_xor(d, 4); d += __shfl_xor(d, 8); return d; }
; DI void unit_sample_attn2(int u, const bf16* __restrict__ Q, const float* __restrict__ ckw, const float* __restrict__ cvw, const float* __restrict__ nkw, const float* __restrict__ nvw, const bf16* __restrict__ G, bf16* __restrict__ MIX, ...
;     ...
;         for (int i = 0; i < 16; ++i) { const int n = n0 + 2 * i + half, dlt = sub ? 16 * (33 + n) : 512 - 4 * n;
;             s[i] = dot16(qs, kv[i]) - slope2 * (float)dlt + ((!sub && (dlt & 15) == 0) ? 1.f : 0.f); }
;         float mn = mB;
; #pragma unroll
;         for (int i = 0; i < 16; ++i) mn = fmaxf(mn, s[i]);
;         const float alpha = fexp2(mB - mn); float ps = 0.f; f32x4 acc = oB * alpha;
; #pragma unroll
;         for (int i = 0; i < 16; ++i) { const float p = fexp2(s[i] - mn); ps += p; acc += vv[i] * p; }
;         lB = lB * alpha + ps; mB = mn; oB = acc;
	v_pk_mul_f32 v[84:85], v[84:85], v[158:159]
	v_pk_mul_f32 v[86:87], v[86:87], v[160:161]
	v_pk_mul_f32 v[80:81], v[80:81], v[158:159]
	v_pk_mul_f32 v[82:83], v[82:83], v[160:161]
	v_pk_mul_f32 v[76:77], v[76:77], v[158:159]
	v_pk_mul_f32 v[78:79], v[78:79], v[160:161]
	v_pk_mul_f32 v[72:73], v[72:73], v[158:159]
	v_pk_mul_f32 v[74:75], v[74:75], v[160:161]
	v_add_f32_e32 v84, v85, v84
	v_add_f32_e32 v86, v86, v87
	v_add_f32_e32 v80, v81, v80
	v_add_f32_e32 v82, v82, v83
	v_add_f32_e32 v76, v77, v76
	v_add_f32_e32 v78, v78, v79
	v_add_f32_e32 v72, v73, v72
	v_add_f32_e32 v74, v74, v75
	v_add_f32_e32 v84, v84, v86
	v_add_f32_e32 v80, v80, v82
	v_add_f32_e32 v76, v76, v78
	v_add_f32_e32 v72, v72, v74
	v_add_f32_dpp v84, v84, v84 quad_perm:[1,0,3,2] row_mask:0xf bank_mask:0xf
	v_add_f32_dpp v80, v80, v80 quad_perm:[1,0,3,2] row_mask:0xf bank_mask:0xf
	v_add_f32_dpp v76, v76, v76 quad_perm:[1,0,3,2] row_mask:0xf bank_mask:0xf
	v_add_f32_dpp v72, v72, v72 quad_perm:[1,0,3,2] row_mask:0xf bank_mask:0xf
	v_add_f32_dpp v84, v84, v84 quad_perm:[2,3,0,1] row_mask:0xf bank_mask:0xf
	v_add_f32_dpp v80, v80, v80 quad_perm:[2,3,0,1] row_mask:0xf bank_mask:0xf
	v_add_f32_dpp v76, v76, v76 quad_perm:[2,3,0,1] row_mask:0xf bank_mask:0xf
	v_add_f32_dpp v72, v72, v72 quad_perm:[2,3,0,1] row_mask:0xf bank_mask:0xf
	v_add_f32_dpp v84, v84, v84 row_half_mirror row_mask:0xf bank_mask:0xf
	v_add_f32_dpp v80, v80, v80 row_half_mirror row_mask:0xf bank_mask:0xf
	v_add_f32_dpp v76, v76, v76 row_half_mirror row_mask:0xf bank_mask:0xf
	v_add_f32_dpp v72, v72, v72 row_half_mirror row_mask:0xf bank_mask:0xf
	v_add_f32_dpp v84, v84, v84 row_mirror row_mask:0xf bank_mask:0xf
	v_add_f32_dpp v80, v80, v80 row_mirror row_mask:0xf bank_mask:0xf
	v_add_f32_dpp v76, v76, v76 row_mirror row_mask:0xf bank_mask:0xf
	v_add_f32_dpp v72, v72, v72 row_mirror row_mask:0xf bank_mask:0xf
	v_cvt_f32_i32_e32 v173, v227
	v_add_u32_e32 v227, 0xfffffff8, v227
	v_fma_f32 v84, -v136, v173, v84
	v_add_f32_e32 v84, v172, v84
	v_cvt_f32_i32_e32 v171, v227
	v_add_u32_e32 v227, 0xfffffff8, v227
	v_fma_f32 v80, -v136, v171, v80
	v_cvt_f32_i32_e32 v173, v227
	v_add_u32_e32 v227, 0xfffffff8, v227
	v_fma_f32 v76, -v136, v173, v76
	v_add_f32_e32 v76, v172, v76
	v_cvt_f32_i32_e32 v171, v227
	v_add_u32_e32 v227, 0xfffffff8, v227
	v_fma_f32 v72, -v136, v171, v72
	v_max3_f32 v135, v175, v132, v128
	v_max3_f32 v135, v135, v124, v120
	v_max3_f32 v135, v135, v116, v112
	v_max3_f32 v135, v135, v108, v104
	v_max3_f32 v135, v135, v100, v96
	v_max3_f32 v135, v135, v92, v88
	v_max3_f32 v135, v135, v84, v80
	v_max3_f32 v135, v135, v76, v72
	v_sub_f32_e32 v133, v175, v135
	v_sub_f32_e32 v132, v132, v135
	v_sub_f32_e32 v128, v128, v135
	v_sub_f32_e32 v124, v124, v135
	v_sub_f32_e32 v120, v120, v135
	v_sub_f32_e32 v116, v116, v135
	v_sub_f32_e32 v112, v112, v135
	v_sub_f32_e32 v108, v108, v135
	v_sub_f32_e32 v104, v104, v135
	v_sub_f32_e32 v100, v100, v135
	v_sub_f32_e32 v96, v96, v135
	v_sub_f32_e32 v92, v92, v135
	v_sub_f32_e32 v88, v88, v135
	v_sub_f32_e32 v84, v84, v135
	v_sub_f32_e32 v80, v80, v135
	v_sub_f32_e32 v76, v76, v135
	v_sub_f32_e32 v72, v72, v135
	v_exp_f32_e32 v133, v133
	v_exp_f32_e32 v132, v132
	v_exp_f32_e32 v128, v128
	v_exp_f32_e32 v124, v124
	v_exp_f32_e32 v120, v120
	v_exp_f32_e32 v116, v116
	v_exp_f32_e32 v112, v112
	v_exp_f32_e32 v108, v108
	v_exp_f32_e32 v104, v104
	v_exp_f32_e32 v100, v100
	v_exp_f32_e32 v96, v96
	v_exp_f32_e32 v92, v92
	v_exp_f32_e32 v88, v88
	v_exp_f32_e32 v84, v84
	v_exp_f32_e32 v80, v80
	v_exp_f32_e32 v76, v76
	v_exp_f32_e32 v72, v72
	v_mov_b32_e32 v175, v135
	v_add_f32_e32 v134, 0, v132
	v_add_f32_e32 v134, v128, v134
	v_add_f32_e32 v134, v124, v134
	v_add_f32_e32 v134, v120, v134
	v_add_f32_e32 v134, v116, v134
	v_add_f32_e32 v134, v112, v134
	v_add_f32_e32 v134, v108, v134
	v_add_f32_e32 v134, v104, v134
	v_add_f32_e32 v134, v100, v134
	v_add_f32_e32 v134, v96, v134
	v_add_f32_e32 v134, v92, v134
	v_add_f32_e32 v134, v88, v134
	v_add_f32_e32 v134, v84, v134
	v_add_f32_e32 v134, v80, v134
	v_add_f32_e32 v134, v76, v134
	v_add_f32_e32 v134, v72, v134
	s_waitcnt vmcnt(29)
	v_mul_f32_e32 v68, v68, v132
	v_mul_f32_e32 v69, v69, v132
	v_mul_f32_e32 v70, v70, v132
	v_mul_f32_e32 v71, v71, v132
	v_fma_f32 v4, v4, v133, v68
	v_fma_f32 v5, v5, v133, v69
	v_fma_f32 v6, v6, v133, v70
	v_fma_f32 v7, v7, v133, v71
	v_fma_f32 v4, v64, v128, v4
	v_fma_f32 v5, v65, v128, v5
	v_fma_f32 v6, v66, v128, v6
	v_fma_f32 v7, v67, v128, v7
	v_fma_f32 v4, v60, v124, v4
	v_fma_f32 v5, v61, v124, v5
	v_fma_f32 v6, v62, v124, v6
	v_fma_f32 v7, v63, v124, v7
	v_fma_f32 v4, v56, v120, v4
	v_fma_f32 v5, v57, v120, v5
	v_fma_f32 v6, v58, v120, v6
	v_fma_f32 v7, v59, v120, v7
	s_waitcnt vmcnt(25)
	v_fma_f32 v4, v52, v116, v4
	v_fma_f32 v5, v53, v116, v5
	v_fma_f32 v6, v54, v116, v6
	v_fma_f32 v7, v55, v116, v7
	v_fma_f32 v4, v48, v112, v4
	v_fma_f32 v5, v49, v112, v5
	v_fma_f32 v6, v50, v112, v6
	v_fma_f32 v7, v51, v112, v7
	v_fma_f32 v4, v44, v108, v4
	v_fma_f32 v5, v45, v108, v5
	v_fma_f32 v6, v46, v108, v6
	v_fma_f32 v7, v47, v108, v7
	v_fma_f32 v4, v40, v104, v4
	v_fma_f32 v5, v41, v104, v5
	v_fma_f32 v6, v42, v104, v6
	v_fma_f32 v7, v43, v104, v7
	s_waitcnt vmcnt(21)
	v_fma_f32 v4, v36, v100, v4
	v_fma_f32 v5, v37, v100, v5
	v_fma_f32 v6, v38, v100, v6
	v_fma_f32 v7, v39, v100, v7
	v_fma_f32 v4, v32, v96, v4
	v_fma_f32 v5, v33, v96, v5
	v_fma_f32 v6, v34, v96, v6
	v_fma_f32 v7, v35, v96, v7
	v_fma_f32 v4, v28, v92, v4
	v_fma_f32 v5, v29, v92, v5
	v_fma_f32 v6, v30, v92, v6
	v_fma_f32 v7, v31, v92, v7
	v_fma_f32 v4, v24, v88, v4
	v_fma_f32 v5, v25, v88, v5
	v_fma_f32 v6, v26, v88, v6
	v_fma_f32 v7, v27, v88, v7
	s_waitcnt vmcnt(17)
; DI float fexp2(float x) { return __builtin_amdgcn_exp2f(x); }
; DI float dot16(f32x4 a, f32x4 b) { float d = (a[0] * b[0] + a[1] * b[1]) + (a[2] * b[2] + a[3] * b[3]); d += __shfl_xor(d, 1); d += __shfl_xor(d, 2); d += __shfl_xor(d, 4); d += __shfl_xor(d, 8); return d; }
; DI void unit_sample_attn2(int u, const bf16* __restrict__ Q, const float* __restrict__ ckw, const float* __restrict__ cvw, const float* __restrict__ nkw, const float* __restrict__ nvw, const bf16* __restrict__ G, bf16* __restrict__ MIX, ...
;     ...
;     for (int n0 = 0; n0 < 96; n0 += 32) {
;         f32x4 kv[16], vv[16]; float s[16];
; #pragma unroll
;         for (int i = 0; i < 16; ++i) { const int n = n0 + 2 * i + half, dlt = sub ? 16 * (33 + n) : 512 - 4 * n; const size_t ro = (size_t)(2048 + j1 - dlt) * 512;
;             kv[i] = __builtin_nontemporal_load((const f32x4*)(ck + ro)); }
; #pragma unroll
;         for (int i = 0; i < 16; ++i) { const int n = n0 + 2 * i + half, dlt = sub ? 16 * (33 + n) : 512 - 4 * n; const size_t ro = (size_t)(2048 + j1 - dlt) * 512;
;             vv[i] = __builtin_nontemporal_load((const f32x4*)(cv + ro)); }
; #pragma unroll
;         for (int i = 0; i < 16; ++i) { const int n = n0 + 2 * i + half, dlt = sub ? 16 * (33 + n) : 512 - 4 * n;
;             s[i] = dot16(qs, kv[i]) - slope2 * (float)dlt + ((!sub && (dlt & 15) == 0) ? 1.f : 0.f); }
;         float mn = mB;
; #pragma unroll
;         for (int i = 0; i < 16; ++i) mn = fmaxf(mn, s[i]);
;         const float alpha = fexp2(mB - mn); float ps = 0.f; f32x4 acc = oB * alpha;
; #pragma unroll
;         for (int i = 0; i < 16; ++i) { const float p = fexp2(s[i] - mn); ps += p; acc += vv[i] * p; }
;         lB = lB * alpha + ps; mB = mn; oB = acc;
	v_fma_f32 v4, v20, v84, v4
	v_fma_f32 v5, v21, v84, v5
	v_fma_f32 v6, v22, v84, v6
	v_fma_f32 v7, v23, v84, v7
	v_fma_f32 v4, v16, v80, v4
	v_fma_f32 v5, v17, v80, v5
	v_fma_f32 v6, v18, v80, v6
	v_fma_f32 v7, v19, v80, v7
	v_fma_f32 v4, v12, v76, v4
	v_fma_f32 v5, v13, v76, v5
	v_fma_f32 v6, v14, v76, v6
	v_fma_f32 v7, v15, v76, v7
	v_fma_f32 v4, v8, v72, v4
	v_fma_f32 v5, v9, v72, v5
	v_fma_f32 v6, v10, v72, v6
	v_fma_f32 v7, v11, v72, v7
	v_fma_f32 v174, v174, v133, v134
	v_add_u32_e32 v225, 0x40000, v224
	global_load_dwordx4 v[68:71], v225, s[2:3] nt
	v_add_u32_e32 v225, 0x4000, v225
	global_load_dwordx4 v[64:67], v225, s[2:3] nt
	v_add_u32_e32 v225, 0x4000, v225
	global_load_dwordx4 v[60:63], v225, s[2:3] nt
	v_add_u32_e32 v225, 0x4000, v225
	global_load_dwordx4 v[56:59], v225, s[2:3] nt
	v_add_u32_e32 v225, 0x4000, v225
	global_load_dwordx4 v[52:55], v225, s[2:3] nt
	v_add_u32_e32 v225, 0x4000, v225
	global_load_dwordx4 v[48:51], v225, s[2:3] nt
	v_add_u32_e32 v225, 0x4000, v225
	global_load_dwordx4 v[44:47], v225, s[2:3] nt
	v_add_u32_e32 v225, 0x4000, v225
	global_load_dwordx4 v[40:43], v225, s[2:3] nt
	v_add_u32_e32 v225, 0x4000, v225
	global_load_dwordx4 v[36:39], v225, s[2:3] nt
	v_add_u32_e32 v225, 0x4000, v225
	global_load_dwordx4 v[32:35], v225, s[2:3] nt
	v_add_u32_e32 v225, 0x4000, v225
	global_load_dwordx4 v[28:31], v225, s[2:3] nt
	v_add_u32_e32 v225, 0x4000, v225
	global_load_dwordx4 v[24:27], v225, s[2:3] nt
	v_add_u32_e32 v225, 0x4000, v225
	global_load_dwordx4 v[20:23], v225, s[2:3] nt
	v_add_u32_e32 v225, 0x4000, v225
	global_load_dwordx4 v[16:19], v225, s[2:3] nt
	v_add_u32_e32 v225, 0x4000, v225
	global_load_dwordx4 v[12:15], v225, s[2:3] nt
	v_add_u32_e32 v225, 0x4000, v225
	global_load_dwordx4 v[8:11], v225, s[2:3] nt
	v_add_u32_e32 v225, 0x80000, v224
	global_load_dwordx4 v[132:135], v225, s[0:1] nt
	v_add_u32_e32 v225, 0x4000, v225
	global_load_dwordx4 v[128:131], v225, s[0:1] nt
	v_add_u32_e32 v225, 0x4000, v225
	global_load_dwordx4 v[124:127], v225, s[0:1] nt
	v_add_u32_e32 v225, 0x4000, v225
	global_load_dwordx4 v[120:123], v225, s[0:1] nt
	v_add_u32_e32 v225, 0x4000, v225
	global_load_dwordx4 v[116:119], v225, s[0:1] nt
	v_add_u32_e32 v225, 0x4000, v225
	global_load_dwordx4 v[112:115], v225, s[0:1] nt
	v_add_u32_e32 v225, 0x4000, v225
	global_load_dwordx4 v[108:111], v225, s[0:1] nt
	v_add_u32_e32 v225, 0x4000, v225
	global_load_dwordx4 v[104:107], v225, s[0:1] nt
	v_add_u32_e32 v225, 0x4000, v225
	global_load_dwordx4 v[100:103], v225, s[0:1] nt
	v_add_u32_e32 v225, 0x4000, v225
	global_load_dwordx4 v[96:99], v225, s[0:1] nt
	v_add_u32_e32 v225, 0x4000, v225
	global_load_dwordx4 v[92:95], v225, s[0:1] nt
	v_add_u32_e32 v225, 0x4000, v225
	global_load_dwordx4 v[88:91], v225, s[0:1] nt
	v_add_u32_e32 v225, 0x4000, v225
	global_load_dwordx4 v[84:87], v225, s[0:1] nt
	v_add_u32_e32 v225, 0x4000, v225
	global_load_dwordx4 v[80:83], v225, s[0:1] nt
	v_add_u32_e32 v225, 0x4000, v225
	global_load_dwordx4 v[76:79], v225, s[0:1] nt
	v_add_u32_e32 v225, 0x4000, v225
	global_load_dwordx4 v[72:75], v225, s[0:1] nt
	v_add_u32_e32 v227, 0xfffffff8, v163
	s_waitcnt vmcnt(45)
	v_pk_mul_f32 v[188:189], v[188:189], v[158:159]
	v_pk_mul_f32 v[190:191], v[190:191], v[160:161]
	v_pk_mul_f32 v[192:193], v[192:193], v[158:159]
	v_pk_mul_f32 v[194:195], v[194:195], v[160:161]
	v_pk_mul_f32 v[196:197], v[196:197], v[158:159]
	v_pk_mul_f32 v[198:199], v[198:199], v[160:161]
	v_pk_mul_f32 v[200:201], v[200:201], v[158:159]
	v_pk_mul_f32 v[202:203], v[202:203], v[160:161]
	v_add_f32_e32 v188, v189, v188
	v_add_f32_e32 v190, v190, v191
	v_add_f32_e32 v192, v193, v192
	v_add_f32_e32 v194, v194, v195
	v_add_f32_e32 v196, v197, v196
	v_add_f32_e32 v198, v198, v199
	v_add_f32_e32 v200, v201, v200
	v_add_f32_e32 v202, v202, v203
	v_add_f32_e32 v188, v188, v190
	v_add_f32_e32 v192, v192, v194
	v_add_f32_e32 v196, v196, v198
	v_add_f32_e32 v200, v200, v202
	v_add_f32_dpp v188, v188, v188 quad_perm:[1,0,3,2] row_mask:0xf bank_mask:0xf
	v_add_f32_dpp v192, v192, v192 quad_perm:[1,0,3,2] row_mask:0xf bank_mask:0xf
	v_add_f32_dpp v196, v196, v196 quad_perm:[1,0,3,2] row_mask:0xf bank_mask:0xf
	v_add_f32_dpp v200, v200, v200 quad_perm:[1,0,3,2] row_mask:0xf bank_mask:0xf
	v_add_f32_dpp v188, v188, v188 quad_perm:[2,3,0,1] row_mask:0xf bank_mask:0xf
	v_add_f32_dpp v192, v192, v192 quad_perm:[2,3,0,1] row_mask:0xf bank_mask:0xf
	v_add_f32_dpp v196, v196, v196 quad_perm:[2,3,0,1] row_mask:0xf bank_mask:0xf
	v_add_f32_dpp v200, v200, v200 quad_perm:[2,3,0,1] row_mask:0xf bank_mask:0xf
	v_add_f32_dpp v188, v188, v188 row_half_mirror row_mask:0xf bank_mask:0xf
	v_add_f32_dpp v192, v192, v192 row_half_mirror row_mask:0xf bank_mask:0xf
	v_add_f32_dpp v196, v196, v196 row_half_mirror row_mask:0xf bank_mask:0xf
	v_add_f32_dpp v200, v200, v200 row_half_mirror row_mask:0xf bank_mask:0xf
	v_add_f32_dpp v188, v188, v188 row_mirror row_mask:0xf bank_mask:0xf
	v_add_f32_dpp v192, v192, v192 row_mirror row_mask:0xf bank_mask:0xf
	v_add_f32_dpp v196, v196, v196 row_mirror row_mask:0xf bank_mask:0xf
	v_add_f32_dpp v200, v200, v200 row_mirror row_mask:0xf bank_mask:0xf
	v_cvt_f32_i32_e32 v173, v227
	v_add_u32_e32 v227, 0xfffffff8, v227
	v_fma_f32 v188, -v136, v173, v188
	v_add_f32_e32 v188, v172, v188
	v_cvt_f32_i32_e32 v171, v227
	v_add_u32_e32 v227, 0xfffffff8, v227
	v_fma_f32 v192, -v136, v171, v192
	v_cvt_f32_i32_e32 v173, v227
	v_add_u32_e32 v227, 0xfffffff8, v227
	v_fma_f32 v196, -v136, v173, v196
	v_add_f32_e32 v196, v172, v196
	v_cvt_f32_i32_e32 v171, v227
	v_add_u32_e32 v227, 0xfffffff8, v227
	v_fma_f32 v200, -v136, v171, v200
	s_waitcnt vmcnt(41)
; DI float dot16(f32x4 a, f32x4 b) { float d = (a[0] * b[0] + a[1] * b[1]) + (a[2] * b[2] + a[3] * b[3]); d += __shfl_xor(d, 1); d += __shfl_xor(d, 2); d += __shfl_xor(d, 4); d += __shfl_xor(d, 8); return d; }
; DI void unit_sample_attn2(int u, const bf16* __restrict__ Q, const float* __restrict__ ckw, const float* __restrict__ cvw, const float* __restrict__ nkw, const float* __restrict__ nvw, const bf16* __restrict__ G, bf16* __restrict__ MIX, ...
;     ...
;         for (int i = 0; i < 16; ++i) { const int n = n0 + 2 * i + half, dlt = sub ? 16 * (33 + n) : 512 - 4 * n;
;             s[i] = dot16(qs, kv[i]) - slope2 * (float)dlt + ((!sub && (dlt & 15) == 0) ? 1.f : 0.f); }
	v_pk_mul_f32 v[204:205], v[204:205], v[158:159]
	v_pk_mul_f32 v[206:207], v[206:207], v[160:161]
	v_pk_mul_f32 v[208:209], v[208:209], v[158:159]
	v_pk_mul_f32 v[210:211], v[210:211], v[160:161]
	v_pk_mul_f32 v[212:213], v[212:213], v[158:159]
	v_pk_mul_f32 v[214:215], v[214:215], v[160:161]
	v_pk_mul_f32 v[216:217], v[216:217], v[158:159]
	v_pk_mul_f32 v[218:219], v[218:219], v[160:161]
	v_add_f32_e32 v204, v205, v204
	v_add_f32_e32 v206, v206, v207
	v_add_f32_e32 v208, v209, v208
	v_add_f32_e32 v210, v210, v211
	v_add_f32_e32 v212, v213, v212
	v_add_f32_e32 v214, v214, v215
	v_add_f32_e32 v216, v217, v216
	v_add_f32_e32 v218, v218, v219
	v_add_f32_e32 v204, v204, v206
	v_add_f32_e32 v208, v208, v210
	v_add_f32_e32 v212, v212, v214
	v_add_f32_e32 v216, v216, v218
	v_add_f32_dpp v204, v204, v204 quad_perm:[1,0,3,2] row_mask:0xf bank_mask:0xf
	v_add_f32_dpp v208, v208, v208 quad_perm:[1,0,3,2] row_mask:0xf bank_mask:0xf
	v_add_f32_dpp v212, v212, v212 quad_perm:[1,0,3,2] row_mask:0xf bank_mask:0xf
	v_add_f32_dpp v216, v216, v216 quad_perm:[1,0,3,2] row_mask:0xf bank_mask:0xf
	v_add_f32_dpp v204, v204, v204 quad_perm:[2,3,0,1] row_mask:0xf bank_mask:0xf
	v_add_f32_dpp v208, v208, v208 quad_perm:[2,3,0,1] row_mask:0xf bank_mask:0xf
	v_add_f32_dpp v212, v212, v212 quad_perm:[2,3,0,1] row_mask:0xf bank_mask:0xf
	v_add_f32_dpp v216, v216, v216 quad_perm:[2,3,0,1] row_mask:0xf bank_mask:0xf
	v_add_f32_dpp v204, v204, v204 row_half_mirror row_mask:0xf bank_mask:0xf
	v_add_f32_dpp v208, v208, v208 row_half_mirror row_mask:0xf bank_mask:0xf
	v_add_f32_dpp v212, v212, v212 row_half_mirror row_mask:0xf bank_mask:0xf
	v_add_f32_dpp v216, v216, v216 row_half_mirror row_mask:0xf bank_mask:0xf
	v_add_f32_dpp v204, v204, v204 row_mirror row_mask:0xf bank_mask:0xf
	v_add_f32_dpp v208, v208, v208 row_mirror row_mask:0xf bank_mask:0xf
	v_add_f32_dpp v212, v212, v212 row_mirror row_mask:0xf bank_mask:0xf
	v_add_f32_dpp v216, v216, v216 row_mirror row_mask:0xf bank_mask:0xf
	v_cvt_f32_i32_e32 v173, v227
	v_add_u32_e32 v227, 0xfffffff8, v227
	v_fma_f32 v204, -v136, v173, v204
	v_add_f32_e32 v204, v172, v204
	v_cvt_f32_i32_e32 v171, v227
	v_add_u32_e32 v227, 0xfffffff8, v227
	v_fma_f32 v208, -v136, v171, v208
	v_cvt_f32_i32_e32 v173, v227
	v_add_u32_e32 v227, 0xfffffff8, v227
	v_fma_f32 v212, -v136, v173, v212
	v_add_f32_e32 v212, v172, v212
	v_cvt_f32_i32_e32 v171, v227
	v_add_u32_e32 v227, 0xfffffff8, v227
	v_fma_f32 v216, -v136, v171, v216
	s_waitcnt vmcnt(37)
	v_pk_mul_f32 v[220:221], v[220:221], v[158:159]
	v_pk_mul_f32 v[222:223], v[222:223], v[160:161]
	v_pk_mul_f32 v[228:229], v[228:229], v[158:159]
	v_pk_mul_f32 v[230:231], v[230:231], v[160:161]
	v_pk_mul_f32 v[232:233], v[232:233], v[158:159]
	v_pk_mul_f32 v[234:235], v[234:235], v[160:161]
	v_pk_mul_f32 v[236:237], v[236:237], v[158:159]
	v_pk_mul_f32 v[238:239], v[238:239], v[160:161]
	v_add_f32_e32 v220, v221, v220
	v_add_f32_e32 v222, v222, v223
	v_add_f32_e32 v228, v229, v228
	v_add_f32_e32 v230, v230, v231
	v_add_f32_e32 v232, v233, v232
	v_add_f32_e32 v234, v234, v235
	v_add_f32_e32 v236, v237, v236
	v_add_f32_e32 v238, v238, v239
	v_add_f32_e32 v220, v220, v222
	v_add_f32_e32 v228, v228, v230
	v_add_f32_e32 v232, v232, v234
	v_add_f32_e32 v236, v236, v238
	v_add_f32_dpp v220, v220, v220 quad_perm:[1,0,3,2] row_mask:0xf bank_mask:0xf
	v_add_f32_dpp v228, v228, v228 quad_perm:[1,0,3,2] row_mask:0xf bank_mask:0xf
	v_add_f32_dpp v232, v232, v232 quad_perm:[1,0,3,2] row_mask:0xf bank_mask:0xf
	v_add_f32_dpp v236, v236, v236 quad_perm:[1,0,3,2] row_mask:0xf bank_mask:0xf
	v_add_f32_dpp v220, v220, v220 quad_perm:[2,3,0,1] row_mask:0xf bank_mask:0xf
	v_add_f32_dpp v228, v228, v228 quad_perm:[2,3,0,1] row_mask:0xf bank_mask:0xf
	v_add_f32_dpp v232, v232, v232 quad_perm:[2,3,0,1] row_mask:0xf bank_mask:0xf
	v_add_f32_dpp v236, v236, v236 quad_perm:[2,3,0,1] row_mask:0xf bank_mask:0xf
	v_add_f32_dpp v220, v220, v220 row_half_mirror row_mask:0xf bank_mask:0xf
	v_add_f32_dpp v228, v228, v228 row_half_mirror row_mask:0xf bank_mask:0xf
	v_add_f32_dpp v232, v232, v232 row_half_mirror row_mask:0xf bank_mask:0xf
	v_add_f32_dpp v236, v236, v236 row_half_mirror row_mask:0xf bank_mask:0xf
	v_add_f32_dpp v220, v220, v220 row_mirror row_mask:0xf bank_mask:0xf
	v_add_f32_dpp v228, v228, v228 row_mirror row_mask:0xf bank_mask:0xf
	v_add_f32_dpp v232, v232, v232 row_mirror row_mask:0xf bank_mask:0xf
	v_add_f32_dpp v236, v236, v236 row_mirror row_mask:0xf bank_mask:0xf
	v_cvt_f32_i32_e32 v173, v227
	v_add_u32_e32 v227, 0xfffffff8, v227
	v_fma_f32 v220, -v136, v173, v220
	v_add_f32_e32 v220, v172, v220
	v_cvt_f32_i32_e32 v171, v227
	v_add_u32_e32 v227, 0xfffffff8, v227
	v_fma_f32 v228, -v136, v171, v228
	v_cvt_f32_i32_e32 v173, v227
	v_add_u32_e32 v227, 0xfffffff8, v227
	v_fma_f32 v232, -v136, v173, v232
	v_add_f32_e32 v232, v172, v232
	v_cvt_f32_i32_e32 v171, v227
	v_add_u32_e32 v227, 0xfffffff8, v227
	v_fma_f32 v236, -v136, v171, v236
	s_waitcnt vmcnt(32)
; DI float fexp2(float x) { return __builtin_amdgcn_exp2f(x); }
; DI float dot16(f32x4 a, f32x4 b) { float d = (a[0] * b[0] + a[1] * b[1]) + (a[2] * b[2] + a[3] * b[3]); d += __shfl_xor(d, 1); d += __shfl_xor(d, 2); d += __shfl_xor(d, 4); d += __shfl_xor(d, 8); return d; }
; DI void unit_sample_attn2(int u, const bf16* __restrict__ Q, const float* __restrict__ ckw, const float* __restrict__ cvw, const float* __restrict__ nkw, const float* __restrict__ nvw, const bf16* __restrict__ G, bf16* __restrict__ MIX, ...
;     ...
;         for (int i = 0; i < 16; ++i) { const int n = n0 + 2 * i + half, dlt = sub ? 16 * (33 + n) : 512 - 4 * n;
;             s[i] = dot16(qs, kv[i]) - slope2 * (float)dlt + ((!sub && (dlt & 15) == 0) ? 1.f : 0.f); }
;         float mn = mB;
; #pragma unroll
;         for (int i = 0; i < 16; ++i) mn = fmaxf(mn, s[i]);
;         const float alpha = fexp2(mB - mn); float ps = 0.f; f32x4 acc = oB * alpha;
; #pragma unroll
;         for (int i = 0; i < 16; ++i) { const float p = fexp2(s[i] - mn); ps += p; acc += vv[i] * p; }
;         lB = lB * alpha + ps; mB = mn; oB = acc;
	v_pk_mul_f32 v[240:241], v[240:241], v[158:159]
	v_pk_mul_f32 v[242:243], v[242:243], v[160:161]
	v_pk_mul_f32 v[176:177], v[176:177], v[158:159]
	v_pk_mul_f32 v[178:179], v[178:179], v[160:161]
	v_pk_mul_f32 v[184:185], v[184:185], v[158:159]
	v_pk_mul_f32 v[186:187], v[186:187], v[160:161]
	v_pk_mul_f32 v[180:181], v[180:181], v[158:159]
	v_pk_mul_f32 v[244:245], v[244:245], v[160:161]
	v_add_f32_e32 v240, v241, v240
	v_add_f32_e32 v242, v242, v243
	v_add_f32_e32 v176, v177, v176
	v_add_f32_e32 v178, v178, v179
	v_add_f32_e32 v184, v185, v184
	v_add_f32_e32 v186, v186, v187
	v_add_f32_e32 v180, v181, v180
	v_add_f32_e32 v244, v244, v245
	v_add_f32_e32 v240, v240, v242
	v_add_f32_e32 v176, v176, v178
	v_add_f32_e32 v184, v184, v186
	v_add_f32_e32 v180, v180, v244
	v_add_f32_dpp v240, v240, v240 quad_perm:[1,0,3,2] row_mask:0xf bank_mask:0xf
	v_add_f32_dpp v176, v176, v176 quad_perm:[1,0,3,2] row_mask:0xf bank_mask:0xf
	v_add_f32_dpp v184, v184, v184 quad_perm:[1,0,3,2] row_mask:0xf bank_mask:0xf
	v_add_f32_dpp v180, v180, v180 quad_perm:[1,0,3,2] row_mask:0xf bank_mask:0xf
	v_add_f32_dpp v240, v240, v240 quad_perm:[2,3,0,1] row_mask:0xf bank_mask:0xf
	v_add_f32_dpp v176, v176, v176 quad_perm:[2,3,0,1] row_mask:0xf bank_mask:0xf
	v_add_f32_dpp v184, v184, v184 quad_perm:[2,3,0,1] row_mask:0xf bank_mask:0xf
	v_add_f32_dpp v180, v180, v180 quad_perm:[2,3,0,1] row_mask:0xf bank_mask:0xf
	v_add_f32_dpp v240, v240, v240 row_half_mirror row_mask:0xf bank_mask:0xf
	v_add_f32_dpp v176, v176, v176 row_half_mirror row_mask:0xf bank_mask:0xf
	v_add_f32_dpp v184, v184, v184 row_half_mirror row_mask:0xf bank_mask:0xf
	v_add_f32_dpp v180, v180, v180 row_half_mirror row_mask:0xf bank_mask:0xf
	v_add_f32_dpp v240, v240, v240 row_mirror row_mask:0xf bank_mask:0xf
	v_add_f32_dpp v176, v176, v176 row_mirror row_mask:0xf bank_mask:0xf
	v_add_f32_dpp v184, v184, v184 row_mirror row_mask:0xf bank_mask:0xf
	v_add_f32_dpp v180, v180, v180 row_mirror row_mask:0xf bank_mask:0xf
	v_cvt_f32_i32_e32 v173, v227
	v_add_u32_e32 v227, 0xfffffff8, v227
	v_fma_f32 v240, -v136, v173, v240
	v_add_f32_e32 v240, v172, v240
	v_cvt_f32_i32_e32 v171, v227
	v_add_u32_e32 v227, 0xfffffff8, v227
	v_fma_f32 v176, -v136, v171, v176
	v_cvt_f32_i32_e32 v173, v227
	v_add_u32_e32 v227, 0xfffffff8, v227
	v_fma_f32 v184, -v136, v173, v184
	v_add_f32_e32 v184, v172, v184
	v_cvt_f32_i32_e32 v171, v227
	v_add_u32_e32 v227, 0xfffffff8, v227
	v_fma_f32 v180, -v136, v171, v180
	v_max3_f32 v191, v175, v188, v192
	v_max3_f32 v191, v191, v196, v200
	v_max3_f32 v191, v191, v204, v208
	v_max3_f32 v191, v191, v212, v216
	v_max3_f32 v191, v191, v220, v228
	v_max3_f32 v191, v191, v232, v236
	v_max3_f32 v191, v191, v240, v176
	v_max3_f32 v191, v191, v184, v180
	v_sub_f32_e32 v189, v175, v191
	v_sub_f32_e32 v188, v188, v191
	v_sub_f32_e32 v192, v192, v191
	v_sub_f32_e32 v196, v196, v191
	v_sub_f32_e32 v200, v200, v191
	v_sub_f32_e32 v204, v204, v191
	v_sub_f32_e32 v208, v208, v191
	v_sub_f32_e32 v212, v212, v191
	v_sub_f32_e32 v216, v216, v191
	v_sub_f32_e32 v220, v220, v191
	v_sub_f32_e32 v228, v228, v191
	v_sub_f32_e32 v232, v232, v191
	v_sub_f32_e32 v236, v236, v191
	v_sub_f32_e32 v240, v240, v191
	v_sub_f32_e32 v176, v176, v191
	v_sub_f32_e32 v184, v184, v191
	v_sub_f32_e32 v180, v180, v191
	v_exp_f32_e32 v189, v189
	v_exp_f32_e32 v188, v188
	v_exp_f32_e32 v192, v192
	v_exp_f32_e32 v196, v196
	v_exp_f32_e32 v200, v200
	v_exp_f32_e32 v204, v204
	v_exp_f32_e32 v208, v208
	v_exp_f32_e32 v212, v212
	v_exp_f32_e32 v216, v216
	v_exp_f32_e32 v220, v220
	v_exp_f32_e32 v228, v228
	v_exp_f32_e32 v232, v232
	v_exp_f32_e32 v236, v236
	v_exp_f32_e32 v240, v240
	v_exp_f32_e32 v176, v176
	v_exp_f32_e32 v184, v184
	v_exp_f32_e32 v180, v180
	v_mov_b32_e32 v175, v191
	v_add_f32_e32 v190, 0, v188
	v_add_f32_e32 v190, v192, v190
	v_add_f32_e32 v190, v196, v190
	v_add_f32_e32 v190, v200, v190
	v_add_f32_e32 v190, v204, v190
	v_add_f32_e32 v190, v208, v190
	v_add_f32_e32 v190, v212, v190
	v_add_f32_e32 v190, v216, v190
	v_add_f32_e32 v190, v220, v190
	v_add_f32_e32 v190, v228, v190
	v_add_f32_e32 v190, v232, v190
	v_add_f32_e32 v190, v236, v190
	v_add_f32_e32 v190, v240, v190
	v_add_f32_e32 v190, v176, v190
	v_add_f32_e32 v190, v184, v190
	v_add_f32_e32 v190, v180, v190
	s_waitcnt vmcnt(28)
	v_mul_f32_e32 v68, v68, v188
	v_mul_f32_e32 v69, v69, v188
	v_mul_f32_e32 v70, v70, v188
	v_mul_f32_e32 v71, v71, v188
	v_fma_f32 v4, v4, v189, v68
	v_fma_f32 v5, v5, v189, v69
	v_fma_f32 v6, v6, v189, v70
	v_fma_f32 v7, v7, v189, v71
	v_fma_f32 v4, v64, v192, v4
	v_fma_f32 v5, v65, v192, v5
	v_fma_f32 v6, v66, v192, v6
	v_fma_f32 v7, v67, v192, v7
	v_fma_f32 v4, v60, v196, v4
	v_fma_f32 v5, v61, v196, v5
	v_fma_f32 v6, v62, v196, v6
	v_fma_f32 v7, v63, v196, v7
	v_fma_f32 v4, v56, v200, v4
	v_fma_f32 v5, v57, v200, v5
	v_fma_f32 v6, v58, v200, v6
	v_fma_f32 v7, v59, v200, v7
	s_waitcnt vmcnt(24)
	v_fma_f32 v4, v52, v204, v4
	v_fma_f32 v5, v53, v204, v5
	v_fma_f32 v6, v54, v204, v6
	v_fma_f32 v7, v55, v204, v7
	v_fma_f32 v4, v48, v208, v4
	v_fma_f32 v5, v49, v208, v5
	v_fma_f32 v6, v50, v208, v6
	v_fma_f32 v7, v51, v208, v7
	v_fma_f32 v4, v44, v212, v4
	v_fma_f32 v5, v45, v212, v5
	v_fma_f32 v6, v46, v212, v6
	v_fma_f32 v7, v47, v212, v7
	v_fma_f32 v4, v40, v216, v4
	v_fma_f32 v5, v41, v216, v5
	v_fma_f32 v6, v42, v216, v6
	v_fma_f32 v7, v43, v216, v7
	s_waitcnt vmcnt(20)
	v_fma_f32 v4, v36, v220, v4
	v_fma_f32 v5, v37, v220, v5
	v_fma_f32 v6, v38, v220, v6
	v_fma_f32 v7, v39, v220, v7
	v_fma_f32 v4, v32, v228, v4
	v_fma_f32 v5, v33, v228, v5
	v_fma_f32 v6, v34, v228, v6
	v_fma_f32 v7, v35, v228, v7
	v_fma_f32 v4, v28, v232, v4
	v_fma_f32 v5, v29, v232, v5
	v_fma_f32 v6, v30, v232, v6
	v_fma_f32 v7, v31, v232, v7
	v_fma_f32 v4, v24, v236, v4
	v_fma_f32 v5, v25, v236, v5
	v_fma_f32 v6, v26, v236, v6
	v_fma_f32 v7, v27, v236, v7
	s_waitcnt vmcnt(16)
; DI float fexp2(float x) { return __builtin_amdgcn_exp2f(x); }
; DI float dot16(f32x4 a, f32x4 b) { float d = (a[0] * b[0] + a[1] * b[1]) + (a[2] * b[2] + a[3] * b[3]); d += __shfl_xor(d, 1); d += __shfl_xor(d, 2); d += __shfl_xor(d, 4); d += __shfl_xor(d, 8); return d; }
; DI void unit_sample_attn2(int u, const bf16* __restrict__ Q, const float* __restrict__ ckw, const float* __restrict__ cvw, const float* __restrict__ nkw, const float* __restrict__ nvw, const bf16* __restrict__ G, bf16* __restrict__ MIX, ...
;     ...
;     for (int n0 = 0; n0 < 96; n0 += 32) {
;         f32x4 kv[16], vv[16]; float s[16];
; #pragma unroll
;         for (int i = 0; i < 16; ++i) { const int n = n0 + 2 * i + half, dlt = sub ? 16 * (33 + n) : 512 - 4 * n; const size_t ro = (size_t)(2048 + j1 - dlt) * 512;
;             kv[i] = __builtin_nontemporal_load((const f32x4*)(ck + ro)); }
; #pragma unroll
;         for (int i = 0; i < 16; ++i) { const int n = n0 + 2 * i + half, dlt = sub ? 16 * (33 + n) : 512 - 4 * n; const size_t ro = (size_t)(2048 + j1 - dlt) * 512;
;             vv[i] = __builtin_nontemporal_load((const f32x4*)(cv + ro)); }
; #pragma unroll
;         for (int i = 0; i < 16; ++i) { const int n = n0 + 2 * i + half, dlt = sub ? 16 * (33 + n) : 512 - 4 * n;
;             s[i] = dot16(qs, kv[i]) - slope2 * (float)dlt + ((!sub && (dlt & 15) == 0) ? 1.f : 0.f); }
;         float mn = mB;
; #pragma unroll
;         for (int i = 0; i < 16; ++i) mn = fmaxf(mn, s[i]);
;         const float alpha = fexp2(mB - mn); float ps = 0.f; f32x4 acc = oB * alpha;
; #pragma unroll
;         for (int i = 0; i < 16; ++i) { const float p = fexp2(s[i] - mn); ps += p; acc += vv[i] * p; }
;         lB = lB * alpha + ps; mB = mn; oB = acc;
	v_fma_f32 v4, v20, v240, v4
	v_fma_f32 v5, v21, v240, v5
	v_fma_f32 v6, v22, v240, v6
	v_fma_f32 v7, v23, v240, v7
	v_fma_f32 v4, v16, v176, v4
	v_fma_f32 v5, v17, v176, v5
	v_fma_f32 v6, v18, v176, v6
	v_fma_f32 v7, v19, v176, v7
	v_fma_f32 v4, v12, v184, v4
	v_fma_f32 v5, v13, v184, v5
	v_fma_f32 v6, v14, v184, v6
	v_fma_f32 v7, v15, v184, v7
	v_fma_f32 v4, v8, v180, v4
	v_fma_f32 v5, v9, v180, v5
	v_fma_f32 v6, v10, v180, v6
	v_fma_f32 v7, v11, v180, v7
	v_fma_f32 v174, v174, v189, v190
	v_add_u32_e32 v225, 0x80000, v224
	global_load_dwordx4 v[68:71], v225, s[2:3] nt
	v_add_u32_e32 v225, 0x4000, v225
	global_load_dwordx4 v[64:67], v225, s[2:3] nt
	v_add_u32_e32 v225, 0x4000, v225
	global_load_dwordx4 v[60:63], v225, s[2:3] nt
	v_add_u32_e32 v225, 0x4000, v225
	global_load_dwordx4 v[56:59], v225, s[2:3] nt
	v_add_u32_e32 v225, 0x4000, v225
	global_load_dwordx4 v[52:55], v225, s[2:3] nt
	v_add_u32_e32 v225, 0x4000, v225
	global_load_dwordx4 v[48:51], v225, s[2:3] nt
	v_add_u32_e32 v225, 0x4000, v225
	global_load_dwordx4 v[44:47], v225, s[2:3] nt
	v_add_u32_e32 v225, 0x4000, v225
	global_load_dwordx4 v[40:43], v225, s[2:3] nt
	v_add_u32_e32 v225, 0x4000, v225
	global_load_dwordx4 v[36:39], v225, s[2:3] nt
	v_add_u32_e32 v225, 0x4000, v225
	global_load_dwordx4 v[32:35], v225, s[2:3] nt
	v_add_u32_e32 v225, 0x4000, v225
	global_load_dwordx4 v[28:31], v225, s[2:3] nt
	v_add_u32_e32 v225, 0x4000, v225
	global_load_dwordx4 v[24:27], v225, s[2:3] nt
	v_add_u32_e32 v225, 0x4000, v225
	global_load_dwordx4 v[20:23], v225, s[2:3] nt
	v_add_u32_e32 v225, 0x4000, v225
	global_load_dwordx4 v[16:19], v225, s[2:3] nt
	v_add_u32_e32 v225, 0x4000, v225
	global_load_dwordx4 v[12:15], v225, s[2:3] nt
	v_add_u32_e32 v225, 0x4000, v225
	global_load_dwordx4 v[8:11], v225, s[2:3] nt
	v_add_u32_e32 v227, 0xffffff78, v163
	s_waitcnt vmcnt(28)
	v_pk_mul_f32 v[132:133], v[132:133], v[158:159]
	v_pk_mul_f32 v[134:135], v[134:135], v[160:161]
	v_pk_mul_f32 v[128:129], v[128:129], v[158:159]
	v_pk_mul_f32 v[130:131], v[130:131], v[160:161]
	v_pk_mul_f32 v[124:125], v[124:125], v[158:159]
	v_pk_mul_f32 v[126:127], v[126:127], v[160:161]
	v_pk_mul_f32 v[120:121], v[120:121], v[158:159]
	v_pk_mul_f32 v[122:123], v[122:123], v[160:161]
	v_add_f32_e32 v132, v133, v132
	v_add_f32_e32 v134, v134, v135
	v_add_f32_e32 v128, v129, v128
	v_add_f32_e32 v130, v130, v131
	v_add_f32_e32 v124, v125, v124
	v_add_f32_e32 v126, v126, v127
	v_add_f32_e32 v120, v121, v120
	v_add_f32_e32 v122, v122, v123
	v_add_f32_e32 v132, v132, v134
	v_add_f32_e32 v128, v128, v130
	v_add_f32_e32 v124, v124, v126
	v_add_f32_e32 v120, v120, v122
	v_add_f32_dpp v132, v132, v132 quad_perm:[1,0,3,2] row_mask:0xf bank_mask:0xf
	v_add_f32_dpp v128, v128, v128 quad_perm:[1,0,3,2] row_mask:0xf bank_mask:0xf
	v_add_f32_dpp v124, v124, v124 quad_perm:[1,0,3,2] row_mask:0xf bank_mask:0xf
	v_add_f32_dpp v120, v120, v120 quad_perm:[1,0,3,2] row_mask:0xf bank_mask:0xf
	v_add_f32_dpp v132, v132, v132 quad_perm:[2,3,0,1] row_mask:0xf bank_mask:0xf
	v_add_f32_dpp v128, v128, v128 quad_perm:[2,3,0,1] row_mask:0xf bank_mask:0xf
	v_add_f32_dpp v124, v124, v124 quad_perm:[2,3,0,1] row_mask:0xf bank_mask:0xf
	v_add_f32_dpp v120, v120, v120 quad_perm:[2,3,0,1] row_mask:0xf bank_mask:0xf
	v_add_f32_dpp v132, v132, v132 row_half_mirror row_mask:0xf bank_mask:0xf
	v_add_f32_dpp v128, v128, v128 row_half_mirror row_mask:0xf bank_mask:0xf
	v_add_f32_dpp v124, v124, v124 row_half_mirror row_mask:0xf bank_mask:0xf
	v_add_f32_dpp v120, v120, v120 row_half_mirror row_mask:0xf bank_mask:0xf
	v_add_f32_dpp v132, v132, v132 row_mirror row_mask:0xf bank_mask:0xf
	v_add_f32_dpp v128, v128, v128 row_mirror row_mask:0xf bank_mask:0xf
	v_add_f32_dpp v124, v124, v124 row_mirror row_mask:0xf bank_mask:0xf
	v_add_f32_dpp v120, v120, v120 row_mirror row_mask:0xf bank_mask:0xf
	v_cvt_f32_i32_e32 v173, v227
	v_add_u32_e32 v227, 0xfffffff8, v227
	v_fma_f32 v132, -v136, v173, v132
	v_add_f32_e32 v132, v172, v132
	v_cvt_f32_i32_e32 v171, v227
	v_add_u32_e32 v227, 0xfffffff8, v227
	v_fma_f32 v128, -v136, v171, v128
	v_cvt_f32_i32_e32 v173, v227
	v_add_u32_e32 v227, 0xfffffff8, v227
	v_fma_f32 v124, -v136, v173, v124
	v_add_f32_e32 v124, v172, v124
	v_cvt_f32_i32_e32 v171, v227
	v_add_u32_e32 v227, 0xfffffff8, v227
	v_fma_f32 v120, -v136, v171, v120
	s_waitcnt vmcnt(24)
	v_pk_mul_f32 v[116:117], v[116:117], v[158:159]
	v_pk_mul_f32 v[118:119], v[118:119], v[160:161]
	v_pk_mul_f32 v[112:113], v[112:113], v[158:159]
	v_pk_mul_f32 v[114:115], v[114:115], v[160:161]
	v_pk_mul_f32 v[108:109], v[108:109], v[158:159]
	v_pk_mul_f32 v[110:111], v[110:111], v[160:161]
	v_pk_mul_f32 v[104:105], v[104:105], v[158:159]
	v_pk_mul_f32 v[106:107], v[106:107], v[160:161]
	v_add_f32_e32 v116, v117, v116
	v_add_f32_e32 v118, v118, v119
	v_add_f32_e32 v112, v113, v112
	v_add_f32_e32 v114, v114, v115
	v_add_f32_e32 v108, v109, v108
	v_add_f32_e32 v110, v110, v111
	v_add_f32_e32 v104, v105, v104
	v_add_f32_e32 v106, v106, v107
	v_add_f32_e32 v116, v116, v118
	v_add_f32_e32 v112, v112, v114
	v_add_f32_e32 v108, v108, v110
	v_add_f32_e32 v104, v104, v106
	v_add_f32_dpp v116, v116, v116 quad_perm:[1,0,3,2] row_mask:0xf bank_mask:0xf
	v_add_f32_dpp v112, v112, v112 quad_perm:[1,0,3,2] row_mask:0xf bank_mask:0xf
	v_add_f32_dpp v108, v108, v108 quad_perm:[1,0,3,2] row_mask:0xf bank_mask:0xf
	v_add_f32_dpp v104, v104, v104 quad_perm:[1,0,3,2] row_mask:0xf bank_mask:0xf
	v_add_f32_dpp v116, v116, v116 quad_perm:[2,3,0,1] row_mask:0xf bank_mask:0xf
	v_add_f32_dpp v112, v112, v112 quad_perm:[2,3,0,1] row_mask:0xf bank_mask:0xf
	v_add_f32_dpp v108, v108, v108 quad_perm:[2,3,0,1] row_mask:0xf bank_mask:0xf
	v_add_f32_dpp v104, v104, v104 quad_perm:[2,3,0,1] row_mask:0xf bank_mask:0xf
	v_add_f32_dpp v116, v116, v116 row_half_mirror row_mask:0xf bank_mask:0xf
	v_add_f32_dpp v112, v112, v112 row_half_mirror row_mask:0xf bank_mask:0xf
	v_add_f32_dpp v108, v108, v108 row_half_mirror row_mask:0xf bank_mask:0xf
	v_add_f32_dpp v104, v104, v104 row_half_mirror row_mask:0xf bank_mask:0xf
	v_add_f32_dpp v116, v116, v116 row_mirror row_mask:0xf bank_mask:0xf
	v_add_f32_dpp v112, v112, v112 row_mirror row_mask:0xf bank_mask:0xf
	v_add_f32_dpp v108, v108, v108 row_mirror row_mask:0xf bank_mask:0xf
	v_add_f32_dpp v104, v104, v104 row_mirror row_mask:0xf bank_mask:0xf
	v_cvt_f32_i32_e32 v173, v227
	v_add_u32_e32 v227, 0xfffffff8, v227
	v_fma_f32 v116, -v136, v173, v116
	v_add_f32_e32 v116, v172, v116
	v_cvt_f32_i32_e32 v171, v227
	v_add_u32_e32 v227, 0xfffffff8, v227
	v_fma_f32 v112, -v136, v171, v112
	v_cvt_f32_i32_e32 v173, v227
	v_add_u32_e32 v227, 0xfffffff8, v227
	v_fma_f32 v108, -v136, v173, v108
	v_add_f32_e32 v108, v172, v108
	v_cvt_f32_i32_e32 v171, v227
	v_add_u32_e32 v227, 0xfffffff8, v227
	v_fma_f32 v104, -v136, v171, v104
	s_waitcnt vmcnt(20)
; DI float fexp2(float x) { return __builtin_amdgcn_exp2f(x); }
; DI float dot16(f32x4 a, f32x4 b) { float d = (a[0] * b[0] + a[1] * b[1]) + (a[2] * b[2] + a[3] * b[3]); d += __shfl_xor(d, 1); d += __shfl_xor(d, 2); d += __shfl_xor(d, 4); d += __shfl_xor(d, 8); return d; }
; DI void unit_sample_attn2(int u, const bf16* __restrict__ Q, const float* __restrict__ ckw, const float* __restrict__ cvw, const float* __restrict__ nkw, const float* __restrict__ nvw, const bf16* __restrict__ G, bf16* __restrict__ MIX, ...
;     ...
;         for (int i = 0; i < 16; ++i) { const int n = n0 + 2 * i + half, dlt = sub ? 16 * (33 + n) : 512 - 4 * n;
;             s[i] = dot16(qs, kv[i]) - slope2 * (float)dlt + ((!sub && (dlt & 15) == 0) ? 1.f : 0.f); }
;         float mn = mB;
; #pragma unroll
;         for (int i = 0; i < 16; ++i) mn = fmaxf(mn, s[i]);
;         const float alpha = fexp2(mB - mn); float ps = 0.f; f32x4 acc = oB * alpha;
; #pragma unroll
;         for (int i = 0; i < 16; ++i) { const float p = fexp2(s[i] - mn); ps += p; acc += vv[i] * p; }
;         lB = lB * alpha + ps; mB = mn; oB = acc;
	v_pk_mul_f32 v[100:101], v[100:101], v[158:159]
	v_pk_mul_f32 v[102:103], v[102:103], v[160:161]
	v_pk_mul_f32 v[96:97], v[96:97], v[158:159]
	v_pk_mul_f32 v[98:99], v[98:99], v[160:161]
	v_pk_mul_f32 v[92:93], v[92:93], v[158:159]
	v_pk_mul_f32 v[94:95], v[94:95], v[160:161]
	v_pk_mul_f32 v[88:89], v[88:89], v[158:159]
	v_pk_mul_f32 v[90:91], v[90:91], v[160:161]
	v_add_f32_e32 v100, v101, v100
	v_add_f32_e32 v102, v102, v103
	v_add_f32_e32 v96, v97, v96
	v_add_f32_e32 v98, v98, v99
	v_add_f32_e32 v92, v93, v92
	v_add_f32_e32 v94, v94, v95
	v_add_f32_e32 v88, v89, v88
	v_add_f32_e32 v90, v90, v91
	v_add_f32_e32 v100, v100, v102
	v_add_f32_e32 v96, v96, v98
	v_add_f32_e32 v92, v92, v94
	v_add_f32_e32 v88, v88, v90
	v_add_f32_dpp v100, v100, v100 quad_perm:[1,0,3,2] row_mask:0xf bank_mask:0xf
	v_add_f32_dpp v96, v96, v96 quad_perm:[1,0,3,2] row_mask:0xf bank_mask:0xf
	v_add_f32_dpp v92, v92, v92 quad_perm:[1,0,3,2] row_mask:0xf bank_mask:0xf
	v_add_f32_dpp v88, v88, v88 quad_perm:[1,0,3,2] row_mask:0xf bank_mask:0xf
	v_add_f32_dpp v100, v100, v100 quad_perm:[2,3,0,1] row_mask:0xf bank_mask:0xf
	v_add_f32_dpp v96, v96, v96 quad_perm:[2,3,0,1] row_mask:0xf bank_mask:0xf
	v_add_f32_dpp v92, v92, v92 quad_perm:[2,3,0,1] row_mask:0xf bank_mask:0xf
	v_add_f32_dpp v88, v88, v88 quad_perm:[2,3,0,1] row_mask:0xf bank_mask:0xf
	v_add_f32_dpp v100, v100, v100 row_half_mirror row_mask:0xf bank_mask:0xf
	v_add_f32_dpp v96, v96, v96 row_half_mirror row_mask:0xf bank_mask:0xf
	v_add_f32_dpp v92, v92, v92 row_half_mirror row_mask:0xf bank_mask:0xf
	v_add_f32_dpp v88, v88, v88 row_half_mirror row_mask:0xf bank_mask:0xf
	v_add_f32_dpp v100, v100, v100 row_mirror row_mask:0xf bank_mask:0xf
	v_add_f32_dpp v96, v96, v96 row_mirror row_mask:0xf bank_mask:0xf
	v_add_f32_dpp v92, v92, v92 row_mirror row_mask:0xf bank_mask:0xf
	v_add_f32_dpp v88, v88, v88 row_mirror row_mask:0xf bank_mask:0xf
	v_cvt_f32_i32_e32 v173, v227
	v_add_u32_e32 v227, 0xfffffff8, v227
	v_fma_f32 v100, -v136, v173, v100
	v_add_f32_e32 v100, v172, v100
	v_cvt_f32_i32_e32 v171, v227
	v_add_u32_e32 v227, 0xfffffff8, v227
	v_fma_f32 v96, -v136, v171, v96
	v_cvt_f32_i32_e32 v173, v227
	v_add_u32_e32 v227, 0xfffffff8, v227
	v_fma_f32 v92, -v136, v173, v92
	v_add_f32_e32 v92, v172, v92
	v_cvt_f32_i32_e32 v171, v227
	v_add_u32_e32 v227, 0xfffffff8, v227
	v_fma_f32 v88, -v136, v171, v88
	s_waitcnt vmcnt(16)
	v_pk_mul_f32 v[84:85], v[84:85], v[158:159]
	v_pk_mul_f32 v[86:87], v[86:87], v[160:161]
	v_pk_mul_f32 v[80:81], v[80:81], v[158:159]
	v_pk_mul_f32 v[82:83], v[82:83], v[160:161]
	v_pk_mul_f32 v[76:77], v[76:77], v[158:159]
	v_pk_mul_f32 v[78:79], v[78:79], v[160:161]
	v_pk_mul_f32 v[72:73], v[72:73], v[158:159]
	v_pk_mul_f32 v[74:75], v[74:75], v[160:161]
	v_add_f32_e32 v84, v85, v84
	v_add_f32_e32 v86, v86, v87
	v_add_f32_e32 v80, v81, v80
	v_add_f32_e32 v82, v82, v83
	v_add_f32_e32 v76, v77, v76
	v_add_f32_e32 v78, v78, v79
	v_add_f32_e32 v72, v73, v72
	v_add_f32_e32 v74, v74, v75
	v_add_f32_e32 v84, v84, v86
	v_add_f32_e32 v80, v80, v82
	v_add_f32_e32 v76, v76, v78
	v_add_f32_e32 v72, v72, v74
	v_add_f32_dpp v84, v84, v84 quad_perm:[1,0,3,2] row_mask:0xf bank_mask:0xf
	v_add_f32_dpp v80, v80, v80 quad_perm:[1,0,3,2] row_mask:0xf bank_mask:0xf
	v_add_f32_dpp v76, v76, v76 quad_perm:[1,0,3,2] row_mask:0xf bank_mask:0xf
	v_add_f32_dpp v72, v72, v72 quad_perm:[1,0,3,2] row_mask:0xf bank_mask:0xf
	v_add_f32_dpp v84, v84, v84 quad_perm:[2,3,0,1] row_mask:0xf bank_mask:0xf
	v_add_f32_dpp v80, v80, v80 quad_perm:[2,3,0,1] row_mask:0xf bank_mask:0xf
	v_add_f32_dpp v76, v76, v76 quad_perm:[2,3,0,1] row_mask:0xf bank_mask:0xf
	v_add_f32_dpp v72, v72, v72 quad_perm:[2,3,0,1] row_mask:0xf bank_mask:0xf
	v_add_f32_dpp v84, v84, v84 row_half_mirror row_mask:0xf bank_mask:0xf
	v_add_f32_dpp v80, v80, v80 row_half_mirror row_mask:0xf bank_mask:0xf
	v_add_f32_dpp v76, v76, v76 row_half_mirror row_mask:0xf bank_mask:0xf
	v_add_f32_dpp v72, v72, v72 row_half_mirror row_mask:0xf bank_mask:0xf
	v_add_f32_dpp v84, v84, v84 row_mirror row_mask:0xf bank_mask:0xf
	v_add_f32_dpp v80, v80, v80 row_mirror row_mask:0xf bank_mask:0xf
	v_add_f32_dpp v76, v76, v76 row_mirror row_mask:0xf bank_mask:0xf
	v_add_f32_dpp v72, v72, v72 row_mirror row_mask:0xf bank_mask:0xf
	v_cvt_f32_i32_e32 v173, v227
	v_add_u32_e32 v227, 0xfffffff8, v227
	v_fma_f32 v84, -v136, v173, v84
	v_add_f32_e32 v84, v172, v84
	v_cvt_f32_i32_e32 v171, v227
	v_add_u32_e32 v227, 0xfffffff8, v227
	v_fma_f32 v80, -v136, v171, v80
	v_cvt_f32_i32_e32 v173, v227
	v_add_u32_e32 v227, 0xfffffff8, v227
	v_fma_f32 v76, -v136, v173, v76
	v_add_f32_e32 v76, v172, v76
	v_cvt_f32_i32_e32 v171, v227
	v_add_u32_e32 v227, 0xfffffff8, v227
	v_fma_f32 v72, -v136, v171, v72
	v_max3_f32 v135, v175, v132, v128
	v_max3_f32 v135, v135, v124, v120
	v_max3_f32 v135, v135, v116, v112
	v_max3_f32 v135, v135, v108, v104
	v_max3_f32 v135, v135, v100, v96
	v_max3_f32 v135, v135, v92, v88
	v_max3_f32 v135, v135, v84, v80
	v_max3_f32 v135, v135, v76, v72
	v_sub_f32_e32 v133, v175, v135
	v_sub_f32_e32 v132, v132, v135
	v_sub_f32_e32 v128, v128, v135
	v_sub_f32_e32 v124, v124, v135
	v_sub_f32_e32 v120, v120, v135
	v_sub_f32_e32 v116, v116, v135
	v_sub_f32_e32 v112, v112, v135
	v_sub_f32_e32 v108, v108, v135
	v_sub_f32_e32 v104, v104, v135
	v_sub_f32_e32 v100, v100, v135
	v_sub_f32_e32 v96, v96, v135
	v_sub_f32_e32 v92, v92, v135
	v_sub_f32_e32 v88, v88, v135
	v_sub_f32_e32 v84, v84, v135
	v_sub_f32_e32 v80, v80, v135
	v_sub_f32_e32 v76, v76, v135
	v_sub_f32_e32 v72, v72, v135
	v_exp_f32_e32 v133, v133
	v_exp_f32_e32 v132, v132
	v_exp_f32_e32 v128, v128
	v_exp_f32_e32 v124, v124
	v_exp_f32_e32 v120, v120
	v_exp_f32_e32 v116, v116
	v_exp_f32_e32 v112, v112
	v_exp_f32_e32 v108, v108
	v_exp_f32_e32 v104, v104
	v_exp_f32_e32 v100, v100
	v_exp_f32_e32 v96, v96
	v_exp_f32_e32 v92, v92
	v_exp_f32_e32 v88, v88
	v_exp_f32_e32 v84, v84
	v_exp_f32_e32 v80, v80
	v_exp_f32_e32 v76, v76
	v_exp_f32_e32 v72, v72
	v_mov_b32_e32 v175, v135
	v_add_f32_e32 v134, 0, v132
	v_add_f32_e32 v134, v128, v134
	v_add_f32_e32 v134, v124, v134
	v_add_f32_e32 v134, v120, v134
	v_add_f32_e32 v134, v116, v134
	v_add_f32_e32 v134, v112, v134
	v_add_f32_e32 v134, v108, v134
	v_add_f32_e32 v134, v104, v134
	v_add_f32_e32 v134, v100, v134
	v_add_f32_e32 v134, v96, v134
	v_add_f32_e32 v134, v92, v134
	v_add_f32_e32 v134, v88, v134
	v_add_f32_e32 v134, v84, v134
	v_add_f32_e32 v134, v80, v134
	v_add_f32_e32 v134, v76, v134
	v_add_f32_e32 v134, v72, v134
	s_waitcnt vmcnt(12)
; DI float fexp2(float x) { return __builtin_amdgcn_exp2f(x); }
; DI float dot16(f32x4 a, f32x4 b) { float d = (a[0] * b[0] + a[1] * b[1]) + (a[2] * b[2] + a[3] * b[3]); d += __shfl_xor(d, 1); d += __shfl_xor(d, 2); d += __shfl_xor(d, 4); d += __shfl_xor(d, 8); return d; }
; DI void unit_sample_attn2(int u, const bf16* __restrict__ Q, const float* __restrict__ ckw, const float* __restrict__ cvw, const float* __restrict__ nkw, const float* __restrict__ nvw, const bf16* __restrict__ G, bf16* __restrict__ MIX, ...
;     ...
;     for (int n0 = 0; n0 < 96; n0 += 32) {
;         f32x4 kv[16], vv[16]; float s[16];
; #pragma unroll
;         for (int i = 0; i < 16; ++i) { const int n = n0 + 2 * i + half, dlt = sub ? 16 * (33 + n) : 512 - 4 * n; const size_t ro = (size_t)(2048 + j1 - dlt) * 512;
;             kv[i] = __builtin_nontemporal_load((const f32x4*)(ck + ro)); }
; #pragma unroll
;         for (int i = 0; i < 16; ++i) { const int n = n0 + 2 * i + half, dlt = sub ? 16 * (33 + n) : 512 - 4 * n; const size_t ro = (size_t)(2048 + j1 - dlt) * 512;
;             vv[i] = __builtin_nontemporal_load((const f32x4*)(cv + ro)); }
; #pragma unroll
;         for (int i = 0; i < 16; ++i) { const int n = n0 + 2 * i + half, dlt = sub ? 16 * (33 + n) : 512 - 4 * n;
;             s[i] = dot16(qs, kv[i]) - slope2 * (float)dlt + ((!sub && (dlt & 15) == 0) ? 1.f : 0.f); }
;         float mn = mB;
; #pragma unroll
;         for (int i = 0; i < 16; ++i) mn = fmaxf(mn, s[i]);
;         const float alpha = fexp2(mB - mn); float ps = 0.f; f32x4 acc = oB * alpha;
; #pragma unroll
;         for (int i = 0; i < 16; ++i) { const float p = fexp2(s[i] - mn); ps += p; acc += vv[i] * p; }
;         lB = lB * alpha + ps; mB = mn; oB = acc;
	v_mul_f32_e32 v68, v68, v132
	v_mul_f32_e32 v69, v69, v132
	v_mul_f32_e32 v70, v70, v132
	v_mul_f32_e32 v71, v71, v132
	v_fma_f32 v4, v4, v133, v68
	v_fma_f32 v5, v5, v133, v69
	v_fma_f32 v6, v6, v133, v70
	v_fma_f32 v7, v7, v133, v71
	v_fma_f32 v4, v64, v128, v4
	v_fma_f32 v5, v65, v128, v5
	v_fma_f32 v6, v66, v128, v6
	v_fma_f32 v7, v67, v128, v7
	v_fma_f32 v4, v60, v124, v4
	v_fma_f32 v5, v61, v124, v5
	v_fma_f32 v6, v62, v124, v6
	v_fma_f32 v7, v63, v124, v7
	v_fma_f32 v4, v56, v120, v4
	v_fma_f32 v5, v57, v120, v5
	v_fma_f32 v6, v58, v120, v6
	v_fma_f32 v7, v59, v120, v7
	s_waitcnt vmcnt(8)
	v_fma_f32 v4, v52, v116, v4
	v_fma_f32 v5, v53, v116, v5
	v_fma_f32 v6, v54, v116, v6
	v_fma_f32 v7, v55, v116, v7
	v_fma_f32 v4, v48, v112, v4
	v_fma_f32 v5, v49, v112, v5
	v_fma_f32 v6, v50, v112, v6
	v_fma_f32 v7, v51, v112, v7
	v_fma_f32 v4, v44, v108, v4
	v_fma_f32 v5, v45, v108, v5
	v_fma_f32 v6, v46, v108, v6
	v_fma_f32 v7, v47, v108, v7
	v_fma_f32 v4, v40, v104, v4
	v_fma_f32 v5, v41, v104, v5
	v_fma_f32 v6, v42, v104, v6
	v_fma_f32 v7, v43, v104, v7
	s_waitcnt vmcnt(4)
	v_fma_f32 v4, v36, v100, v4
	v_fma_f32 v5, v37, v100, v5
	v_fma_f32 v6, v38, v100, v6
	v_fma_f32 v7, v39, v100, v7
	v_fma_f32 v4, v32, v96, v4
	v_fma_f32 v5, v33, v96, v5
	v_fma_f32 v6, v34, v96, v6
	v_fma_f32 v7, v35, v96, v7
	v_fma_f32 v4, v28, v92, v4
	v_fma_f32 v5, v29, v92, v5
	v_fma_f32 v6, v30, v92, v6
	v_fma_f32 v7, v31, v92, v7
	v_fma_f32 v4, v24, v88, v4
	v_fma_f32 v5, v25, v88, v5
	v_fma_f32 v6, v26, v88, v6
	v_fma_f32 v7, v27, v88, v7
	s_waitcnt vmcnt(0)
	v_fma_f32 v4, v20, v84, v4
	v_fma_f32 v5, v21, v84, v5
	v_fma_f32 v6, v22, v84, v6
	v_fma_f32 v7, v23, v84, v7
	v_fma_f32 v4, v16, v80, v4
	v_fma_f32 v5, v17, v80, v5
	v_fma_f32 v6, v18, v80, v6
	v_fma_f32 v7, v19, v80, v7
	v_fma_f32 v4, v12, v76, v4
	v_fma_f32 v5, v13, v76, v5
	v_fma_f32 v6, v14, v76, v6
	v_fma_f32 v7, v15, v76, v7
	v_fma_f32 v4, v8, v72, v4
	v_fma_f32 v5, v9, v72, v5
	v_fma_f32 v6, v10, v72, v6
	v_fma_f32 v7, v11, v72, v7
	v_fma_f32 v174, v174, v133, v134
	v_mov_b32_e32 v85, v175
	v_mov_b32_e32 v87, v174
	s_branch .Ls1_done
.Ls1_s:
	v_add_u32_e32 v224, 0x1e0, v173
	v_add_u32_e32 v224, s94, v224
	v_lshl_add_u32 v224, v224, 11, v162
	v_mov_b32_e32 v175, v85
	v_mov_b32_e32 v174, v87
	v_mov_b32_e32 v225, v224
	global_load_dwordx4 v[132:135], v225, s[0:1] nt
	v_add_u32_e32 v225, 0xffff0000, v225
	global_load_dwordx4 v[128:131], v225, s[0:1] nt
	v_add_u32_e32 v225, 0xffff0000, v225
	global_load_dwordx4 v[124:127], v225, s[0:1] nt
	v_add_u32_e32 v225, 0xffff0000, v225
	global_load_dwordx4 v[120:123], v225, s[0:1] nt
	v_add_u32_e32 v225, 0xffff0000, v225
	global_load_dwordx4 v[116:119], v225, s[0:1] nt
	v_add_u32_e32 v225, 0xffff0000, v225
	global_load_dwordx4 v[112:115], v225, s[0:1] nt
	v_add_u32_e32 v225, 0xffff0000, v225
	global_load_dwordx4 v[108:111], v225, s[0:1] nt
	v_add_u32_e32 v225, 0xffff0000, v225
	global_load_dwordx4 v[104:107], v225, s[0:1] nt
	v_add_u32_e32 v225, 0xffff0000, v225
	global_load_dwordx4 v[100:103], v225, s[0:1] nt
	v_add_u32_e32 v225, 0xffff0000, v225
	global_load_dwordx4 v[96:99], v225, s[0:1] nt
	v_add_u32_e32 v225, 0xffff0000, v225
	global_load_dwordx4 v[92:95], v225, s[0:1] nt
	v_add_u32_e32 v225, 0xffff0000, v225
	global_load_dwordx4 v[88:91], v225, s[0:1] nt
	v_add_u32_e32 v225, 0xffff0000, v225
	global_load_dwordx4 v[84:87], v225, s[0:1] nt
	v_add_u32_e32 v225, 0xffff0000, v225
	global_load_dwordx4 v[80:83], v225, s[0:1] nt
	v_add_u32_e32 v225, 0xffff0000, v225
	global_load_dwordx4 v[76:79], v225, s[0:1] nt
	v_add_u32_e32 v225, 0xffff0000, v225
	global_load_dwordx4 v[72:75], v225, s[0:1] nt
	v_mov_b32_e32 v225, v224
	global_load_dwordx4 v[68:71], v225, s[2:3] nt
	v_add_u32_e32 v225, 0xffff0000, v225
	global_load_dwordx4 v[64:67], v225, s[2:3] nt
	v_add_u32_e32 v225, 0xffff0000, v225
	global_load_dwordx4 v[60:63], v225, s[2:3] nt
	v_add_u32_e32 v225, 0xffff0000, v225
	global_load_dwordx4 v[56:59], v225, s[2:3] nt
	v_add_u32_e32 v225, 0xffff0000, v225
	global_load_dwordx4 v[52:55], v225, s[2:3] nt
	v_add_u32_e32 v225, 0xffff0000, v225
	global_load_dwordx4 v[48:51], v225, s[2:3] nt
	v_add_u32_e32 v225, 0xffff0000, v225
	global_load_dwordx4 v[44:47], v225, s[2:3] nt
	v_add_u32_e32 v225, 0xffff0000, v225
	global_load_dwordx4 v[40:43], v225, s[2:3] nt
	v_add_u32_e32 v225, 0xffff0000, v225
	global_load_dwordx4 v[36:39], v225, s[2:3] nt
	v_add_u32_e32 v225, 0xffff0000, v225
	global_load_dwordx4 v[32:35], v225, s[2:3] nt
	v_add_u32_e32 v225, 0xffff0000, v225
	global_load_dwordx4 v[28:31], v225, s[2:3] nt
	v_add_u32_e32 v225, 0xffff0000, v225
	global_load_dwordx4 v[24:27], v225, s[2:3] nt
	v_add_u32_e32 v225, 0xffff0000, v225
	global_load_dwordx4 v[20:23], v225, s[2:3] nt
	v_add_u32_e32 v225, 0xffff0000, v225
	global_load_dwordx4 v[16:19], v225, s[2:3] nt
	v_add_u32_e32 v225, 0xffff0000, v225
	global_load_dwordx4 v[12:15], v225, s[2:3] nt
	v_add_u32_e32 v225, 0xffff0000, v225
	global_load_dwordx4 v[8:11], v225, s[2:3] nt
	v_add_u32_e32 v225, 0xfff00000, v224
	global_load_dwordx4 v[188:191], v225, s[0:1] nt
	v_add_u32_e32 v225, 0xffff0000, v225
	global_load_dwordx4 v[192:195], v225, s[0:1] nt
	v_add_u32_e32 v225, 0xffff0000, v225
	global_load_dwordx4 v[196:199], v225, s[0:1] nt
	v_add_u32_e32 v225, 0xffff0000, v225
	global_load_dwordx4 v[200:203], v225, s[0:1] nt
	v_add_u32_e32 v225, 0xffff0000, v225
	global_load_dwordx4 v[204:207], v225, s[0:1] nt
	v_add_u32_e32 v225, 0xffff0000, v225
	global_load_dwordx4 v[208:211], v225, s[0:1] nt
	v_add_u32_e32 v225, 0xffff0000, v225
	global_load_dwordx4 v[212:215], v225, s[0:1] nt
	v_add_u32_e32 v225, 0xffff0000, v225
	global_load_dwordx4 v[216:219], v225, s[0:1] nt
	v_add_u32_e32 v225, 0xffff0000, v225
	global_load_dwordx4 v[220:223], v225, s[0:1] nt
	v_add_u32_e32 v225, 0xffff0000, v225
	global_load_dwordx4 v[228:231], v225, s[0:1] nt
	v_add_u32_e32 v225, 0xffff0000, v225
	global_load_dwordx4 v[232:235], v225, s[0:1] nt
	v_add_u32_e32 v225, 0xffff0000, v225
	global_load_dwordx4 v[236:239], v225, s[0:1] nt
	v_add_u32_e32 v225, 0xffff0000, v225
	global_load_dwordx4 v[240:243], v225, s[0:1] nt
	v_add_u32_e32 v225, 0xffff0000, v225
	global_load_dwordx4 v[176:179], v225, s[0:1] nt
	v_add_u32_e32 v225, 0xffff0000, v225
	global_load_dwordx4 v[184:187], v225, s[0:1] nt
	v_add_u32_e32 v225, 0xffff0000, v225
	global_load_dwordx2 v[180:181], v225, s[0:1] nt
	global_load_dwordx2 v[244:245], v225, s[0:1] offset:8 nt
	v_add_u32_e32 v227, 0xfffffe20, v172
	s_waitcnt vmcnt(45)
; DI float dot16(f32x4 a, f32x4 b) { float d = (a[0] * b[0] + a[1] * b[1]) + (a[2] * b[2] + a[3] * b[3]); d += __shfl_xor(d, 1); d += __shfl_xor(d, 2); d += __shfl_xor(d, 4); d += __shfl_xor(d, 8); return d; }
; DI void unit_sample_attn2(int u, const bf16* __restrict__ Q, const float* __restrict__ ckw, const float* __restrict__ cvw, const float* __restrict__ nkw, const float* __restrict__ nvw, const bf16* __restrict__ G, bf16* __restrict__ MIX, ...
;     ...
;         for (int i = 0; i < 16; ++i) { const int n = n0 + 2 * i + half, dlt = sub ? 16 * (33 + n) : 512 - 4 * n;
;             s[i] = dot16(qs, kv[i]) - slope2 * (float)dlt + ((!sub && (dlt & 15) == 0) ? 1.f : 0.f); }
	v_pk_mul_f32 v[132:133], v[132:133], v[158:159]
	v_pk_mul_f32 v[134:135], v[134:135], v[160:161]
	v_pk_mul_f32 v[128:129], v[128:129], v[158:159]
	v_pk_mul_f32 v[130:131], v[130:131], v[160:161]
	v_pk_mul_f32 v[124:125], v[124:125], v[158:159]
	v_pk_mul_f32 v[126:127], v[126:127], v[160:161]
	v_pk_mul_f32 v[120:121], v[120:121], v[158:159]
	v_pk_mul_f32 v[122:123], v[122:123], v[160:161]
	v_add_f32_e32 v132, v133, v132
	v_add_f32_e32 v134, v134, v135
	v_add_f32_e32 v128, v129, v128
	v_add_f32_e32 v130, v130, v131
	v_add_f32_e32 v124, v125, v124
	v_add_f32_e32 v126, v126, v127
	v_add_f32_e32 v120, v121, v120
	v_add_f32_e32 v122, v122, v123
	v_add_f32_e32 v132, v132, v134
	v_add_f32_e32 v128, v128, v130
	v_add_f32_e32 v124, v124, v126
	v_add_f32_e32 v120, v120, v122
	v_add_f32_dpp v132, v132, v132 quad_perm:[1,0,3,2] row_mask:0xf bank_mask:0xf
	v_add_f32_dpp v128, v128, v128 quad_perm:[1,0,3,2] row_mask:0xf bank_mask:0xf
	v_add_f32_dpp v124, v124, v124 quad_perm:[1,0,3,2] row_mask:0xf bank_mask:0xf
	v_add_f32_dpp v120, v120, v120 quad_perm:[1,0,3,2] row_mask:0xf bank_mask:0xf
	v_add_f32_dpp v132, v132, v132 quad_perm:[2,3,0,1] row_mask:0xf bank_mask:0xf
	v_add_f32_dpp v128, v128, v128 quad_perm:[2,3,0,1] row_mask:0xf bank_mask:0xf
	v_add_f32_dpp v124, v124, v124 quad_perm:[2,3,0,1] row_mask:0xf bank_mask:0xf
	v_add_f32_dpp v120, v120, v120 quad_perm:[2,3,0,1] row_mask:0xf bank_mask:0xf
	v_add_f32_dpp v132, v132, v132 row_half_mirror row_mask:0xf bank_mask:0xf
	v_add_f32_dpp v128, v128, v128 row_half_mirror row_mask:0xf bank_mask:0xf
	v_add_f32_dpp v124, v124, v124 row_half_mirror row_mask:0xf bank_mask:0xf
	v_add_f32_dpp v120, v120, v120 row_half_mirror row_mask:0xf bank_mask:0xf
	v_add_f32_dpp v132, v132, v132 row_mirror row_mask:0xf bank_mask:0xf
	v_add_f32_dpp v128, v128, v128 row_mirror row_mask:0xf bank_mask:0xf
	v_add_f32_dpp v124, v124, v124 row_mirror row_mask:0xf bank_mask:0xf
	v_add_f32_dpp v120, v120, v120 row_mirror row_mask:0xf bank_mask:0xf
	v_cvt_f32_i32_e32 v171, v227
	v_add_u32_e32 v227, 32, v227
	v_fma_f32 v132, -v136, v171, v132
	v_cvt_f32_i32_e32 v163, v227
	v_add_u32_e32 v227, 32, v227
	v_fma_f32 v128, -v136, v163, v128
	v_cvt_f32_i32_e32 v171, v227
	v_add_u32_e32 v227, 32, v227
	v_fma_f32 v124, -v136, v171, v124
	v_cvt_f32_i32_e32 v163, v227
	v_add_u32_e32 v227, 32, v227
	v_fma_f32 v120, -v136, v163, v120
	s_waitcnt vmcnt(41)
	v_pk_mul_f32 v[116:117], v[116:117], v[158:159]
	v_pk_mul_f32 v[118:119], v[118:119], v[160:161]
	v_pk_mul_f32 v[112:113], v[112:113], v[158:159]
	v_pk_mul_f32 v[114:115], v[114:115], v[160:161]
	v_pk_mul_f32 v[108:109], v[108:109], v[158:159]
	v_pk_mul_f32 v[110:111], v[110:111], v[160:161]
	v_pk_mul_f32 v[104:105], v[104:105], v[158:159]
	v_pk_mul_f32 v[106:107], v[106:107], v[160:161]
	v_add_f32_e32 v116, v117, v116
	v_add_f32_e32 v118, v118, v119
	v_add_f32_e32 v112, v113, v112
	v_add_f32_e32 v114, v114, v115
	v_add_f32_e32 v108, v109, v108
	v_add_f32_e32 v110, v110, v111
	v_add_f32_e32 v104, v105, v104
	v_add_f32_e32 v106, v106, v107
	v_add_f32_e32 v116, v116, v118
	v_add_f32_e32 v112, v112, v114
	v_add_f32_e32 v108, v108, v110
	v_add_f32_e32 v104, v104, v106
	v_add_f32_dpp v116, v116, v116 quad_perm:[1,0,3,2] row_mask:0xf bank_mask:0xf
	v_add_f32_dpp v112, v112, v112 quad_perm:[1,0,3,2] row_mask:0xf bank_mask:0xf
	v_add_f32_dpp v108, v108, v108 quad_perm:[1,0,3,2] row_mask:0xf bank_mask:0xf
	v_add_f32_dpp v104, v104, v104 quad_perm:[1,0,3,2] row_mask:0xf bank_mask:0xf
	v_add_f32_dpp v116, v116, v116 quad_perm:[2,3,0,1] row_mask:0xf bank_mask:0xf
	v_add_f32_dpp v112, v112, v112 quad_perm:[2,3,0,1] row_mask:0xf bank_mask:0xf
	v_add_f32_dpp v108, v108, v108 quad_perm:[2,3,0,1] row_mask:0xf bank_mask:0xf
	v_add_f32_dpp v104, v104, v104 quad_perm:[2,3,0,1] row_mask:0xf bank_mask:0xf
	v_add_f32_dpp v116, v116, v116 row_half_mirror row_mask:0xf bank_mask:0xf
	v_add_f32_dpp v112, v112, v112 row_half_mirror row_mask:0xf bank_mask:0xf
	v_add_f32_dpp v108, v108, v108 row_half_mirror row_mask:0xf bank_mask:0xf
	v_add_f32_dpp v104, v104, v104 row_half_mirror row_mask:0xf bank_mask:0xf
	v_add_f32_dpp v116, v116, v116 row_mirror row_mask:0xf bank_mask:0xf
	v_add_f32_dpp v112, v112, v112 row_mirror row_mask:0xf bank_mask:0xf
	v_add_f32_dpp v108, v108, v108 row_mirror row_mask:0xf bank_mask:0xf
	v_add_f32_dpp v104, v104, v104 row_mirror row_mask:0xf bank_mask:0xf
	v_cvt_f32_i32_e32 v171, v227
	v_add_u32_e32 v227, 32, v227
	v_fma_f32 v116, -v136, v171, v116
	v_cvt_f32_i32_e32 v163, v227
	v_add_u32_e32 v227, 32, v227
	v_fma_f32 v112, -v136, v163, v112
	v_cvt_f32_i32_e32 v171, v227
	v_add_u32_e32 v227, 32, v227
	v_fma_f32 v108, -v136, v171, v108
	v_cvt_f32_i32_e32 v163, v227
	v_add_u32_e32 v227, 32, v227
	v_fma_f32 v104, -v136, v163, v104
	s_waitcnt vmcnt(37)
; DI float fexp2(float x) { return __builtin_amdgcn_exp2f(x); }
; DI float dot16(f32x4 a, f32x4 b) { float d = (a[0] * b[0] + a[1] * b[1]) + (a[2] * b[2] + a[3] * b[3]); d += __shfl_xor(d, 1); d += __shfl_xor(d, 2); d += __shfl_xor(d, 4); d += __shfl_xor(d, 8); return d; }
; DI void unit_sample_attn2(int u, const bf16* __restrict__ Q, const float* __restrict__ ckw, const float* __restrict__ cvw, const float* __restrict__ nkw, const float* __restrict__ nvw, const bf16* __restrict__ G, bf16* __restrict__ MIX, ...
;     ...
;         for (int i = 0; i < 16; ++i) { const int n = n0 + 2 * i + half, dlt = sub ? 16 * (33 + n) : 512 - 4 * n;
;             s[i] = dot16(qs, kv[i]) - slope2 * (float)dlt + ((!sub && (dlt & 15) == 0) ? 1.f : 0.f); }
;         float mn = mB;
; #pragma unroll
;         for (int i = 0; i < 16; ++i) mn = fmaxf(mn, s[i]);
;         const float alpha = fexp2(mB - mn); float ps = 0.f; f32x4 acc = oB * alpha;
; #pragma unroll
;         for (int i = 0; i < 16; ++i) { const float p = fexp2(s[i] - mn); ps += p; acc += vv[i] * p; }
;         lB = lB * alpha + ps; mB = mn; oB = acc;
	v_pk_mul_f32 v[100:101], v[100:101], v[158:159]
	v_pk_mul_f32 v[102:103], v[102:103], v[160:161]
	v_pk_mul_f32 v[96:97], v[96:97], v[158:159]
	v_pk_mul_f32 v[98:99], v[98:99], v[160:161]
	v_pk_mul_f32 v[92:93], v[92:93], v[158:159]
	v_pk_mul_f32 v[94:95], v[94:95], v[160:161]
	v_pk_mul_f32 v[88:89], v[88:89], v[158:159]
	v_pk_mul_f32 v[90:91], v[90:91], v[160:161]
	v_add_f32_e32 v100, v101, v100
	v_add_f32_e32 v102, v102, v103
	v_add_f32_e32 v96, v97, v96
	v_add_f32_e32 v98, v98, v99
	v_add_f32_e32 v92, v93, v92
	v_add_f32_e32 v94, v94, v95
	v_add_f32_e32 v88, v89, v88
	v_add_f32_e32 v90, v90, v91
	v_add_f32_e32 v100, v100, v102
	v_add_f32_e32 v96, v96, v98
	v_add_f32_e32 v92, v92, v94
	v_add_f32_e32 v88, v88, v90
	v_add_f32_dpp v100, v100, v100 quad_perm:[1,0,3,2] row_mask:0xf bank_mask:0xf
	v_add_f32_dpp v96, v96, v96 quad_perm:[1,0,3,2] row_mask:0xf bank_mask:0xf
	v_add_f32_dpp v92, v92, v92 quad_perm:[1,0,3,2] row_mask:0xf bank_mask:0xf
	v_add_f32_dpp v88, v88, v88 quad_perm:[1,0,3,2] row_mask:0xf bank_mask:0xf
	v_add_f32_dpp v100, v100, v100 quad_perm:[2,3,0,1] row_mask:0xf bank_mask:0xf
	v_add_f32_dpp v96, v96, v96 quad_perm:[2,3,0,1] row_mask:0xf bank_mask:0xf
	v_add_f32_dpp v92, v92, v92 quad_perm:[2,3,0,1] row_mask:0xf bank_mask:0xf
	v_add_f32_dpp v88, v88, v88 quad_perm:[2,3,0,1] row_mask:0xf bank_mask:0xf
	v_add_f32_dpp v100, v100, v100 row_half_mirror row_mask:0xf bank_mask:0xf
	v_add_f32_dpp v96, v96, v96 row_half_mirror row_mask:0xf bank_mask:0xf
	v_add_f32_dpp v92, v92, v92 row_half_mirror row_mask:0xf bank_mask:0xf
	v_add_f32_dpp v88, v88, v88 row_half_mirror row_mask:0xf bank_mask:0xf
	v_add_f32_dpp v100, v100, v100 row_mirror row_mask:0xf bank_mask:0xf
	v_add_f32_dpp v96, v96, v96 row_mirror row_mask:0xf bank_mask:0xf
	v_add_f32_dpp v92, v92, v92 row_mirror row_mask:0xf bank_mask:0xf
	v_add_f32_dpp v88, v88, v88 row_mirror row_mask:0xf bank_mask:0xf
	v_cvt_f32_i32_e32 v171, v227
	v_add_u32_e32 v227, 32, v227
	v_fma_f32 v100, -v136, v171, v100
	v_cvt_f32_i32_e32 v163, v227
	v_add_u32_e32 v227, 32, v227
	v_fma_f32 v96, -v136, v163, v96
	v_cvt_f32_i32_e32 v171, v227
	v_add_u32_e32 v227, 32, v227
	v_fma_f32 v92, -v136, v171, v92
	v_cvt_f32_i32_e32 v163, v227
	v_add_u32_e32 v227, 32, v227
	v_fma_f32 v88, -v136, v163, v88
	s_waitcnt vmcnt(33)
	v_pk_mul_f32 v[84:85], v[84:85], v[158:159]
	v_pk_mul_f32 v[86:87], v[86:87], v[160:161]
	v_pk_mul_f32 v[80:81], v[80:81], v[158:159]
	v_pk_mul_f32 v[82:83], v[82:83], v[160:161]
	v_pk_mul_f32 v[76:77], v[76:77], v[158:159]
	v_pk_mul_f32 v[78:79], v[78:79], v[160:161]
	v_pk_mul_f32 v[72:73], v[72:73], v[158:159]
	v_pk_mul_f32 v[74:75], v[74:75], v[160:161]
	v_add_f32_e32 v84, v85, v84
	v_add_f32_e32 v86, v86, v87
	v_add_f32_e32 v80, v81, v80
	v_add_f32_e32 v82, v82, v83
	v_add_f32_e32 v76, v77, v76
	v_add_f32_e32 v78, v78, v79
	v_add_f32_e32 v72, v73, v72
	v_add_f32_e32 v74, v74, v75
	v_add_f32_e32 v84, v84, v86
	v_add_f32_e32 v80, v80, v82
	v_add_f32_e32 v76, v76, v78
	v_add_f32_e32 v72, v72, v74
	v_add_f32_dpp v84, v84, v84 quad_perm:[1,0,3,2] row_mask:0xf bank_mask:0xf
	v_add_f32_dpp v80, v80, v80 quad_perm:[1,0,3,2] row_mask:0xf bank_mask:0xf
	v_add_f32_dpp v76, v76, v76 quad_perm:[1,0,3,2] row_mask:0xf bank_mask:0xf
	v_add_f32_dpp v72, v72, v72 quad_perm:[1,0,3,2] row_mask:0xf bank_mask:0xf
	v_add_f32_dpp v84, v84, v84 quad_perm:[2,3,0,1] row_mask:0xf bank_mask:0xf
	v_add_f32_dpp v80, v80, v80 quad_perm:[2,3,0,1] row_mask:0xf bank_mask:0xf
	v_add_f32_dpp v76, v76, v76 quad_perm:[2,3,0,1] row_mask:0xf bank_mask:0xf
	v_add_f32_dpp v72, v72, v72 quad_perm:[2,3,0,1] row_mask:0xf bank_mask:0xf
	v_add_f32_dpp v84, v84, v84 row_half_mirror row_mask:0xf bank_mask:0xf
	v_add_f32_dpp v80, v80, v80 row_half_mirror row_mask:0xf bank_mask:0xf
	v_add_f32_dpp v76, v76, v76 row_half_mirror row_mask:0xf bank_mask:0xf
	v_add_f32_dpp v72, v72, v72 row_half_mirror row_mask:0xf bank_mask:0xf
	v_add_f32_dpp v84, v84, v84 row_mirror row_mask:0xf bank_mask:0xf
	v_add_f32_dpp v80, v80, v80 row_mirror row_mask:0xf bank_mask:0xf
	v_add_f32_dpp v76, v76, v76 row_mirror row_mask:0xf bank_mask:0xf
	v_add_f32_dpp v72, v72, v72 row_mirror row_mask:0xf bank_mask:0xf
	v_cvt_f32_i32_e32 v171, v227
	v_add_u32_e32 v227, 32, v227
	v_fma_f32 v84, -v136, v171, v84
	v_cvt_f32_i32_e32 v163, v227
	v_add_u32_e32 v227, 32, v227
	v_fma_f32 v80, -v136, v163, v80
	v_cvt_f32_i32_e32 v171, v227
	v_add_u32_e32 v227, 32, v227
	v_fma_f32 v76, -v136, v171, v76
	v_cvt_f32_i32_e32 v163, v227
	v_add_u32_e32 v227, 32, v227
	v_fma_f32 v72, -v136, v163, v72
	v_max3_f32 v135, v175, v132, v128
	v_max3_f32 v135, v135, v124, v120
	v_max3_f32 v135, v135, v116, v112
	v_max3_f32 v135, v135, v108, v104
	v_max3_f32 v135, v135, v100, v96
	v_max3_f32 v135, v135, v92, v88
	v_max3_f32 v135, v135, v84, v80
	v_max3_f32 v135, v135, v76, v72
	v_sub_f32_e32 v133, v175, v135
	v_sub_f32_e32 v132, v132, v135
	v_sub_f32_e32 v128, v128, v135
	v_sub_f32_e32 v124, v124, v135
	v_sub_f32_e32 v120, v120, v135
	v_sub_f32_e32 v116, v116, v135
	v_sub_f32_e32 v112, v112, v135
	v_sub_f32_e32 v108, v108, v135
	v_sub_f32_e32 v104, v104, v135
	v_sub_f32_e32 v100, v100, v135
	v_sub_f32_e32 v96, v96, v135
	v_sub_f32_e32 v92, v92, v135
	v_sub_f32_e32 v88, v88, v135
	v_sub_f32_e32 v84, v84, v135
	v_sub_f32_e32 v80, v80, v135
	v_sub_f32_e32 v76, v76, v135
	v_sub_f32_e32 v72, v72, v135
	v_exp_f32_e32 v133, v133
	v_exp_f32_e32 v132, v132
	v_exp_f32_e32 v128, v128
	v_exp_f32_e32 v124, v124
	v_exp_f32_e32 v120, v120
	v_exp_f32_e32 v116, v116
	v_exp_f32_e32 v112, v112
	v_exp_f32_e32 v108, v108
	v_exp_f32_e32 v104, v104
	v_exp_f32_e32 v100, v100
	v_exp_f32_e32 v96, v96
	v_exp_f32_e32 v92, v92
	v_exp_f32_e32 v88, v88
	v_exp_f32_e32 v84, v84
	v_exp_f32_e32 v80, v80
	v_exp_f32_e32 v76, v76
	v_exp_f32_e32 v72, v72
	v_mov_b32_e32 v175, v135
	v_add_f32_e32 v134, 0, v132
	v_add_f32_e32 v134, v128, v134
	v_add_f32_e32 v134, v124, v134
	v_add_f32_e32 v134, v120, v134
	v_add_f32_e32 v134, v116, v134
	v_add_f32_e32 v134, v112, v134
	v_add_f32_e32 v134, v108, v134
	v_add_f32_e32 v134, v104, v134
	v_add_f32_e32 v134, v100, v134
	v_add_f32_e32 v134, v96, v134
	v_add_f32_e32 v134, v92, v134
	v_add_f32_e32 v134, v88, v134
	v_add_f32_e32 v134, v84, v134
	v_add_f32_e32 v134, v80, v134
	v_add_f32_e32 v134, v76, v134
	v_add_f32_e32 v134, v72, v134
	s_waitcnt vmcnt(29)
; DI float fexp2(float x) { return __builtin_amdgcn_exp2f(x); }
; DI float dot16(f32x4 a, f32x4 b) { float d = (a[0] * b[0] + a[1] * b[1]) + (a[2] * b[2] + a[3] * b[3]); d += __shfl_xor(d, 1); d += __shfl_xor(d, 2); d += __shfl_xor(d, 4); d += __shfl_xor(d, 8); return d; }
; DI void unit_sample_attn2(int u, const bf16* __restrict__ Q, const float* __restrict__ ckw, const float* __restrict__ cvw, const float* __restrict__ nkw, const float* __restrict__ nvw, const bf16* __restrict__ G, bf16* __restrict__ MIX, ...
;     ...
;     for (int n0 = 0; n0 < 96; n0 += 32) {
;         f32x4 kv[16], vv[16]; float s[16];
; #pragma unroll
;         for (int i = 0; i < 16; ++i) { const int n = n0 + 2 * i + half, dlt = sub ? 16 * (33 + n) : 512 - 4 * n; const size_t ro = (size_t)(2048 + j1 - dlt) * 512;
;             kv[i] = __builtin_nontemporal_load((const f32x4*)(ck + ro)); }
; #pragma unroll
;         for (int i = 0; i < 16; ++i) { const int n = n0 + 2 * i + half, dlt = sub ? 16 * (33 + n) : 512 - 4 * n; const size_t ro = (size_t)(2048 + j1 - dlt) * 512;
;             vv[i] = __builtin_nontemporal_load((const f32x4*)(cv + ro)); }
; #pragma unroll
;         for (int i = 0; i < 16; ++i) { const int n = n0 + 2 * i + half, dlt = sub ? 16 * (33 + n) : 512 - 4 * n;
;             s[i] = dot16(qs, kv[i]) - slope2 * (float)dlt + ((!sub && (dlt & 15) == 0) ? 1.f : 0.f); }
;         float mn = mB;
; #pragma unroll
;         for (int i = 0; i < 16; ++i) mn = fmaxf(mn, s[i]);
;         const float alpha = fexp2(mB - mn); float ps = 0.f; f32x4 acc = oB * alpha;
; #pragma unroll
;         for (int i = 0; i < 16; ++i) { const float p = fexp2(s[i] - mn); ps += p; acc += vv[i] * p; }
;         lB = lB * alpha + ps; mB = mn; oB = acc;
	v_mul_f32_e32 v68, v68, v132
	v_mul_f32_e32 v69, v69, v132
	v_mul_f32_e32 v70, v70, v132
	v_mul_f32_e32 v71, v71, v132
	v_fma_f32 v4, v4, v133, v68
	v_fma_f32 v5, v5, v133, v69
	v_fma_f32 v6, v6, v133, v70
	v_fma_f32 v7, v7, v133, v71
	v_fma_f32 v4, v64, v128, v4
	v_fma_f32 v5, v65, v128, v5
	v_fma_f32 v6, v66, v128, v6
	v_fma_f32 v7, v67, v128, v7
	v_fma_f32 v4, v60, v124, v4
	v_fma_f32 v5, v61, v124, v5
	v_fma_f32 v6, v62, v124, v6
	v_fma_f32 v7, v63, v124, v7
	v_fma_f32 v4, v56, v120, v4
	v_fma_f32 v5, v57, v120, v5
	v_fma_f32 v6, v58, v120, v6
	v_fma_f32 v7, v59, v120, v7
	s_waitcnt vmcnt(25)
	v_fma_f32 v4, v52, v116, v4
	v_fma_f32 v5, v53, v116, v5
	v_fma_f32 v6, v54, v116, v6
	v_fma_f32 v7, v55, v116, v7
	v_fma_f32 v4, v48, v112, v4
	v_fma_f32 v5, v49, v112, v5
	v_fma_f32 v6, v50, v112, v6
	v_fma_f32 v7, v51, v112, v7
	v_fma_f32 v4, v44, v108, v4
	v_fma_f32 v5, v45, v108, v5
	v_fma_f32 v6, v46, v108, v6
	v_fma_f32 v7, v47, v108, v7
	v_fma_f32 v4, v40, v104, v4
	v_fma_f32 v5, v41, v104, v5
	v_fma_f32 v6, v42, v104, v6
	v_fma_f32 v7, v43, v104, v7
	s_waitcnt vmcnt(21)
	v_fma_f32 v4, v36, v100, v4
	v_fma_f32 v5, v37, v100, v5
	v_fma_f32 v6, v38, v100, v6
	v_fma_f32 v7, v39, v100, v7
	v_fma_f32 v4, v32, v96, v4
	v_fma_f32 v5, v33, v96, v5
	v_fma_f32 v6, v34, v96, v6
	v_fma_f32 v7, v35, v96, v7
	v_fma_f32 v4, v28, v92, v4
	v_fma_f32 v5, v29, v92, v5
	v_fma_f32 v6, v30, v92, v6
	v_fma_f32 v7, v31, v92, v7
	v_fma_f32 v4, v24, v88, v4
	v_fma_f32 v5, v25, v88, v5
	v_fma_f32 v6, v26, v88, v6
	v_fma_f32 v7, v27, v88, v7
	s_waitcnt vmcnt(17)
	v_fma_f32 v4, v20, v84, v4
	v_fma_f32 v5, v21, v84, v5
	v_fma_f32 v6, v22, v84, v6
	v_fma_f32 v7, v23, v84, v7
	v_fma_f32 v4, v16, v80, v4
	v_fma_f32 v5, v17, v80, v5
	v_fma_f32 v6, v18, v80, v6
	v_fma_f32 v7, v19, v80, v7
	v_fma_f32 v4, v12, v76, v4
	v_fma_f32 v5, v13, v76, v5
	v_fma_f32 v6, v14, v76, v6
	v_fma_f32 v7, v15, v76, v7
	v_fma_f32 v4, v8, v72, v4
	v_fma_f32 v5, v9, v72, v5
	v_fma_f32 v6, v10, v72, v6
	v_fma_f32 v7, v11, v72, v7
	v_fma_f32 v174, v174, v133, v134
	v_add_u32_e32 v225, 0xfff00000, v224
	global_load_dwordx4 v[68:71], v225, s[2:3] nt
	v_add_u32_e32 v225, 0xffff0000, v225
	global_load_dwordx4 v[64:67], v225, s[2:3] nt
	v_add_u32_e32 v225, 0xffff0000, v225
	global_load_dwordx4 v[60:63], v225, s[2:3] nt
	v_add_u32_e32 v225, 0xffff0000, v225
	global_load_dwordx4 v[56:59], v225, s[2:3] nt
	v_add_u32_e32 v225, 0xffff0000, v225
	global_load_dwordx4 v[52:55], v225, s[2:3] nt
	v_add_u32_e32 v225, 0xffff0000, v225
	global_load_dwordx4 v[48:51], v225, s[2:3] nt
	v_add_u32_e32 v225, 0xffff0000, v225
	global_load_dwordx4 v[44:47], v225, s[2:3] nt
	v_add_u32_e32 v225, 0xffff0000, v225
	global_load_dwordx4 v[40:43], v225, s[2:3] nt
	v_add_u32_e32 v225, 0xffff0000, v225
	global_load_dwordx4 v[36:39], v225, s[2:3] nt
	v_add_u32_e32 v225, 0xffff0000, v225
	global_load_dwordx4 v[32:35], v225, s[2:3] nt
	v_add_u32_e32 v225, 0xffff0000, v225
	global_load_dwordx4 v[28:31], v225, s[2:3] nt
	v_add_u32_e32 v225, 0xffff0000, v225
	global_load_dwordx4 v[24:27], v225, s[2:3] nt
	v_add_u32_e32 v225, 0xffff0000, v225
	global_load_dwordx4 v[20:23], v225, s[2:3] nt
	v_add_u32_e32 v225, 0xffff0000, v225
	global_load_dwordx4 v[16:19], v225, s[2:3] nt
	v_add_u32_e32 v225, 0xffff0000, v225
	global_load_dwordx4 v[12:15], v225, s[2:3] nt
	v_add_u32_e32 v225, 0xffff0000, v225
	global_load_dwordx4 v[8:11], v225, s[2:3] nt
	v_add_u32_e32 v225, 0xffe00000, v224
	global_load_dwordx4 v[132:135], v225, s[0:1] nt
	v_add_u32_e32 v225, 0xffff0000, v225
	global_load_dwordx4 v[128:131], v225, s[0:1] nt
	v_add_u32_e32 v225, 0xffff0000, v225
	global_load_dwordx4 v[124:127], v225, s[0:1] nt
	v_add_u32_e32 v225, 0xffff0000, v225
	global_load_dwordx4 v[120:123], v225, s[0:1] nt
	v_add_u32_e32 v225, 0xffff0000, v225
	global_load_dwordx4 v[116:119], v225, s[0:1] nt
	v_add_u32_e32 v225, 0xffff0000, v225
	global_load_dwordx4 v[112:115], v225, s[0:1] nt
	v_add_u32_e32 v225, 0xffff0000, v225
	global_load_dwordx4 v[108:111], v225, s[0:1] nt
	v_add_u32_e32 v225, 0xffff0000, v225
	global_load_dwordx4 v[104:107], v225, s[0:1] nt
	v_add_u32_e32 v225, 0xffff0000, v225
	global_load_dwordx4 v[100:103], v225, s[0:1] nt
	v_add_u32_e32 v225, 0xffff0000, v225
	global_load_dwordx4 v[96:99], v225, s[0:1] nt
	v_add_u32_e32 v225, 0xffff0000, v225
	global_load_dwordx4 v[92:95], v225, s[0:1] nt
	v_add_u32_e32 v225, 0xffff0000, v225
	global_load_dwordx4 v[88:91], v225, s[0:1] nt
	v_add_u32_e32 v225, 0xffff0000, v225
	global_load_dwordx4 v[84:87], v225, s[0:1] nt
	v_add_u32_e32 v225, 0xffff0000, v225
	global_load_dwordx4 v[80:83], v225, s[0:1] nt
	v_add_u32_e32 v225, 0xffff0000, v225
	global_load_dwordx4 v[76:79], v225, s[0:1] nt
	v_add_u32_e32 v225, 0xffff0000, v225
	global_load_dwordx4 v[72:75], v225, s[0:1] nt
	v_add_u32_e32 v227, 0x20, v172
	s_waitcnt vmcnt(45)
; DI float dot16(f32x4 a, f32x4 b) { float d = (a[0] * b[0] + a[1] * b[1]) + (a[2] * b[2] + a[3] * b[3]); d += __shfl_xor(d, 1); d += __shfl_xor(d, 2); d += __shfl_xor(d, 4); d += __shfl_xor(d, 8); return d; }
; DI void unit_sample_attn2(int u, const bf16* __restrict__ Q, const float* __restrict__ ckw, const float* __restrict__ cvw, const float* __restrict__ nkw, const float* __restrict__ nvw, const bf16* __restrict__ G, bf16* __restrict__ MIX, ...
;     ...
;         for (int i = 0; i < 16; ++i) { const int n = n0 + 2 * i + half, dlt = sub ? 16 * (33 + n) : 512 - 4 * n;
;             s[i] = dot16(qs, kv[i]) - slope2 * (float)dlt + ((!sub && (dlt & 15) == 0) ? 1.f : 0.f); }
	v_pk_mul_f32 v[188:189], v[188:189], v[158:159]
	v_pk_mul_f32 v[190:191], v[190:191], v[160:161]
	v_pk_mul_f32 v[192:193], v[192:193], v[158:159]
	v_pk_mul_f32 v[194:195], v[194:195], v[160:161]
	v_pk_mul_f32 v[196:197], v[196:197], v[158:159]
	v_pk_mul_f32 v[198:199], v[198:199], v[160:161]
	v_pk_mul_f32 v[200:201], v[200:201], v[158:159]
	v_pk_mul_f32 v[202:203], v[202:203], v[160:161]
	v_add_f32_e32 v188, v189, v188
	v_add_f32_e32 v190, v190, v191
	v_add_f32_e32 v192, v193, v192
	v_add_f32_e32 v194, v194, v195
	v_add_f32_e32 v196, v197, v196
	v_add_f32_e32 v198, v198, v199
	v_add_f32_e32 v200, v201, v200
	v_add_f32_e32 v202, v202, v203
	v_add_f32_e32 v188, v188, v190
	v_add_f32_e32 v192, v192, v194
	v_add_f32_e32 v196, v196, v198
	v_add_f32_e32 v200, v200, v202
	v_add_f32_dpp v188, v188, v188 quad_perm:[1,0,3,2] row_mask:0xf bank_mask:0xf
	v_add_f32_dpp v192, v192, v192 quad_perm:[1,0,3,2] row_mask:0xf bank_mask:0xf
	v_add_f32_dpp v196, v196, v196 quad_perm:[1,0,3,2] row_mask:0xf bank_mask:0xf
	v_add_f32_dpp v200, v200, v200 quad_perm:[1,0,3,2] row_mask:0xf bank_mask:0xf
	v_add_f32_dpp v188, v188, v188 quad_perm:[2,3,0,1] row_mask:0xf bank_mask:0xf
	v_add_f32_dpp v192, v192, v192 quad_perm:[2,3,0,1] row_mask:0xf bank_mask:0xf
	v_add_f32_dpp v196, v196, v196 quad_perm:[2,3,0,1] row_mask:0xf bank_mask:0xf
	v_add_f32_dpp v200, v200, v200 quad_perm:[2,3,0,1] row_mask:0xf bank_mask:0xf
	v_add_f32_dpp v188, v188, v188 row_half_mirror row_mask:0xf bank_mask:0xf
	v_add_f32_dpp v192, v192, v192 row_half_mirror row_mask:0xf bank_mask:0xf
	v_add_f32_dpp v196, v196, v196 row_half_mirror row_mask:0xf bank_mask:0xf
	v_add_f32_dpp v200, v200, v200 row_half_mirror row_mask:0xf bank_mask:0xf
	v_add_f32_dpp v188, v188, v188 row_mirror row_mask:0xf bank_mask:0xf
	v_add_f32_dpp v192, v192, v192 row_mirror row_mask:0xf bank_mask:0xf
	v_add_f32_dpp v196, v196, v196 row_mirror row_mask:0xf bank_mask:0xf
	v_add_f32_dpp v200, v200, v200 row_mirror row_mask:0xf bank_mask:0xf
	v_cvt_f32_i32_e32 v171, v227
	v_add_u32_e32 v227, 32, v227
	v_fma_f32 v188, -v136, v171, v188
	v_cvt_f32_i32_e32 v163, v227
	v_add_u32_e32 v227, 32, v227
	v_fma_f32 v192, -v136, v163, v192
	v_cvt_f32_i32_e32 v171, v227
	v_add_u32_e32 v227, 32, v227
	v_fma_f32 v196, -v136, v171, v196
	v_cvt_f32_i32_e32 v163, v227
	v_add_u32_e32 v227, 32, v227
	v_fma_f32 v200, -v136, v163, v200
	s_waitcnt vmcnt(41)
	v_pk_mul_f32 v[204:205], v[204:205], v[158:159]
	v_pk_mul_f32 v[206:207], v[206:207], v[160:161]
	v_pk_mul_f32 v[208:209], v[208:209], v[158:159]
	v_pk_mul_f32 v[210:211], v[210:211], v[160:161]
	v_pk_mul_f32 v[212:213], v[212:213], v[158:159]
	v_pk_mul_f32 v[214:215], v[214:215], v[160:161]
	v_pk_mul_f32 v[216:217], v[216:217], v[158:159]
	v_pk_mul_f32 v[218:219], v[218:219], v[160:161]
	v_add_f32_e32 v204, v205, v204
	v_add_f32_e32 v206, v206, v207
	v_add_f32_e32 v208, v209, v208
	v_add_f32_e32 v210, v210, v211
	v_add_f32_e32 v212, v213, v212
	v_add_f32_e32 v214, v214, v215
	v_add_f32_e32 v216, v217, v216
	v_add_f32_e32 v218, v218, v219
	v_add_f32_e32 v204, v204, v206
	v_add_f32_e32 v208, v208, v210
	v_add_f32_e32 v212, v212, v214
	v_add_f32_e32 v216, v216, v218
	v_add_f32_dpp v204, v204, v204 quad_perm:[1,0,3,2] row_mask:0xf bank_mask:0xf
	v_add_f32_dpp v208, v208, v208 quad_perm:[1,0,3,2] row_mask:0xf bank_mask:0xf
	v_add_f32_dpp v212, v212, v212 quad_perm:[1,0,3,2] row_mask:0xf bank_mask:0xf
	v_add_f32_dpp v216, v216, v216 quad_perm:[1,0,3,2] row_mask:0xf bank_mask:0xf
	v_add_f32_dpp v204, v204, v204 quad_perm:[2,3,0,1] row_mask:0xf bank_mask:0xf
	v_add_f32_dpp v208, v208, v208 quad_perm:[2,3,0,1] row_mask:0xf bank_mask:0xf
	v_add_f32_dpp v212, v212, v212 quad_perm:[2,3,0,1] row_mask:0xf bank_mask:0xf
	v_add_f32_dpp v216, v216, v216 quad_perm:[2,3,0,1] row_mask:0xf bank_mask:0xf
	v_add_f32_dpp v204, v204, v204 row_half_mirror row_mask:0xf bank_mask:0xf
	v_add_f32_dpp v208, v208, v208 row_half_mirror row_mask:0xf bank_mask:0xf
	v_add_f32_dpp v212, v212, v212 row_half_mirror row_mask:0xf bank_mask:0xf
	v_add_f32_dpp v216, v216, v216 row_half_mirror row_mask:0xf bank_mask:0xf
	v_add_f32_dpp v204, v204, v204 row_mirror row_mask:0xf bank_mask:0xf
	v_add_f32_dpp v208, v208, v208 row_mirror row_mask:0xf bank_mask:0xf
	v_add_f32_dpp v212, v212, v212 row_mirror row_mask:0xf bank_mask:0xf
	v_add_f32_dpp v216, v216, v216 row_mirror row_mask:0xf bank_mask:0xf
	v_cvt_f32_i32_e32 v171, v227
	v_add_u32_e32 v227, 32, v227
	v_fma_f32 v204, -v136, v171, v204
	v_cvt_f32_i32_e32 v163, v227
	v_add_u32_e32 v227, 32, v227
	v_fma_f32 v208, -v136, v163, v208
	v_cvt_f32_i32_e32 v171, v227
	v_add_u32_e32 v227, 32, v227
	v_fma_f32 v212, -v136, v171, v212
	v_cvt_f32_i32_e32 v163, v227
	v_add_u32_e32 v227, 32, v227
	v_fma_f32 v216, -v136, v163, v216
	s_waitcnt vmcnt(37)
; DI float fexp2(float x) { return __builtin_amdgcn_exp2f(x); }
; DI float dot16(f32x4 a, f32x4 b) { float d = (a[0] * b[0] + a[1] * b[1]) + (a[2] * b[2] + a[3] * b[3]); d += __shfl_xor(d, 1); d += __shfl_xor(d, 2); d += __shfl_xor(d, 4); d += __shfl_xor(d, 8); return d; }
; DI void unit_sample_attn2(int u, const bf16* __restrict__ Q, const float* __restrict__ ckw, const float* __restrict__ cvw, const float* __restrict__ nkw, const float* __restrict__ nvw, const bf16* __restrict__ G, bf16* __restrict__ MIX, ...
;     ...
;         for (int i = 0; i < 16; ++i) { const int n = n0 + 2 * i + half, dlt = sub ? 16 * (33 + n) : 512 - 4 * n;
;             s[i] = dot16(qs, kv[i]) - slope2 * (float)dlt + ((!sub && (dlt & 15) == 0) ? 1.f : 0.f); }
;         float mn = mB;
; #pragma unroll
;         for (int i = 0; i < 16; ++i) mn = fmaxf(mn, s[i]);
;         const float alpha = fexp2(mB - mn); float ps = 0.f; f32x4 acc = oB * alpha;
; #pragma unroll
;         for (int i = 0; i < 16; ++i) { const float p = fexp2(s[i] - mn); ps += p; acc += vv[i] * p; }
;         lB = lB * alpha + ps; mB = mn; oB = acc;
	v_pk_mul_f32 v[220:221], v[220:221], v[158:159]
	v_pk_mul_f32 v[222:223], v[222:223], v[160:161]
	v_pk_mul_f32 v[228:229], v[228:229], v[158:159]
	v_pk_mul_f32 v[230:231], v[230:231], v[160:161]
	v_pk_mul_f32 v[232:233], v[232:233], v[158:159]
	v_pk_mul_f32 v[234:235], v[234:235], v[160:161]
	v_pk_mul_f32 v[236:237], v[236:237], v[158:159]
	v_pk_mul_f32 v[238:239], v[238:239], v[160:161]
	v_add_f32_e32 v220, v221, v220
	v_add_f32_e32 v222, v222, v223
	v_add_f32_e32 v228, v229, v228
	v_add_f32_e32 v230, v230, v231
	v_add_f32_e32 v232, v233, v232
	v_add_f32_e32 v234, v234, v235
	v_add_f32_e32 v236, v237, v236
	v_add_f32_e32 v238, v238, v239
	v_add_f32_e32 v220, v220, v222
	v_add_f32_e32 v228, v228, v230
	v_add_f32_e32 v232, v232, v234
	v_add_f32_e32 v236, v236, v238
	v_add_f32_dpp v220, v220, v220 quad_perm:[1,0,3,2] row_mask:0xf bank_mask:0xf
	v_add_f32_dpp v228, v228, v228 quad_perm:[1,0,3,2] row_mask:0xf bank_mask:0xf
	v_add_f32_dpp v232, v232, v232 quad_perm:[1,0,3,2] row_mask:0xf bank_mask:0xf
	v_add_f32_dpp v236, v236, v236 quad_perm:[1,0,3,2] row_mask:0xf bank_mask:0xf
	v_add_f32_dpp v220, v220, v220 quad_perm:[2,3,0,1] row_mask:0xf bank_mask:0xf
	v_add_f32_dpp v228, v228, v228 quad_perm:[2,3,0,1] row_mask:0xf bank_mask:0xf
	v_add_f32_dpp v232, v232, v232 quad_perm:[2,3,0,1] row_mask:0xf bank_mask:0xf
	v_add_f32_dpp v236, v236, v236 quad_perm:[2,3,0,1] row_mask:0xf bank_mask:0xf
	v_add_f32_dpp v220, v220, v220 row_half_mirror row_mask:0xf bank_mask:0xf
	v_add_f32_dpp v228, v228, v228 row_half_mirror row_mask:0xf bank_mask:0xf
	v_add_f32_dpp v232, v232, v232 row_half_mirror row_mask:0xf bank_mask:0xf
	v_add_f32_dpp v236, v236, v236 row_half_mirror row_mask:0xf bank_mask:0xf
	v_add_f32_dpp v220, v220, v220 row_mirror row_mask:0xf bank_mask:0xf
	v_add_f32_dpp v228, v228, v228 row_mirror row_mask:0xf bank_mask:0xf
	v_add_f32_dpp v232, v232, v232 row_mirror row_mask:0xf bank_mask:0xf
	v_add_f32_dpp v236, v236, v236 row_mirror row_mask:0xf bank_mask:0xf
	v_cvt_f32_i32_e32 v171, v227
	v_add_u32_e32 v227, 32, v227
	v_fma_f32 v220, -v136, v171, v220
	v_cvt_f32_i32_e32 v163, v227
	v_add_u32_e32 v227, 32, v227
	v_fma_f32 v228, -v136, v163, v228
	v_cvt_f32_i32_e32 v171, v227
	v_add_u32_e32 v227, 32, v227
	v_fma_f32 v232, -v136, v171, v232
	v_cvt_f32_i32_e32 v163, v227
	v_add_u32_e32 v227, 32, v227
	v_fma_f32 v236, -v136, v163, v236
	s_waitcnt vmcnt(32)
	v_pk_mul_f32 v[240:241], v[240:241], v[158:159]
	v_pk_mul_f32 v[242:243], v[242:243], v[160:161]
	v_pk_mul_f32 v[176:177], v[176:177], v[158:159]
	v_pk_mul_f32 v[178:179], v[178:179], v[160:161]
	v_pk_mul_f32 v[184:185], v[184:185], v[158:159]
	v_pk_mul_f32 v[186:187], v[186:187], v[160:161]
	v_pk_mul_f32 v[180:181], v[180:181], v[158:159]
	v_pk_mul_f32 v[244:245], v[244:245], v[160:161]
	v_add_f32_e32 v240, v241, v240
	v_add_f32_e32 v242, v242, v243
	v_add_f32_e32 v176, v177, v176
	v_add_f32_e32 v178, v178, v179
	v_add_f32_e32 v184, v185, v184
	v_add_f32_e32 v186, v186, v187
	v_add_f32_e32 v180, v181, v180
	v_add_f32_e32 v244, v244, v245
	v_add_f32_e32 v240, v240, v242
	v_add_f32_e32 v176, v176, v178
	v_add_f32_e32 v184, v184, v186
	v_add_f32_e32 v180, v180, v244
	v_add_f32_dpp v240, v240, v240 quad_perm:[1,0,3,2] row_mask:0xf bank_mask:0xf
	v_add_f32_dpp v176, v176, v176 quad_perm:[1,0,3,2] row_mask:0xf bank_mask:0xf
	v_add_f32_dpp v184, v184, v184 quad_perm:[1,0,3,2] row_mask:0xf bank_mask:0xf
	v_add_f32_dpp v180, v180, v180 quad_perm:[1,0,3,2] row_mask:0xf bank_mask:0xf
	v_add_f32_dpp v240, v240, v240 quad_perm:[2,3,0,1] row_mask:0xf bank_mask:0xf
	v_add_f32_dpp v176, v176, v176 quad_perm:[2,3,0,1] row_mask:0xf bank_mask:0xf
	v_add_f32_dpp v184, v184, v184 quad_perm:[2,3,0,1] row_mask:0xf bank_mask:0xf
	v_add_f32_dpp v180, v180, v180 quad_perm:[2,3,0,1] row_mask:0xf bank_mask:0xf
	v_add_f32_dpp v240, v240, v240 row_half_mirror row_mask:0xf bank_mask:0xf
	v_add_f32_dpp v176, v176, v176 row_half_mirror row_mask:0xf bank_mask:0xf
	v_add_f32_dpp v184, v184, v184 row_half_mirror row_mask:0xf bank_mask:0xf
	v_add_f32_dpp v180, v180, v180 row_half_mirror row_mask:0xf bank_mask:0xf
	v_add_f32_dpp v240, v240, v240 row_mirror row_mask:0xf bank_mask:0xf
	v_add_f32_dpp v176, v176, v176 row_mirror row_mask:0xf bank_mask:0xf
	v_add_f32_dpp v184, v184, v184 row_mirror row_mask:0xf bank_mask:0xf
	v_add_f32_dpp v180, v180, v180 row_mirror row_mask:0xf bank_mask:0xf
	v_cvt_f32_i32_e32 v171, v227
	v_add_u32_e32 v227, 32, v227
	v_fma_f32 v240, -v136, v171, v240
	v_cvt_f32_i32_e32 v163, v227
	v_add_u32_e32 v227, 32, v227
	v_fma_f32 v176, -v136, v163, v176
	v_cvt_f32_i32_e32 v171, v227
	v_add_u32_e32 v227, 32, v227
	v_fma_f32 v184, -v136, v171, v184
	v_cvt_f32_i32_e32 v163, v227
	v_add_u32_e32 v227, 32, v227
	v_fma_f32 v180, -v136, v163, v180
	v_max3_f32 v191, v175, v188, v192
	v_max3_f32 v191, v191, v196, v200
	v_max3_f32 v191, v191, v204, v208
	v_max3_f32 v191, v191, v212, v216
	v_max3_f32 v191, v191, v220, v228
	v_max3_f32 v191, v191, v232, v236
	v_max3_f32 v191, v191, v240, v176
	v_max3_f32 v191, v191, v184, v180
	v_sub_f32_e32 v189, v175, v191
	v_sub_f32_e32 v188, v188, v191
	v_sub_f32_e32 v192, v192, v191
	v_sub_f32_e32 v196, v196, v191
	v_sub_f32_e32 v200, v200, v191
	v_sub_f32_e32 v204, v204, v191
	v_sub_f32_e32 v208, v208, v191
	v_sub_f32_e32 v212, v212, v191
	v_sub_f32_e32 v216, v216, v191
	v_sub_f32_e32 v220, v220, v191
	v_sub_f32_e32 v228, v228, v191
	v_sub_f32_e32 v232, v232, v191
	v_sub_f32_e32 v236, v236, v191
	v_sub_f32_e32 v240, v240, v191
	v_sub_f32_e32 v176, v176, v191
	v_sub_f32_e32 v184, v184, v191
	v_sub_f32_e32 v180, v180, v191
	v_exp_f32_e32 v189, v189
	v_exp_f32_e32 v188, v188
	v_exp_f32_e32 v192, v192
	v_exp_f32_e32 v196, v196
	v_exp_f32_e32 v200, v200
	v_exp_f32_e32 v204, v204
	v_exp_f32_e32 v208, v208
	v_exp_f32_e32 v212, v212
	v_exp_f32_e32 v216, v216
	v_exp_f32_e32 v220, v220
	v_exp_f32_e32 v228, v228
	v_exp_f32_e32 v232, v232
	v_exp_f32_e32 v236, v236
	v_exp_f32_e32 v240, v240
	v_exp_f32_e32 v176, v176
	v_exp_f32_e32 v184, v184
	v_exp_f32_e32 v180, v180
	v_mov_b32_e32 v175, v191
	v_add_f32_e32 v190, 0, v188
	v_add_f32_e32 v190, v192, v190
	v_add_f32_e32 v190, v196, v190
	v_add_f32_e32 v190, v200, v190
	v_add_f32_e32 v190, v204, v190
	v_add_f32_e32 v190, v208, v190
	v_add_f32_e32 v190, v212, v190
	v_add_f32_e32 v190, v216, v190
	v_add_f32_e32 v190, v220, v190
	v_add_f32_e32 v190, v228, v190
	v_add_f32_e32 v190, v232, v190
	v_add_f32_e32 v190, v236, v190
	v_add_f32_e32 v190, v240, v190
	v_add_f32_e32 v190, v176, v190
	v_add_f32_e32 v190, v184, v190
	v_add_f32_e32 v190, v180, v190
	s_waitcnt vmcnt(28)
; DI float fexp2(float x) { return __builtin_amdgcn_exp2f(x); }
; DI float dot16(f32x4 a, f32x4 b) { float d = (a[0] * b[0] + a[1] * b[1]) + (a[2] * b[2] + a[3] * b[3]); d += __shfl_xor(d, 1); d += __shfl_xor(d, 2); d += __shfl_xor(d, 4); d += __shfl_xor(d, 8); return d; }
; DI void unit_sample_attn2(int u, const bf16* __restrict__ Q, const float* __restrict__ ckw, const float* __restrict__ cvw, const float* __restrict__ nkw, const float* __restrict__ nvw, const bf16* __restrict__ G, bf16* __restrict__ MIX, ...
;     ...
;     for (int n0 = 0; n0 < 96; n0 += 32) {
;         f32x4 kv[16], vv[16]; float s[16];
; #pragma unroll
;         for (int i = 0; i < 16; ++i) { const int n = n0 + 2 * i + half, dlt = sub ? 16 * (33 + n) : 512 - 4 * n; const size_t ro = (size_t)(2048 + j1 - dlt) * 512;
;             kv[i] = __builtin_nontemporal_load((const f32x4*)(ck + ro)); }
; #pragma unroll
;         for (int i = 0; i < 16; ++i) { const int n = n0 + 2 * i + half, dlt = sub ? 16 * (33 + n) : 512 - 4 * n; const size_t ro = (size_t)(2048 + j1 - dlt) * 512;
;             vv[i] = __builtin_nontemporal_load((const f32x4*)(cv + ro)); }
; #pragma unroll
;         for (int i = 0; i < 16; ++i) { const int n = n0 + 2 * i + half, dlt = sub ? 16 * (33 + n) : 512 - 4 * n;
;             s[i] = dot16(qs, kv[i]) - slope2 * (float)dlt + ((!sub && (dlt & 15) == 0) ? 1.f : 0.f); }
;         float mn = mB;
; #pragma unroll
;         for (int i = 0; i < 16; ++i) mn = fmaxf(mn, s[i]);
;         const float alpha = fexp2(mB - mn); float ps = 0.f; f32x4 acc = oB * alpha;
; #pragma unroll
;         for (int i = 0; i < 16; ++i) { const float p = fexp2(s[i] - mn); ps += p; acc += vv[i] * p; }
;         lB = lB * alpha + ps; mB = mn; oB = acc;
	v_mul_f32_e32 v68, v68, v188
	v_mul_f32_e32 v69, v69, v188
	v_mul_f32_e32 v70, v70, v188
	v_mul_f32_e32 v71, v71, v188
	v_fma_f32 v4, v4, v189, v68
	v_fma_f32 v5, v5, v189, v69
	v_fma_f32 v6, v6, v189, v70
	v_fma_f32 v7, v7, v189, v71
	v_fma_f32 v4, v64, v192, v4
	v_fma_f32 v5, v65, v192, v5
	v_fma_f32 v6, v66, v192, v6
	v_fma_f32 v7, v67, v192, v7
	v_fma_f32 v4, v60, v196, v4
	v_fma_f32 v5, v61, v196, v5
	v_fma_f32 v6, v62, v196, v6
	v_fma_f32 v7, v63, v196, v7
	v_fma_f32 v4, v56, v200, v4
	v_fma_f32 v5, v57, v200, v5
	v_fma_f32 v6, v58, v200, v6
	v_fma_f32 v7, v59, v200, v7
	s_waitcnt vmcnt(24)
	v_fma_f32 v4, v52, v204, v4
	v_fma_f32 v5, v53, v204, v5
	v_fma_f32 v6, v54, v204, v6
	v_fma_f32 v7, v55, v204, v7
	v_fma_f32 v4, v48, v208, v4
	v_fma_f32 v5, v49, v208, v5
	v_fma_f32 v6, v50, v208, v6
	v_fma_f32 v7, v51, v208, v7
	v_fma_f32 v4, v44, v212, v4
	v_fma_f32 v5, v45, v212, v5
	v_fma_f32 v6, v46, v212, v6
	v_fma_f32 v7, v47, v212, v7
	v_fma_f32 v4, v40, v216, v4
	v_fma_f32 v5, v41, v216, v5
	v_fma_f32 v6, v42, v216, v6
	v_fma_f32 v7, v43, v216, v7
	s_waitcnt vmcnt(20)
	v_fma_f32 v4, v36, v220, v4
	v_fma_f32 v5, v37, v220, v5
	v_fma_f32 v6, v38, v220, v6
	v_fma_f32 v7, v39, v220, v7
	v_fma_f32 v4, v32, v228, v4
	v_fma_f32 v5, v33, v228, v5
	v_fma_f32 v6, v34, v228, v6
	v_fma_f32 v7, v35, v228, v7
	v_fma_f32 v4, v28, v232, v4
	v_fma_f32 v5, v29, v232, v5
	v_fma_f32 v6, v30, v232, v6
	v_fma_f32 v7, v31, v232, v7
	v_fma_f32 v4, v24, v236, v4
	v_fma_f32 v5, v25, v236, v5
	v_fma_f32 v6, v26, v236, v6
	v_fma_f32 v7, v27, v236, v7
	s_waitcnt vmcnt(16)
	v_fma_f32 v4, v20, v240, v4
	v_fma_f32 v5, v21, v240, v5
	v_fma_f32 v6, v22, v240, v6
	v_fma_f32 v7, v23, v240, v7
	v_fma_f32 v4, v16, v176, v4
	v_fma_f32 v5, v17, v176, v5
	v_fma_f32 v6, v18, v176, v6
	v_fma_f32 v7, v19, v176, v7
	v_fma_f32 v4, v12, v184, v4
	v_fma_f32 v5, v13, v184, v5
	v_fma_f32 v6, v14, v184, v6
	v_fma_f32 v7, v15, v184, v7
	v_fma_f32 v4, v8, v180, v4
	v_fma_f32 v5, v9, v180, v5
	v_fma_f32 v6, v10, v180, v6
	v_fma_f32 v7, v11, v180, v7
	v_fma_f32 v174, v174, v189, v190
	v_add_u32_e32 v225, 0xffe00000, v224
	global_load_dwordx4 v[68:71], v225, s[2:3] nt
	v_add_u32_e32 v225, 0xffff0000, v225
	global_load_dwordx4 v[64:67], v225, s[2:3] nt
	v_add_u32_e32 v225, 0xffff0000, v225
	global_load_dwordx4 v[60:63], v225, s[2:3] nt
	v_add_u32_e32 v225, 0xffff0000, v225
	global_load_dwordx4 v[56:59], v225, s[2:3] nt
	v_add_u32_e32 v225, 0xffff0000, v225
	global_load_dwordx4 v[52:55], v225, s[2:3] nt
	v_add_u32_e32 v225, 0xffff0000, v225
	global_load_dwordx4 v[48:51], v225, s[2:3] nt
	v_add_u32_e32 v225, 0xffff0000, v225
	global_load_dwordx4 v[44:47], v225, s[2:3] nt
	v_add_u32_e32 v225, 0xffff0000, v225
	global_load_dwordx4 v[40:43], v225, s[2:3] nt
	v_add_u32_e32 v225, 0xffff0000, v225
	global_load_dwordx4 v[36:39], v225, s[2:3] nt
	v_add_u32_e32 v225, 0xffff0000, v225
	global_load_dwordx4 v[32:35], v225, s[2:3] nt
	v_add_u32_e32 v225, 0xffff0000, v225
	global_load_dwordx4 v[28:31], v225, s[2:3] nt
	v_add_u32_e32 v225, 0xffff0000, v225
	global_load_dwordx4 v[24:27], v225, s[2:3] nt
	v_add_u32_e32 v225, 0xffff0000, v225
	global_load_dwordx4 v[20:23], v225, s[2:3] nt
	v_add_u32_e32 v225, 0xffff0000, v225
	global_load_dwordx4 v[16:19], v225, s[2:3] nt
	v_add_u32_e32 v225, 0xffff0000, v225
	global_load_dwordx4 v[12:15], v225, s[2:3] nt
	v_add_u32_e32 v225, 0xffff0000, v225
	global_load_dwordx4 v[8:11], v225, s[2:3] nt
	v_add_u32_e32 v227, 0x220, v172
	s_waitcnt vmcnt(28)
	v_pk_mul_f32 v[132:133], v[132:133], v[158:159]
	v_pk_mul_f32 v[134:135], v[134:135], v[160:161]
	v_pk_mul_f32 v[128:129], v[128:129], v[158:159]
	v_pk_mul_f32 v[130:131], v[130:131], v[160:161]
	v_pk_mul_f32 v[124:125], v[124:125], v[158:159]
	v_pk_mul_f32 v[126:127], v[126:127], v[160:161]
	v_pk_mul_f32 v[120:121], v[120:121], v[158:159]
	v_pk_mul_f32 v[122:123], v[122:123], v[160:161]
	v_add_f32_e32 v132, v133, v132
	v_add_f32_e32 v134, v134, v135
	v_add_f32_e32 v128, v129, v128
	v_add_f32_e32 v130, v130, v131
	v_add_f32_e32 v124, v125, v124
	v_add_f32_e32 v126, v126, v127
	v_add_f32_e32 v120, v121, v120
	v_add_f32_e32 v122, v122, v123
	v_add_f32_e32 v132, v132, v134
	v_add_f32_e32 v128, v128, v130
	v_add_f32_e32 v124, v124, v126
	v_add_f32_e32 v120, v120, v122
	v_add_f32_dpp v132, v132, v132 quad_perm:[1,0,3,2] row_mask:0xf bank_mask:0xf
	v_add_f32_dpp v128, v128, v128 quad_perm:[1,0,3,2] row_mask:0xf bank_mask:0xf
	v_add_f32_dpp v124, v124, v124 quad_perm:[1,0,3,2] row_mask:0xf bank_mask:0xf
	v_add_f32_dpp v120, v120, v120 quad_perm:[1,0,3,2] row_mask:0xf bank_mask:0xf
	v_add_f32_dpp v132, v132, v132 quad_perm:[2,3,0,1] row_mask:0xf bank_mask:0xf
	v_add_f32_dpp v128, v128, v128 quad_perm:[2,3,0,1] row_mask:0xf bank_mask:0xf
	v_add_f32_dpp v124, v124, v124 quad_perm:[2,3,0,1] row_mask:0xf bank_mask:0xf
	v_add_f32_dpp v120, v120, v120 quad_perm:[2,3,0,1] row_mask:0xf bank_mask:0xf
	v_add_f32_dpp v132, v132, v132 row_half_mirror row_mask:0xf bank_mask:0xf
	v_add_f32_dpp v128, v128, v128 row_half_mirror row_mask:0xf bank_mask:0xf
	v_add_f32_dpp v124, v124, v124 row_half_mirror row_mask:0xf bank_mask:0xf
	v_add_f32_dpp v120, v120, v120 row_half_mirror row_mask:0xf bank_mask:0xf
	v_add_f32_dpp v132, v132, v132 row_mirror row_mask:0xf bank_mask:0xf
	v_add_f32_dpp v128, v128, v128 row_mirror row_mask:0xf bank_mask:0xf
	v_add_f32_dpp v124, v124, v124 row_mirror row_mask:0xf bank_mask:0xf
	v_add_f32_dpp v120, v120, v120 row_mirror row_mask:0xf bank_mask:0xf
	v_cvt_f32_i32_e32 v171, v227
	v_add_u32_e32 v227, 32, v227
	v_fma_f32 v132, -v136, v171, v132
	v_cvt_f32_i32_e32 v163, v227
	v_add_u32_e32 v227, 32, v227
	v_fma_f32 v128, -v136, v163, v128
	v_cvt_f32_i32_e32 v171, v227
	v_add_u32_e32 v227, 32, v227
	v_fma_f32 v124, -v136, v171, v124
	v_cvt_f32_i32_e32 v163, v227
	v_add_u32_e32 v227, 32, v227
	v_fma_f32 v120, -v136, v163, v120
	s_waitcnt vmcnt(24)
; DI float dot16(f32x4 a, f32x4 b) { float d = (a[0] * b[0] + a[1] * b[1]) + (a[2] * b[2] + a[3] * b[3]); d += __shfl_xor(d, 1); d += __shfl_xor(d, 2); d += __shfl_xor(d, 4); d += __shfl_xor(d, 8); return d; }
; DI void unit_sample_attn2(int u, const bf16* __restrict__ Q, const float* __restrict__ ckw, const float* __restrict__ cvw, const float* __restrict__ nkw, const float* __restrict__ nvw, const bf16* __restrict__ G, bf16* __restrict__ MIX, ...
;     ...
;         for (int i = 0; i < 16; ++i) { const int n = n0 + 2 * i + half, dlt = sub ? 16 * (33 + n) : 512 - 4 * n;
;             s[i] = dot16(qs, kv[i]) - slope2 * (float)dlt + ((!sub && (dlt & 15) == 0) ? 1.f : 0.f); }
	v_pk_mul_f32 v[116:117], v[116:117], v[158:159]
	v_pk_mul_f32 v[118:119], v[118:119], v[160:161]
	v_pk_mul_f32 v[112:113], v[112:113], v[158:159]
	v_pk_mul_f32 v[114:115], v[114:115], v[160:161]
	v_pk_mul_f32 v[108:109], v[108:109], v[158:159]
	v_pk_mul_f32 v[110:111], v[110:111], v[160:161]
	v_pk_mul_f32 v[104:105], v[104:105], v[158:159]
	v_pk_mul_f32 v[106:107], v[106:107], v[160:161]
	v_add_f32_e32 v116, v117, v116
	v_add_f32_e32 v118, v118, v119
	v_add_f32_e32 v112, v113, v112
	v_add_f32_e32 v114, v114, v115
	v_add_f32_e32 v108, v109, v108
	v_add_f32_e32 v110, v110, v111
	v_add_f32_e32 v104, v105, v104
	v_add_f32_e32 v106, v106, v107
	v_add_f32_e32 v116, v116, v118
	v_add_f32_e32 v112, v112, v114
	v_add_f32_e32 v108, v108, v110
	v_add_f32_e32 v104, v104, v106
	v_add_f32_dpp v116, v116, v116 quad_perm:[1,0,3,2] row_mask:0xf bank_mask:0xf
	v_add_f32_dpp v112, v112, v112 quad_perm:[1,0,3,2] row_mask:0xf bank_mask:0xf
	v_add_f32_dpp v108, v108, v108 quad_perm:[1,0,3,2] row_mask:0xf bank_mask:0xf
	v_add_f32_dpp v104, v104, v104 quad_perm:[1,0,3,2] row_mask:0xf bank_mask:0xf
	v_add_f32_dpp v116, v116, v116 quad_perm:[2,3,0,1] row_mask:0xf bank_mask:0xf
	v_add_f32_dpp v112, v112, v112 quad_perm:[2,3,0,1] row_mask:0xf bank_mask:0xf
	v_add_f32_dpp v108, v108, v108 quad_perm:[2,3,0,1] row_mask:0xf bank_mask:0xf
	v_add_f32_dpp v104, v104, v104 quad_perm:[2,3,0,1] row_mask:0xf bank_mask:0xf
	v_add_f32_dpp v116, v116, v116 row_half_mirror row_mask:0xf bank_mask:0xf
	v_add_f32_dpp v112, v112, v112 row_half_mirror row_mask:0xf bank_mask:0xf
	v_add_f32_dpp v108, v108, v108 row_half_mirror row_mask:0xf bank_mask:0xf
	v_add_f32_dpp v104, v104, v104 row_half_mirror row_mask:0xf bank_mask:0xf
	v_add_f32_dpp v116, v116, v116 row_mirror row_mask:0xf bank_mask:0xf
	v_add_f32_dpp v112, v112, v112 row_mirror row_mask:0xf bank_mask:0xf
	v_add_f32_dpp v108, v108, v108 row_mirror row_mask:0xf bank_mask:0xf
	v_add_f32_dpp v104, v104, v104 row_mirror row_mask:0xf bank_mask:0xf
	v_cvt_f32_i32_e32 v171, v227
	v_add_u32_e32 v227, 32, v227
	v_fma_f32 v116, -v136, v171, v116
	v_cvt_f32_i32_e32 v163, v227
	v_add_u32_e32 v227, 32, v227
	v_fma_f32 v112, -v136, v163, v112
	v_cvt_f32_i32_e32 v171, v227
	v_add_u32_e32 v227, 32, v227
	v_fma_f32 v108, -v136, v171, v108
	v_cvt_f32_i32_e32 v163, v227
	v_add_u32_e32 v227, 32, v227
	v_fma_f32 v104, -v136, v163, v104
	s_waitcnt vmcnt(20)
	v_pk_mul_f32 v[100:101], v[100:101], v[158:159]
	v_pk_mul_f32 v[102:103], v[102:103], v[160:161]
	v_pk_mul_f32 v[96:97], v[96:97], v[158:159]
	v_pk_mul_f32 v[98:99], v[98:99], v[160:161]
	v_pk_mul_f32 v[92:93], v[92:93], v[158:159]
	v_pk_mul_f32 v[94:95], v[94:95], v[160:161]
	v_pk_mul_f32 v[88:89], v[88:89], v[158:159]
	v_pk_mul_f32 v[90:91], v[90:91], v[160:161]
	v_add_f32_e32 v100, v101, v100
	v_add_f32_e32 v102, v102, v103
	v_add_f32_e32 v96, v97, v96
	v_add_f32_e32 v98, v98, v99
	v_add_f32_e32 v92, v93, v92
	v_add_f32_e32 v94, v94, v95
	v_add_f32_e32 v88, v89, v88
	v_add_f32_e32 v90, v90, v91
	v_add_f32_e32 v100, v100, v102
	v_add_f32_e32 v96, v96, v98
	v_add_f32_e32 v92, v92, v94
	v_add_f32_e32 v88, v88, v90
	v_add_f32_dpp v100, v100, v100 quad_perm:[1,0,3,2] row_mask:0xf bank_mask:0xf
	v_add_f32_dpp v96, v96, v96 quad_perm:[1,0,3,2] row_mask:0xf bank_mask:0xf
	v_add_f32_dpp v92, v92, v92 quad_perm:[1,0,3,2] row_mask:0xf bank_mask:0xf
	v_add_f32_dpp v88, v88, v88 quad_perm:[1,0,3,2] row_mask:0xf bank_mask:0xf
	v_add_f32_dpp v100, v100, v100 quad_perm:[2,3,0,1] row_mask:0xf bank_mask:0xf
	v_add_f32_dpp v96, v96, v96 quad_perm:[2,3,0,1] row_mask:0xf bank_mask:0xf
	v_add_f32_dpp v92, v92, v92 quad_perm:[2,3,0,1] row_mask:0xf bank_mask:0xf
	v_add_f32_dpp v88, v88, v88 quad_perm:[2,3,0,1] row_mask:0xf bank_mask:0xf
	v_add_f32_dpp v100, v100, v100 row_half_mirror row_mask:0xf bank_mask:0xf
	v_add_f32_dpp v96, v96, v96 row_half_mirror row_mask:0xf bank_mask:0xf
	v_add_f32_dpp v92, v92, v92 row_half_mirror row_mask:0xf bank_mask:0xf
	v_add_f32_dpp v88, v88, v88 row_half_mirror row_mask:0xf bank_mask:0xf
	v_add_f32_dpp v100, v100, v100 row_mirror row_mask:0xf bank_mask:0xf
	v_add_f32_dpp v96, v96, v96 row_mirror row_mask:0xf bank_mask:0xf
	v_add_f32_dpp v92, v92, v92 row_mirror row_mask:0xf bank_mask:0xf
	v_add_f32_dpp v88, v88, v88 row_mirror row_mask:0xf bank_mask:0xf
	v_cvt_f32_i32_e32 v171, v227
	v_add_u32_e32 v227, 32, v227
	v_fma_f32 v100, -v136, v171, v100
	v_cvt_f32_i32_e32 v163, v227
	v_add_u32_e32 v227, 32, v227
	v_fma_f32 v96, -v136, v163, v96
	v_cvt_f32_i32_e32 v171, v227
	v_add_u32_e32 v227, 32, v227
	v_fma_f32 v92, -v136, v171, v92
	v_cvt_f32_i32_e32 v163, v227
	v_add_u32_e32 v227, 32, v227
	v_fma_f32 v88, -v136, v163, v88
	s_waitcnt vmcnt(16)
; DI float fexp2(float x) { return __builtin_amdgcn_exp2f(x); }
; DI float dot16(f32x4 a, f32x4 b) { float d = (a[0] * b[0] + a[1] * b[1]) + (a[2] * b[2] + a[3] * b[3]); d += __shfl_xor(d, 1); d += __shfl_xor(d, 2); d += __shfl_xor(d, 4); d += __shfl_xor(d, 8); return d; }
; DI void unit_sample_attn2(int u, const bf16* __restrict__ Q, const float* __restrict__ ckw, const float* __restrict__ cvw, const float* __restrict__ nkw, const float* __restrict__ nvw, const bf16* __restrict__ G, bf16* __restrict__ MIX, ...
;     ...
;         for (int i = 0; i < 16; ++i) { const int n = n0 + 2 * i + half, dlt = sub ? 16 * (33 + n) : 512 - 4 * n;
;             s[i] = dot16(qs, kv[i]) - slope2 * (float)dlt + ((!sub && (dlt & 15) == 0) ? 1.f : 0.f); }
;         float mn = mB;
; #pragma unroll
;         for (int i = 0; i < 16; ++i) mn = fmaxf(mn, s[i]);
;         const float alpha = fexp2(mB - mn); float ps = 0.f; f32x4 acc = oB * alpha;
; #pragma unroll
;         for (int i = 0; i < 16; ++i) { const float p = fexp2(s[i] - mn); ps += p; acc += vv[i] * p; }
;         lB = lB * alpha + ps; mB = mn; oB = acc;
	v_pk_mul_f32 v[84:85], v[84:85], v[158:159]
	v_pk_mul_f32 v[86:87], v[86:87], v[160:161]
	v_pk_mul_f32 v[80:81], v[80:81], v[158:159]
	v_pk_mul_f32 v[82:83], v[82:83], v[160:161]
	v_pk_mul_f32 v[76:77], v[76:77], v[158:159]
	v_pk_mul_f32 v[78:79], v[78:79], v[160:161]
	v_pk_mul_f32 v[72:73], v[72:73], v[158:159]
	v_pk_mul_f32 v[74:75], v[74:75], v[160:161]
	v_add_f32_e32 v84, v85, v84
	v_add_f32_e32 v86, v86, v87
	v_add_f32_e32 v80, v81, v80
	v_add_f32_e32 v82, v82, v83
	v_add_f32_e32 v76, v77, v76
	v_add_f32_e32 v78, v78, v79
	v_add_f32_e32 v72, v73, v72
	v_add_f32_e32 v74, v74, v75
	v_add_f32_e32 v84, v84, v86
	v_add_f32_e32 v80, v80, v82
	v_add_f32_e32 v76, v76, v78
	v_add_f32_e32 v72, v72, v74
	v_add_f32_dpp v84, v84, v84 quad_perm:[1,0,3,2] row_mask:0xf bank_mask:0xf
	v_add_f32_dpp v80, v80, v80 quad_perm:[1,0,3,2] row_mask:0xf bank_mask:0xf
	v_add_f32_dpp v76, v76, v76 quad_perm:[1,0,3,2] row_mask:0xf bank_mask:0xf
	v_add_f32_dpp v72, v72, v72 quad_perm:[1,0,3,2] row_mask:0xf bank_mask:0xf
	v_add_f32_dpp v84, v84, v84 quad_perm:[2,3,0,1] row_mask:0xf bank_mask:0xf
	v_add_f32_dpp v80, v80, v80 quad_perm:[2,3,0,1] row_mask:0xf bank_mask:0xf
	v_add_f32_dpp v76, v76, v76 quad_perm:[2,3,0,1] row_mask:0xf bank_mask:0xf
	v_add_f32_dpp v72, v72, v72 quad_perm:[2,3,0,1] row_mask:0xf bank_mask:0xf
	v_add_f32_dpp v84, v84, v84 row_half_mirror row_mask:0xf bank_mask:0xf
	v_add_f32_dpp v80, v80, v80 row_half_mirror row_mask:0xf bank_mask:0xf
	v_add_f32_dpp v76, v76, v76 row_half_mirror row_mask:0xf bank_mask:0xf
	v_add_f32_dpp v72, v72, v72 row_half_mirror row_mask:0xf bank_mask:0xf
	v_add_f32_dpp v84, v84, v84 row_mirror row_mask:0xf bank_mask:0xf
	v_add_f32_dpp v80, v80, v80 row_mirror row_mask:0xf bank_mask:0xf
	v_add_f32_dpp v76, v76, v76 row_mirror row_mask:0xf bank_mask:0xf
	v_add_f32_dpp v72, v72, v72 row_mirror row_mask:0xf bank_mask:0xf
	v_cvt_f32_i32_e32 v171, v227
	v_add_u32_e32 v227, 32, v227
	v_fma_f32 v84, -v136, v171, v84
	v_cvt_f32_i32_e32 v163, v227
	v_add_u32_e32 v227, 32, v227
	v_fma_f32 v80, -v136, v163, v80
	v_cvt_f32_i32_e32 v171, v227
	v_add_u32_e32 v227, 32, v227
	v_fma_f32 v76, -v136, v171, v76
	v_cvt_f32_i32_e32 v163, v227
	v_add_u32_e32 v227, 32, v227
	v_fma_f32 v72, -v136, v163, v72
	v_max3_f32 v135, v175, v132, v128
	v_max3_f32 v135, v135, v124, v120
	v_max3_f32 v135, v135, v116, v112
	v_max3_f32 v135, v135, v108, v104
	v_max3_f32 v135, v135, v100, v96
	v_max3_f32 v135, v135, v92, v88
	v_max3_f32 v135, v135, v84, v80
	v_max3_f32 v135, v135, v76, v72
	v_sub_f32_e32 v133, v175, v135
	v_sub_f32_e32 v132, v132, v135
	v_sub_f32_e32 v128, v128, v135
	v_sub_f32_e32 v124, v124, v135
	v_sub_f32_e32 v120, v120, v135
	v_sub_f32_e32 v116, v116, v135
	v_sub_f32_e32 v112, v112, v135
	v_sub_f32_e32 v108, v108, v135
	v_sub_f32_e32 v104, v104, v135
	v_sub_f32_e32 v100, v100, v135
	v_sub_f32_e32 v96, v96, v135
	v_sub_f32_e32 v92, v92, v135
	v_sub_f32_e32 v88, v88, v135
	v_sub_f32_e32 v84, v84, v135
	v_sub_f32_e32 v80, v80, v135
	v_sub_f32_e32 v76, v76, v135
	v_sub_f32_e32 v72, v72, v135
	v_exp_f32_e32 v133, v133
	v_exp_f32_e32 v132, v132
	v_exp_f32_e32 v128, v128
	v_exp_f32_e32 v124, v124
	v_exp_f32_e32 v120, v120
	v_exp_f32_e32 v116, v116
	v_exp_f32_e32 v112, v112
	v_exp_f32_e32 v108, v108
	v_exp_f32_e32 v104, v104
	v_exp_f32_e32 v100, v100
	v_exp_f32_e32 v96, v96
	v_exp_f32_e32 v92, v92
	v_exp_f32_e32 v88, v88
	v_exp_f32_e32 v84, v84
	v_exp_f32_e32 v80, v80
	v_exp_f32_e32 v76, v76
	v_exp_f32_e32 v72, v72
	v_mov_b32_e32 v175, v135
	v_add_f32_e32 v134, 0, v132
	v_add_f32_e32 v134, v128, v134
	v_add_f32_e32 v134, v124, v134
	v_add_f32_e32 v134, v120, v134
	v_add_f32_e32 v134, v116, v134
	v_add_f32_e32 v134, v112, v134
	v_add_f32_e32 v134, v108, v134
	v_add_f32_e32 v134, v104, v134
	v_add_f32_e32 v134, v100, v134
	v_add_f32_e32 v134, v96, v134
	v_add_f32_e32 v134, v92, v134
	v_add_f32_e32 v134, v88, v134
	v_add_f32_e32 v134, v84, v134
	v_add_f32_e32 v134, v80, v134
	v_add_f32_e32 v134, v76, v134
	v_add_f32_e32 v134, v72, v134
	s_waitcnt vmcnt(12)
	v_mul_f32_e32 v68, v68, v132
	v_mul_f32_e32 v69, v69, v132
	v_mul_f32_e32 v70, v70, v132
	v_mul_f32_e32 v71, v71, v132
	v_fma_f32 v4, v4, v133, v68
	v_fma_f32 v5, v5, v133, v69
	v_fma_f32 v6, v6, v133, v70
	v_fma_f32 v7, v7, v133, v71
	v_fma_f32 v4, v64, v128, v4
	v_fma_f32 v5, v65, v128, v5
	v_fma_f32 v6, v66, v128, v6
	v_fma_f32 v7, v67, v128, v7
	v_fma_f32 v4, v60, v124, v4
	v_fma_f32 v5, v61, v124, v5
	v_fma_f32 v6, v62, v124, v6
	v_fma_f32 v7, v63, v124, v7
	v_fma_f32 v4, v56, v120, v4
	v_fma_f32 v5, v57, v120, v5
	v_fma_f32 v6, v58, v120, v6
	v_fma_f32 v7, v59, v120, v7
	s_waitcnt vmcnt(8)
	v_fma_f32 v4, v52, v116, v4
	v_fma_f32 v5, v53, v116, v5
	v_fma_f32 v6, v54, v116, v6
	v_fma_f32 v7, v55, v116, v7
	v_fma_f32 v4, v48, v112, v4
	v_fma_f32 v5, v49, v112, v5
	v_fma_f32 v6, v50, v112, v6
	v_fma_f32 v7, v51, v112, v7
	v_fma_f32 v4, v44, v108, v4
	v_fma_f32 v5, v45, v108, v5
	v_fma_f32 v6, v46, v108, v6
	v_fma_f32 v7, v47, v108, v7
	v_fma_f32 v4, v40, v104, v4
	v_fma_f32 v5, v41, v104, v5
	v_fma_f32 v6, v42, v104, v6
	v_fma_f32 v7, v43, v104, v7
	s_waitcnt vmcnt(4)
	v_fma_f32 v4, v36, v100, v4
	v_fma_f32 v5, v37, v100, v5
	v_fma_f32 v6, v38, v100, v6
	v_fma_f32 v7, v39, v100, v7
	v_fma_f32 v4, v32, v96, v4
	v_fma_f32 v5, v33, v96, v5
	v_fma_f32 v6, v34, v96, v6
	v_fma_f32 v7, v35, v96, v7
	v_fma_f32 v4, v28, v92, v4
	v_fma_f32 v5, v29, v92, v5
	v_fma_f32 v6, v30, v92, v6
	v_fma_f32 v7, v31, v92, v7
	v_fma_f32 v4, v24, v88, v4
	v_fma_f32 v5, v25, v88, v5
	v_fma_f32 v6, v26, v88, v6
	v_fma_f32 v7, v27, v88, v7
	s_waitcnt vmcnt(0)
	v_fma_f32 v4, v20, v84, v4
	v_fma_f32 v5, v21, v84, v5
	v_fma_f32 v6, v22, v84, v6
	v_fma_f32 v7, v23, v84, v7
	v_fma_f32 v4, v16, v80, v4
	v_fma_f32 v5, v17, v80, v5
	v_fma_f32 v6, v18, v80, v6
	v_fma_f32 v7, v19, v80, v7
	v_fma_f32 v4, v12, v76, v4
	v_fma_f32 v5, v13, v76, v5
	v_fma_f32 v6, v14, v76, v6
	v_fma_f32 v7, v15, v76, v7
	v_fma_f32 v4, v8, v72, v4
	v_fma_f32 v5, v9, v72, v5
	v_fma_f32 v6, v10, v72, v6
	v_fma_f32 v7, v11, v72, v7
	v_fma_f32 v174, v174, v133, v134
	v_mov_b32_e32 v85, v175
	v_mov_b32_e32 v87, v174
	s_branch .Ls1_done
; DI float dot16(f32x4 a, f32x4 b) { float d = (a[0] * b[0] + a[1] * b[1]) + (a[2] * b[2] + a[3] * b[3]); d += __shfl_xor(d, 1); d += __shfl_xor(d, 2); d += __shfl_xor(d, 4); d += __shfl_xor(d, 8); return d; }
; DI void unit_sample_attn2(int u, const bf16* __restrict__ Q, const float* __restrict__ ckw, const float* __restrict__ cvw, const float* __restrict__ nkw, const float* __restrict__ nvw, const bf16* __restrict__ G, bf16* __restrict__ MIX, ...
;     ...
;     {   f32x4 kv[9], vv[9]; int idxs[9];
; #pragma unroll
;         for (int i = 0; i < 9; ++i) { int idx = 1920 + wave + 8 * (2 * i + half); idxs[i] = idx; if (idx > 2051) idx = 2051;
;             const float* kp = (idx < 2048) ? ck + (size_t)idx * 512 : nk + (size_t)(idx - 2048) * 512;
;             const float* vp = (idx < 2048) ? cv + (size_t)idx * 512 : nv + (size_t)(idx - 2048) * 512;
;             kv[i] = __builtin_nontemporal_load((const f32x4*)kp); vv[i] = __builtin_nontemporal_load((const f32x4*)vp); }
; #pragma unroll
;         for (int jj = 0; jj < 4; ++jj) { float s[9]; float mn = NEG;
; #pragma unroll
;             for (int i = 0; i < 9; ++i) { const int dlt = 2048 + jj - idxs[i];
;                 const int cnt = (dlt <= 128 ? 1 : 0) + ((dlt & 3) == 0 ? 1 : 0) + ((dlt & 15) == 0 ? 1 : 0);
;                 const float lc = (cnt == 3) ? 1.5849625f : (cnt == 2) ? 1.f : 0.f;
;                 const float d = dot16(q[jj], kv[i]);
;                 s[i] = (idxs[i] > 2051 || dlt < 0 || cnt == 0) ? NEG : d - slope2 * (float)dlt + lc; mn = fmaxf(mn, s[i]); }
.Ls1_done:
	s_lshl_b64 s[0:1], s[6:7], 13
	s_add_u32 s2, s63, s0
	v_readlane_b32 s3, v246, 3
	s_addc_u32 s3, s3, s1
	v_readlane_b32 s6, v246, 9
	s_add_u32 s0, s6, s0
	v_readlane_b32 s6, v246, 7
	s_addc_u32 s1, s6, s1
	v_mov_b32_e32 v163, v2
	v_lshl_add_u64 v[42:43], s[0:1], 0, v[162:163]
	v_readlane_b32 s0, v247, 62
	s_movk_i32 s1, 0x800
	v_lshl_add_u64 v[40:41], s[2:3], 0, v[162:163]
	v_lshl_add_u32 v89, v170, 3, s0
	v_min_i32_e32 v8, 0x803, v89
	v_add_u32_e32 v10, 0xfffff800, v8
	v_ashrrev_i32_e32 v9, 31, v8
	v_cmp_gt_i32_e32 vcc, s1, v89
	s_movk_i32 s2, 0x7f0
	v_min_i32_e32 v76, 0x783, v89
	v_cndmask_b32_e32 v9, 0, v9, vcc
	v_cndmask_b32_e32 v8, v10, v8, vcc
	v_cndmask_b32_e32 v11, v41, v157, vcc
	v_cndmask_b32_e32 v10, v40, v156, vcc
	v_lshlrev_b64 v[8:9], 11, v[8:9]
	v_cndmask_b32_e32 v13, v43, v155, vcc
	v_cndmask_b32_e32 v12, v42, v154, vcc
	v_lshl_add_u64 v[10:11], v[10:11], 0, v[8:9]
	v_lshl_add_u64 v[8:9], v[12:13], 0, v[8:9]
	global_load_dwordx4 v[56:59], v[10:11], off nt
	s_nop 0
	global_load_dwordx4 v[8:11], v[8:9], off nt
	v_min_i32_e32 v12, 0x7f3, v89
	v_add_u32_e32 v14, 16, v12
	v_ashrrev_i32_e32 v13, 31, v14
	v_add_u32_e32 v12, 0xfffff810, v12
	v_cmp_gt_i32_e32 vcc, s2, v89
	v_add_u32_e32 v78, 0x80, v76
	v_readlane_b32 s0, v247, 56
	v_cndmask_b32_e32 v13, 0, v13, vcc
	v_cndmask_b32_e32 v12, v12, v14, vcc
	v_cndmask_b32_e32 v15, v41, v157, vcc
	v_cndmask_b32_e32 v14, v40, v156, vcc
	v_lshlrev_b64 v[12:13], 11, v[12:13]
	v_cndmask_b32_e32 v17, v43, v155, vcc
	v_cndmask_b32_e32 v16, v42, v154, vcc
	v_lshl_add_u64 v[14:15], v[14:15], 0, v[12:13]
	v_lshl_add_u64 v[12:13], v[16:17], 0, v[12:13]
	v_min_i32_e32 v16, 0x7e3, v89
	v_add_u32_e32 v18, 32, v16
	v_ashrrev_i32_e32 v17, 31, v18
	v_add_u32_e32 v16, 0xfffff820, v16
	v_cmp_gt_i32_e32 vcc, s48, v89
	global_load_dwordx4 v[44:47], v[14:15], off nt
	s_nop 0
	global_load_dwordx4 v[12:15], v[12:13], off nt
	v_cndmask_b32_e32 v17, 0, v17, vcc
	v_cndmask_b32_e32 v16, v16, v18, vcc
	v_cndmask_b32_e32 v19, v41, v157, vcc
	v_cndmask_b32_e32 v18, v40, v156, vcc
	v_lshlrev_b64 v[16:17], 11, v[16:17]
	v_cndmask_b32_e32 v21, v43, v155, vcc
	v_cndmask_b32_e32 v20, v42, v154, vcc
	v_lshl_add_u64 v[18:19], v[18:19], 0, v[16:17]
	v_lshl_add_u64 v[16:17], v[20:21], 0, v[16:17]
	v_min_i32_e32 v20, 0x7d3, v89
	v_add_u32_e32 v22, 48, v20
	v_ashrrev_i32_e32 v21, 31, v22
	v_add_u32_e32 v20, 0xfffff830, v20
	v_cmp_gt_i32_e32 vcc, s92, v89
	global_load_dwordx4 v[48:51], v[18:19], off nt
	s_nop 0
	global_load_dwordx4 v[16:19], v[16:17], off nt
	v_cndmask_b32_e32 v21, 0, v21, vcc
	v_cndmask_b32_e32 v20, v20, v22, vcc
	v_cndmask_b32_e32 v23, v41, v157, vcc
	v_cndmask_b32_e32 v22, v40, v156, vcc
	v_lshlrev_b64 v[20:21], 11, v[20:21]
	v_cndmask_b32_e32 v25, v43, v155, vcc
	v_cndmask_b32_e32 v24, v42, v154, vcc
	v_lshl_add_u64 v[22:23], v[22:23], 0, v[20:21]
	v_lshl_add_u64 v[20:21], v[24:25], 0, v[20:21]
	v_min_i32_e32 v24, 0x7c3, v89
	v_add_u32_e32 v26, 64, v24
	v_ashrrev_i32_e32 v25, 31, v26
	v_add_u32_e32 v24, 0xfffff840, v24
	v_cmp_gt_i32_e32 vcc, s93, v89
	global_load_dwordx4 v[52:55], v[22:23], off nt
	s_nop 0
	global_load_dwordx4 v[20:23], v[20:21], off nt
	v_cndmask_b32_e32 v25, 0, v25, vcc
	v_cndmask_b32_e32 v24, v24, v26, vcc
	v_cndmask_b32_e32 v27, v41, v157, vcc
	v_cndmask_b32_e32 v26, v40, v156, vcc
	v_lshlrev_b64 v[24:25], 11, v[24:25]
	v_cndmask_b32_e32 v29, v43, v155, vcc
	v_cndmask_b32_e32 v28, v42, v154, vcc
	v_lshl_add_u64 v[26:27], v[26:27], 0, v[24:25]
	v_lshl_add_u64 v[24:25], v[28:29], 0, v[24:25]
	v_min_i32_e32 v28, 0x7b3, v89
	v_add_u32_e32 v30, 0x50, v28
	v_ashrrev_i32_e32 v29, 31, v30
	v_add_u32_e32 v28, 0xfffff850, v28
	v_cmp_gt_i32_e32 vcc, s42, v89
	global_load_dwordx4 v[60:63], v[26:27], off nt
	s_nop 0
	global_load_dwordx4 v[24:27], v[24:25], off nt
	v_cndmask_b32_e32 v29, 0, v29, vcc
	v_cndmask_b32_e32 v28, v28, v30, vcc
	v_cndmask_b32_e32 v31, v41, v157, vcc
	v_cndmask_b32_e32 v30, v40, v156, vcc
	v_lshlrev_b64 v[28:29], 11, v[28:29]
	v_cndmask_b32_e32 v33, v43, v155, vcc
	v_cndmask_b32_e32 v32, v42, v154, vcc
	v_lshl_add_u64 v[30:31], v[30:31], 0, v[28:29]
	v_lshl_add_u64 v[28:29], v[32:33], 0, v[28:29]
	v_min_i32_e32 v32, 0x7a3, v89
	v_add_u32_e32 v34, 0x60, v32
	v_ashrrev_i32_e32 v33, 31, v34
	v_add_u32_e32 v32, 0xfffff860, v32
	v_cmp_gt_i32_e32 vcc, s43, v89
	global_load_dwordx4 v[68:71], v[30:31], off nt
	s_nop 0
	global_load_dwordx4 v[28:31], v[28:29], off nt
	v_cndmask_b32_e32 v33, 0, v33, vcc
	v_cndmask_b32_e32 v32, v32, v34, vcc
	v_cndmask_b32_e32 v35, v41, v157, vcc
	v_cndmask_b32_e32 v34, v40, v156, vcc
	v_lshlrev_b64 v[32:33], 11, v[32:33]
	v_cndmask_b32_e32 v37, v43, v155, vcc
	v_cndmask_b32_e32 v36, v42, v154, vcc
	v_lshl_add_u64 v[34:35], v[34:35], 0, v[32:33]
	v_lshl_add_u64 v[32:33], v[36:37], 0, v[32:33]
	global_load_dwordx4 v[64:67], v[34:35], off nt
	s_nop 0
	global_load_dwordx4 v[32:35], v[32:33], off nt
	s_waitcnt vmcnt(13)
	v_mov_b32_e32 v82, v57
	v_mov_b32_e32 v57, v59
	v_mov_b32_e32 v83, v58
	v_pk_mul_f32 v[58:59], v[56:57], v[152:153]
	v_min_i32_e32 v36, 0x793, v89
	v_pk_fma_f32 v[58:59], v[82:83], v[150:151], v[58:59]
	v_add_u32_e32 v38, 0x70, v36
	v_add_f32_e32 v58, v58, v59
	v_ashrrev_i32_e32 v37, 31, v38
	v_add_u32_e32 v36, 0xfffff870, v36
	v_cmp_gt_i32_e32 vcc, s95, v89
	v_ashrrev_i32_e32 v77, 31, v78
	s_waitcnt lgkmcnt(0)
	v_add_f32_dpp v58, v58, v58 quad_perm:[1,0,3,2] row_mask:0xf bank_mask:0xf
	v_cndmask_b32_e32 v37, 0, v37, vcc
	v_cndmask_b32_e32 v36, v36, v38, vcc
	v_cndmask_b32_e32 v39, v41, v157, vcc
	v_cndmask_b32_e32 v38, v40, v156, vcc
	s_waitcnt lgkmcnt(0)
; DI float dot16(f32x4 a, f32x4 b) { float d = (a[0] * b[0] + a[1] * b[1]) + (a[2] * b[2] + a[3] * b[3]); d += __shfl_xor(d, 1); d += __shfl_xor(d, 2); d += __shfl_xor(d, 4); d += __shfl_xor(d, 8); return d; }
; DI void unit_sample_attn2(int u, const bf16* __restrict__ Q, const float* __restrict__ ckw, const float* __restrict__ cvw, const float* __restrict__ nkw, const float* __restrict__ nvw, const bf16* __restrict__ G, bf16* __restrict__ MIX, ...
;     ...
;         for (int jj = 0; jj < 4; ++jj) { float s[9]; float mn = NEG;
; #pragma unroll
;             for (int i = 0; i < 9; ++i) { const int dlt = 2048 + jj - idxs[i];
;                 const int cnt = (dlt <= 128 ? 1 : 0) + ((dlt & 3) == 0 ? 1 : 0) + ((dlt & 15) == 0 ? 1 : 0);
;                 const float lc = (cnt == 3) ? 1.5849625f : (cnt == 2) ? 1.f : 0.f;
;                 const float d = dot16(q[jj], kv[i]);
;                 s[i] = (idxs[i] > 2051 || dlt < 0 || cnt == 0) ? NEG : d - slope2 * (float)dlt + lc; mn = fmaxf(mn, s[i]); }
	v_add_f32_dpp v58, v58, v58 quad_perm:[2,3,0,1] row_mask:0xf bank_mask:0xf
	v_cndmask_b32_e32 v73, v43, v155, vcc
	v_cndmask_b32_e32 v72, v42, v154, vcc
	v_add_u32_e32 v76, 0xfffff880, v76
	v_cmp_gt_i32_e32 vcc, s30, v89
	v_add_u32_e32 v91, s0, v170
	v_sub_u32_e32 v80, 0x800, v89
	s_movk_i32 s0, 0x77f
	s_waitcnt lgkmcnt(0)
	v_add_f32_dpp v58, v58, v58 row_half_mirror row_mask:0xf bank_mask:0xf
	v_cndmask_b32_e32 v77, 0, v77, vcc
	v_cndmask_b32_e32 v76, v76, v78, vcc
	v_cndmask_b32_e32 v41, v41, v157, vcc
	v_cndmask_b32_e32 v40, v40, v156, vcc
	v_cndmask_b32_e32 v43, v43, v155, vcc
	v_cndmask_b32_e32 v42, v42, v154, vcc
	v_cmp_lt_i32_e32 vcc, s0, v89
	v_and_b32_e32 v86, 3, v80
	v_cndmask_b32_e64 v81, 0, 1, vcc
	v_cmp_eq_u32_e32 vcc, 0, v86
	v_and_b32_e32 v88, 15, v80
	v_cvt_f32_u32_e32 v80, v80
	v_cndmask_b32_e64 v86, 0, 1, vcc
	v_cmp_eq_u32_e32 vcc, 0, v88
	s_waitcnt lgkmcnt(0)
	v_add_f32_dpp v58, v58, v58 row_mirror row_mask:0xf bank_mask:0xf
	v_fma_f32 v58, -v136, v80, v58
	v_addc_co_u32_e32 v81, vcc, v86, v81, vcc
	v_cmp_eq_u32_e32 vcc, 2, v81
	v_cmp_eq_u32_e64 s[6:7], 0, v81
	s_waitcnt vmcnt(11)
	v_mov_b32_e32 v59, v46
	v_cndmask_b32_e64 v86, 0, 1.0, vcc
	v_cmp_ne_u32_e32 vcc, 3, v81
	s_waitcnt vmcnt(9)
	v_mov_b32_e32 v80, v49
	v_mov_b32_e32 v49, v51
	v_cndmask_b32_e32 v86, v183, v86, vcc
	v_cmp_lt_i32_e32 vcc, s1, v89
	v_add_f32_e32 v58, v86, v58
	s_or_b64 vcc, vcc, s[6:7]
	v_cndmask_b32_e32 v86, v58, v226, vcc
	v_mov_b32_e32 v58, v45
	v_mov_b32_e32 v45, v47
	v_pk_mul_f32 v[46:47], v[44:45], v[152:153]
	v_mov_b32_e32 v81, v50
	v_pk_fma_f32 v[94:95], v[58:59], v[150:151], v[46:47]
	v_pk_mul_f32 v[46:47], v[48:49], v[152:153]
	s_waitcnt vmcnt(7)
	v_mov_b32_e32 v50, v53
	v_mov_b32_e32 v53, v55
	v_pk_fma_f32 v[96:97], v[80:81], v[150:151], v[46:47]
	v_mov_b32_e32 v51, v54
	v_pk_mul_f32 v[46:47], v[52:53], v[152:153]
	s_waitcnt vmcnt(5)
	v_mov_b32_e32 v54, v61
	v_mov_b32_e32 v61, v63
	v_pk_fma_f32 v[98:99], v[50:51], v[150:151], v[46:47]
	v_mov_b32_e32 v55, v62
	v_pk_mul_f32 v[46:47], v[60:61], v[152:153]
	s_waitcnt vmcnt(3)
	v_mov_b32_e32 v62, v69
	v_mov_b32_e32 v69, v71
	v_pk_fma_f32 v[100:101], v[54:55], v[150:151], v[46:47]
	v_mov_b32_e32 v63, v70
	v_pk_mul_f32 v[46:47], v[68:69], v[152:153]
	v_lshlrev_b64 v[36:37], 11, v[36:37]
	v_pk_fma_f32 v[102:103], v[62:63], v[150:151], v[46:47]
	s_waitcnt vmcnt(1)
	v_mov_b32_e32 v46, v65
	v_mov_b32_e32 v47, v66
	v_mov_b32_e32 v65, v67
	v_mov_b32_e32 v66, v96
	v_mov_b32_e32 v67, v94
	v_mov_b32_e32 v94, v97
	v_pk_add_f32 v[66:67], v[66:67], v[94:95]
	v_lshl_add_u64 v[38:39], v[38:39], 0, v[36:37]
	v_lshl_add_u64 v[36:37], v[72:73], 0, v[36:37]
	global_load_dwordx4 v[72:75], v[38:39], off nt
	s_nop 0
	global_load_dwordx4 v[36:39], v[36:37], off nt
	v_lshlrev_b64 v[76:77], 11, v[76:77]
	v_lshl_add_u64 v[40:41], v[40:41], 0, v[76:77]
	v_lshl_add_u64 v[42:43], v[42:43], 0, v[76:77]
	s_waitcnt lgkmcnt(0)
	v_add_f32_dpp v94, v66, v66 quad_perm:[1,0,3,2] row_mask:0xf bank_mask:0xf
	v_add_f32_dpp v95, v67, v67 quad_perm:[1,0,3,2] row_mask:0xf bank_mask:0xf
	global_load_dwordx4 v[76:79], v[40:41], off nt
	s_nop 0
	global_load_dwordx4 v[40:43], v[42:43], off nt
	s_movk_i32 s0, 0x76f
	v_sub_u32_e32 v90, 0x7f0, v89
	v_cmp_lt_i32_e32 vcc, s0, v89
	s_movk_i32 s0, 0x75f
	s_waitcnt lgkmcnt(0)
	v_add_f32_dpp v94, v94, v94 quad_perm:[2,3,0,1] row_mask:0xf bank_mask:0xf
	v_add_f32_dpp v95, v95, v95 quad_perm:[2,3,0,1] row_mask:0xf bank_mask:0xf
	v_sub_u32_e32 v92, 0x7e0, v89
	v_and_b32_e32 v107, 3, v90
	v_and_b32_e32 v108, 3, v92
	v_and_b32_e32 v110, 15, v92
	s_waitcnt lgkmcnt(0)
	v_add_f32_dpp v94, v94, v94 row_half_mirror row_mask:0xf bank_mask:0xf
	v_add_f32_dpp v95, v95, v95 row_half_mirror row_mask:0xf bank_mask:0xf
	v_cndmask_b32_e64 v104, 0, 1, vcc
	v_cmp_lt_i32_e32 vcc, s0, v89
	v_and_b32_e32 v109, 15, v90
	v_cndmask_b32_e64 v106, 0, 1, vcc
	v_cmp_eq_u32_e32 vcc, 0, v107
	v_cmp_lt_i32_e64 s[6:7], s2, v89
	s_movk_i32 s0, 0x74f
	v_cndmask_b32_e64 v107, 0, 1, vcc
	v_cmp_eq_u32_e32 vcc, 0, v108
	v_pk_mul_f32 v[70:71], v[64:65], v[152:153]
	v_max_f32_e32 v88, 0xf149f2ca, v86
	v_cndmask_b32_e64 v108, 0, 1, vcc
	v_cmp_eq_u32_e32 vcc, 0, v110
	v_pk_fma_f32 v[96:97], v[46:47], v[150:151], v[70:71]
	v_and_b32_e32 v84, 15, v169
	v_addc_co_u32_e32 v108, vcc, v108, v106, vcc
	v_cmp_eq_u32_e32 vcc, 0, v109
	v_cmp_eq_u32_e64 s[8:9], 0, v108
	v_lshl_add_u32 v93, v164, 2, 0
	v_addc_co_u32_e32 v109, vcc, v107, v104, vcc
	v_cmp_eq_u32_e32 vcc, 2, v108
	v_cmp_eq_u32_e64 s[10:11], 0, v109
	s_waitcnt lgkmcnt(0)
	v_add_f32_dpp v94, v94, v94 row_mirror row_mask:0xf bank_mask:0xf
	v_add_f32_dpp v95, v95, v95 row_mirror row_mask:0xf bank_mask:0xf
	v_mov_b32_e32 v104, v100
	v_mov_b32_e32 v105, v98
	v_mov_b32_e32 v98, v101
	v_pk_add_f32 v[98:99], v[104:105], v[98:99]
	v_cvt_f32_u32_e32 v105, v90
	v_cvt_f32_u32_e32 v104, v92
	v_cndmask_b32_e64 v106, 0, 1.0, vcc
	v_cmp_eq_u32_e32 vcc, 2, v109
	s_waitcnt lgkmcnt(0)
	v_add_f32_dpp v98, v98, v98 quad_perm:[1,0,3,2] row_mask:0xf bank_mask:0xf
	v_add_f32_dpp v99, v99, v99 quad_perm:[1,0,3,2] row_mask:0xf bank_mask:0xf
	v_cndmask_b32_e64 v107, 0, 1.0, vcc
	v_cmp_ne_u32_e32 vcc, 3, v109
	v_pk_fma_f32 v[94:95], v[136:137], v[104:105], v[94:95] op_sel_hi:[0,1,1] neg_lo:[1,0,0] neg_hi:[1,0,0]
	v_sub_u32_e32 v104, 0x7d0, v89
	s_waitcnt lgkmcnt(0)
	v_add_f32_dpp v98, v98, v98 quad_perm:[2,3,0,1] row_mask:0xf bank_mask:0xf
	v_add_f32_dpp v99, v99, v99 quad_perm:[2,3,0,1] row_mask:0xf bank_mask:0xf
	v_cndmask_b32_e32 v107, v183, v107, vcc
	v_cmp_ne_u32_e32 vcc, 3, v108
	v_cndmask_b32_e32 v106, v183, v106, vcc
	v_cmp_lt_i32_e32 vcc, s48, v89
	v_pk_add_f32 v[94:95], v[106:107], v[94:95]
	s_or_b64 vcc, vcc, s[8:9]
	v_cndmask_b32_e32 v90, v94, v226, vcc
	s_or_b64 vcc, s[6:7], s[10:11]
	v_cndmask_b32_e32 v92, v95, v226, vcc
	v_cmp_lt_i32_e32 vcc, s0, v89
	s_movk_i32 s0, 0x73f
	s_waitcnt lgkmcnt(0)
; DI float dot16(f32x4 a, f32x4 b) { float d = (a[0] * b[0] + a[1] * b[1]) + (a[2] * b[2] + a[3] * b[3]); d += __shfl_xor(d, 1); d += __shfl_xor(d, 2); d += __shfl_xor(d, 4); d += __shfl_xor(d, 8); return d; }
; DI void unit_sample_attn2(int u, const bf16* __restrict__ Q, const float* __restrict__ ckw, const float* __restrict__ cvw, const float* __restrict__ nkw, const float* __restrict__ nvw, const bf16* __restrict__ G, bf16* __restrict__ MIX, ...
;     ...
;             for (int i = 0; i < 9; ++i) { const int dlt = 2048 + jj - idxs[i];
;                 const int cnt = (dlt <= 128 ? 1 : 0) + ((dlt & 3) == 0 ? 1 : 0) + ((dlt & 15) == 0 ? 1 : 0);
;                 const float lc = (cnt == 3) ? 1.5849625f : (cnt == 2) ? 1.f : 0.f;
;                 const float d = dot16(q[jj], kv[i]);
;                 s[i] = (idxs[i] > 2051 || dlt < 0 || cnt == 0) ? NEG : d - slope2 * (float)dlt + lc; mn = fmaxf(mn, s[i]); }
	v_add_f32_dpp v94, v98, v98 row_half_mirror row_mask:0xf bank_mask:0xf
	v_add_f32_dpp v95, v99, v99 row_half_mirror row_mask:0xf bank_mask:0xf
	v_sub_u32_e32 v105, 0x7c0, v89
	v_cndmask_b32_e64 v98, 0, 1, vcc
	v_cmp_lt_i32_e32 vcc, s0, v89
	v_and_b32_e32 v101, 3, v104
	v_and_b32_e32 v106, 3, v105
	v_cndmask_b32_e64 v100, 0, 1, vcc
	v_cmp_eq_u32_e32 vcc, 0, v101
	v_and_b32_e32 v108, 15, v105
	v_and_b32_e32 v107, 15, v104
	v_cndmask_b32_e64 v101, 0, 1, vcc
	v_cmp_eq_u32_e32 vcc, 0, v106
	v_cmp_lt_i32_e64 s[6:7], s92, v89
	v_cndmask_b32_e64 v106, 0, 1, vcc
	v_cmp_eq_u32_e32 vcc, 0, v108
	s_movk_i32 s0, 0x72f
	s_waitcnt vmcnt(3)
	v_mov_b32_e32 v70, v73
	v_addc_co_u32_e32 v106, vcc, v106, v100, vcc
	v_cmp_eq_u32_e32 vcc, 0, v107
	v_cmp_eq_u32_e64 s[8:9], 0, v106
	v_mov_b32_e32 v73, v75
	v_addc_co_u32_e32 v107, vcc, v101, v98, vcc
	v_cmp_eq_u32_e32 vcc, 2, v106
	v_cmp_eq_u32_e64 s[10:11], 0, v107
	v_mov_b32_e32 v71, v74
	v_cndmask_b32_e64 v100, 0, 1.0, vcc
	s_waitcnt lgkmcnt(0)
	v_add_f32_dpp v94, v94, v94 row_mirror row_mask:0xf bank_mask:0xf
	v_add_f32_dpp v95, v95, v95 row_mirror row_mask:0xf bank_mask:0xf
	v_mov_b32_e32 v98, v96
	v_mov_b32_e32 v99, v102
	v_mov_b32_e32 v102, v97
	v_pk_add_f32 v[96:97], v[98:99], v[102:103]
	v_cvt_f32_u32_e32 v103, v104
	v_cvt_f32_u32_e32 v102, v105
	v_cmp_eq_u32_e32 vcc, 2, v107
	v_pk_mul_f32 v[66:67], v[72:73], v[152:153]
	s_waitcnt lgkmcnt(0)
	v_add_f32_dpp v96, v96, v96 quad_perm:[1,0,3,2] row_mask:0xf bank_mask:0xf
	v_add_f32_dpp v97, v97, v97 quad_perm:[1,0,3,2] row_mask:0xf bank_mask:0xf
	v_cndmask_b32_e64 v101, 0, 1.0, vcc
	v_cmp_ne_u32_e32 vcc, 3, v107
	v_pk_fma_f32 v[94:95], v[136:137], v[102:103], v[94:95] op_sel_hi:[0,1,1] neg_lo:[1,0,0] neg_hi:[1,0,0]
	v_sub_u32_e32 v102, 0x7b0, v89
	s_waitcnt lgkmcnt(0)
	v_add_f32_dpp v96, v96, v96 quad_perm:[2,3,0,1] row_mask:0xf bank_mask:0xf
	v_add_f32_dpp v97, v97, v97 quad_perm:[2,3,0,1] row_mask:0xf bank_mask:0xf
	v_cndmask_b32_e32 v101, v183, v101, vcc
	v_cmp_ne_u32_e32 vcc, 3, v106
	v_cndmask_b32_e32 v100, v183, v100, vcc
	v_cmp_lt_i32_e32 vcc, s93, v89
	v_pk_add_f32 v[94:95], v[100:101], v[94:95]
	s_or_b64 vcc, vcc, s[8:9]
	v_cndmask_b32_e32 v100, v94, v226, vcc
	s_or_b64 vcc, s[6:7], s[10:11]
	v_cndmask_b32_e32 v101, v95, v226, vcc
	v_cmp_lt_i32_e32 vcc, s0, v89
	s_movk_i32 s0, 0x71f
	s_waitcnt lgkmcnt(0)
	v_add_f32_dpp v94, v96, v96 row_half_mirror row_mask:0xf bank_mask:0xf
	v_add_f32_dpp v95, v97, v97 row_half_mirror row_mask:0xf bank_mask:0xf
	v_sub_u32_e32 v103, 0x7a0, v89
	v_cndmask_b32_e64 v96, 0, 1, vcc
	v_cmp_lt_i32_e32 vcc, s0, v89
	v_and_b32_e32 v99, 3, v102
	v_and_b32_e32 v104, 3, v103
	v_cndmask_b32_e64 v98, 0, 1, vcc
	v_cmp_eq_u32_e32 vcc, 0, v99
	v_and_b32_e32 v106, 15, v103
	v_and_b32_e32 v105, 15, v102
	v_cndmask_b32_e64 v99, 0, 1, vcc
	v_cmp_eq_u32_e32 vcc, 0, v104
	v_pk_fma_f32 v[74:75], v[70:71], v[150:151], v[66:67]
	v_cndmask_b32_e64 v104, 0, 1, vcc
	v_cmp_eq_u32_e32 vcc, 0, v106
	s_waitcnt vmcnt(1)
	v_mov_b32_e32 v66, v77
	v_mov_b32_e32 v77, v79
	v_addc_co_u32_e32 v104, vcc, v104, v98, vcc
	v_cmp_eq_u32_e32 vcc, 0, v105
	v_mov_b32_e32 v67, v78
	v_pk_mul_f32 v[78:79], v[76:77], v[152:153]
	v_addc_co_u32_e32 v105, vcc, v99, v96, vcc
	v_pk_fma_f32 v[78:79], v[66:67], v[150:151], v[78:79]
	v_cmp_eq_u32_e32 vcc, 2, v104
	v_cmp_eq_u32_e64 s[8:9], 0, v104
	v_cmp_lt_i32_e64 s[6:7], s42, v89
	s_waitcnt lgkmcnt(0)
	v_add_f32_dpp v94, v94, v94 row_mirror row_mask:0xf bank_mask:0xf
	v_add_f32_dpp v95, v95, v95 row_mirror row_mask:0xf bank_mask:0xf
	v_mov_b32_e32 v96, v78
	v_mov_b32_e32 v97, v74
	v_mov_b32_e32 v74, v79
	v_pk_add_f32 v[74:75], v[96:97], v[74:75]
	v_cvt_f32_u32_e32 v97, v102
	v_cvt_f32_u32_e32 v96, v103
	v_cndmask_b32_e64 v98, 0, 1.0, vcc
	v_cmp_eq_u32_e32 vcc, 2, v105
	s_waitcnt lgkmcnt(0)
	v_add_f32_dpp v74, v74, v74 quad_perm:[1,0,3,2] row_mask:0xf bank_mask:0xf
	v_add_f32_dpp v75, v75, v75 quad_perm:[1,0,3,2] row_mask:0xf bank_mask:0xf
	v_cndmask_b32_e64 v99, 0, 1.0, vcc
	v_cmp_ne_u32_e32 vcc, 3, v105
	v_pk_fma_f32 v[94:95], v[136:137], v[96:97], v[94:95] op_sel_hi:[0,1,1] neg_lo:[1,0,0] neg_hi:[1,0,0]
	v_cmp_eq_u32_e64 s[10:11], 0, v105
	s_waitcnt lgkmcnt(0)
	v_add_f32_dpp v74, v74, v74 quad_perm:[2,3,0,1] row_mask:0xf bank_mask:0xf
	v_add_f32_dpp v75, v75, v75 quad_perm:[2,3,0,1] row_mask:0xf bank_mask:0xf
	v_cndmask_b32_e32 v99, v183, v99, vcc
	v_cmp_ne_u32_e32 vcc, 3, v104
	v_cndmask_b32_e32 v98, v183, v98, vcc
	v_cmp_lt_i32_e32 vcc, s43, v89
	v_pk_add_f32 v[94:95], v[98:99], v[94:95]
	s_or_b64 vcc, vcc, s[8:9]
	v_cndmask_b32_e32 v98, v94, v226, vcc
	s_or_b64 vcc, s[6:7], s[10:11]
	s_movk_i32 s0, 0x70f
	v_cndmask_b32_e32 v99, v95, v226, vcc
	v_sub_u32_e32 v96, 0x790, v89
	v_cmp_lt_i32_e32 vcc, s0, v89
	s_movk_i32 s0, 0x6ff
	s_waitcnt lgkmcnt(0)
; #define LAS __attribute__((address_space(3)))
; DI float fexp2(float x) { return __builtin_amdgcn_exp2f(x); }
; DI float dot16(f32x4 a, f32x4 b) { float d = (a[0] * b[0] + a[1] * b[1]) + (a[2] * b[2] + a[3] * b[3]); d += __shfl_xor(d, 1); d += __shfl_xor(d, 2); d += __shfl_xor(d, 4); d += __shfl_xor(d, 8); return d; }
; DI void unit_sample_attn2(int u, const bf16* __restrict__ Q, const float* __restrict__ ckw, const float* __restrict__ cvw, const float* __restrict__ nkw, const float* __restrict__ nvw, const bf16* __restrict__ G, bf16* __restrict__ MIX, ...
;     ...
;                 const float d = dot16(q[jj], kv[i]);
;                 s[i] = (idxs[i] > 2051 || dlt < 0 || cnt == 0) ? NEG : d - slope2 * (float)dlt + lc; mn = fmaxf(mn, s[i]); }
;             float ps = 0.f; f32x4 acc = (f32x4){0.f, 0.f, 0.f, 0.f};
; #pragma unroll
;             for (int i = 0; i < 9; ++i) { const float p = (s[i] <= NEG) ? 0.f : fexp2(s[i] - mn); ps += p; acc += vv[i] * p; }
;             *(LAS f32x4*)(pA + (pst * 4 + jj) * 128 + (lane & 31) * 4) = acc;
;             if ((lane & 15) == 0) { sA[(pst * 4 + jj) * 2 + hl] = mn; sA[128 + (pst * 4 + jj) * 2 + hl] = ps; } }
	v_add_f32_dpp v74, v74, v74 row_half_mirror row_mask:0xf bank_mask:0xf
	v_add_f32_dpp v75, v75, v75 row_half_mirror row_mask:0xf bank_mask:0xf
	v_sub_u32_e32 v97, 0x780, v89
	v_cndmask_b32_e64 v78, 0, 1, vcc
	v_cmp_lt_i32_e32 vcc, s0, v89
	v_and_b32_e32 v95, 3, v96
	v_and_b32_e32 v102, 3, v97
	v_cndmask_b32_e64 v94, 0, 1, vcc
	v_cmp_eq_u32_e32 vcc, 0, v95
	v_and_b32_e32 v104, 15, v97
	v_and_b32_e32 v103, 15, v96
	v_cndmask_b32_e64 v95, 0, 1, vcc
	v_cmp_eq_u32_e32 vcc, 0, v102
	v_max3_f32 v88, v88, v92, v90
	v_cndmask_b32_e64 v102, 0, 1, vcc
	v_cmp_eq_u32_e32 vcc, 0, v104
	v_cmp_lt_i32_e64 s[10:11], s95, v89
	v_max3_f32 v88, v88, v101, v100
	v_addc_co_u32_e32 v102, vcc, v102, v94, vcc
	v_cmp_eq_u32_e32 vcc, 0, v103
	v_cmp_eq_u32_e64 s[8:9], 0, v102
	v_max3_f32 v88, v88, v99, v98
	v_addc_co_u32_e32 v103, vcc, v95, v78, vcc
	v_cmp_eq_u32_e32 vcc, 2, v102
	v_cmp_eq_u32_e64 s[6:7], 0, v103
	s_waitcnt lgkmcnt(0)
	v_add_f32_dpp v74, v74, v74 row_mirror row_mask:0xf bank_mask:0xf
	v_add_f32_dpp v75, v75, v75 row_mirror row_mask:0xf bank_mask:0xf
	v_cvt_f32_u32_e32 v79, v96
	v_cvt_f32_u32_e32 v78, v97
	v_cndmask_b32_e64 v94, 0, 1.0, vcc
	v_cmp_eq_u32_e32 vcc, 2, v103
	v_pk_fma_f32 v[74:75], v[136:137], v[78:79], v[74:75] op_sel_hi:[0,1,1] neg_lo:[1,0,0] neg_hi:[1,0,0]
	s_nop 0
	v_cndmask_b32_e64 v95, 0, 1.0, vcc
	v_cmp_ne_u32_e32 vcc, 3, v103
	s_nop 1
	v_cndmask_b32_e32 v95, v183, v95, vcc
	v_cmp_ne_u32_e32 vcc, 3, v102
	s_nop 1
	v_cndmask_b32_e32 v94, v183, v94, vcc
	v_cmp_lt_i32_e32 vcc, s30, v89
	v_pk_add_f32 v[74:75], v[94:95], v[74:75]
	s_or_b64 vcc, s[8:9], vcc
	v_cndmask_b32_e32 v104, v74, v226, vcc
	s_or_b64 vcc, s[10:11], s[6:7]
	v_cndmask_b32_e32 v75, v75, v226, vcc
	v_max3_f32 v79, v88, v75, v104
	v_sub_f32_e32 v74, v86, v79
	v_exp_f32_e32 v74, v74
	v_sub_f32_e32 v78, v92, v79
	v_exp_f32_e32 v78, v78
	v_cmp_ne_u32_e32 vcc, 0, v84
	v_cmp_eq_u32_e64 s[6:7], 0, v84
	v_sub_f32_e32 v84, v90, v79
	v_cmp_nge_f32_e64 s[8:9], s45, v86
	v_exp_f32_e32 v84, v84
	v_sub_f32_e32 v86, v101, v79
	v_cndmask_b32_e64 v74, 0, v74, s[8:9]
	v_cmp_nge_f32_e64 s[8:9], s45, v92
	v_exp_f32_e32 v86, v86
	v_sub_f32_e32 v88, v100, v79
	v_cndmask_b32_e64 v78, 0, v78, s[8:9]
	v_cmp_nge_f32_e64 s[8:9], s45, v90
	v_exp_f32_e32 v88, v88
	v_sub_f32_e32 v90, v99, v79
	v_exp_f32_e32 v90, v90
	v_sub_f32_e32 v92, v98, v79
	v_cndmask_b32_e64 v84, 0, v84, s[8:9]
	v_cmp_nge_f32_e64 s[8:9], s45, v101
	v_exp_f32_e32 v92, v92
	v_pk_fma_f32 v[94:95], v[10:11], v[74:75], 0 op_sel_hi:[1,0,0]
	v_cndmask_b32_e64 v86, 0, v86, s[8:9]
	v_cmp_nge_f32_e64 s[8:9], s45, v100
	v_pk_fma_f32 v[96:97], v[8:9], v[74:75], 0 op_sel_hi:[1,0,0]
	v_pk_fma_f32 v[94:95], v[14:15], v[78:79], v[94:95] op_sel_hi:[1,0,1]
	v_cndmask_b32_e64 v88, 0, v88, s[8:9]
	v_cmp_nge_f32_e64 s[8:9], s45, v99
	v_pk_fma_f32 v[96:97], v[12:13], v[78:79], v[96:97] op_sel_hi:[1,0,1]
	v_pk_fma_f32 v[94:95], v[18:19], v[84:85], v[94:95] op_sel_hi:[1,0,1]
	v_cndmask_b32_e64 v90, 0, v90, s[8:9]
	v_cmp_nge_f32_e64 s[8:9], s45, v98
	v_sub_f32_e32 v98, v75, v79
	v_pk_fma_f32 v[96:97], v[16:17], v[84:85], v[96:97] op_sel_hi:[1,0,1]
	v_cndmask_b32_e64 v92, 0, v92, s[8:9]
	v_exp_f32_e32 v100, v98
	v_cmp_nge_f32_e64 s[8:9], s45, v75
	v_sub_f32_e32 v75, v104, v79
	v_pk_fma_f32 v[96:97], v[20:21], v[86:87], v[96:97] op_sel_hi:[1,0,1]
	v_pk_fma_f32 v[94:95], v[22:23], v[86:87], v[94:95] op_sel_hi:[1,0,1]
	v_exp_f32_e32 v75, v75
	v_pk_fma_f32 v[94:95], v[26:27], v[88:89], v[94:95] op_sel_hi:[1,0,1]
	v_pk_fma_f32 v[96:97], v[24:25], v[88:89], v[96:97] op_sel_hi:[1,0,1]
	v_pk_fma_f32 v[94:95], v[30:31], v[90:91], v[94:95] op_sel_hi:[1,0,1]
	v_pk_fma_f32 v[96:97], v[28:29], v[90:91], v[96:97] op_sel_hi:[1,0,1]
	v_pk_fma_f32 v[98:99], v[34:35], v[92:93], v[94:95] op_sel_hi:[1,0,1]
	v_pk_fma_f32 v[96:97], v[32:33], v[92:93], v[96:97] op_sel_hi:[1,0,1]
	v_cndmask_b32_e64 v94, 0, v100, s[8:9]
	v_cmp_nge_f32_e64 s[8:9], s45, v104
	v_pk_fma_f32 v[102:103], v[36:37], v[94:95], v[96:97] op_sel_hi:[1,0,1]
	v_pk_fma_f32 v[98:99], v[38:39], v[94:95], v[98:99] op_sel_hi:[1,0,1]
	v_cndmask_b32_e64 v96, 0, v75, s[8:9]
	s_waitcnt vmcnt(0)
	v_pk_fma_f32 v[100:101], v[42:43], v[96:97], v[98:99] op_sel_hi:[1,0,1]
	v_pk_fma_f32 v[98:99], v[40:41], v[96:97], v[102:103] op_sel_hi:[1,0,1]
	v_lshl_add_u32 v75, v91, 11, v93
	ds_write_b128 v75, v[98:101]
	v_lshlrev_b32_e32 v75, 2, v137
	s_and_saveexec_b64 s[2:3], s[6:7]
	s_cbranch_execz .LBB0_736
	v_add_f32_e32 v74, 0, v74
	v_add_f32_e32 v74, v78, v74
	v_add_f32_e32 v74, v84, v74
	v_add_f32_e32 v74, v86, v74
	v_add_f32_e32 v74, v88, v74
	v_add_f32_e32 v74, v90, v74
	v_add_f32_e32 v74, v92, v74
	v_add_f32_e32 v74, v94, v74
	v_lshlrev_b32_e32 v78, 5, v91
	v_add_f32_e32 v74, v96, v74
	v_add3_u32 v78, 0, v78, v75
	ds_write2st64_b32 v78, v79, v74 offset0:160 offset1:162
